# peeled first K-iteration with srcC=0 at 11 GEMM sites, accumulator zeroing removed
# speedup vs baseline: 1.0005x; 1.0005x over previous
; #define PG8_STAGE(bufoff, gbase, voff) do { _Pragma("unroll") for (int _i = 0; _i < 2; ++_i) \
;         __builtin_amdgcn_global_load_lds((const unsigned*)((const char*)(gbase) + (voff)[_i]), (LAS unsigned*)(lds + (bufoff) + ldsw + _i * 8192), 16, 0, 0); } while (0)
; #define PG8_LDA(dst, b, h) do { _Pragma("unroll") for (int m = 0; m < 4; ++m) _Pragma("unroll") for (int k = 0; k < 2; ++k) dst[m][k] = *(const LAS bf16x8*)(lds + PG8_SA(b, h) + aoff + m * 2048 + k * 1024); } while (0)
; #define PG8_LDB(dst, b, h) do { _Pragma("unroll") for (int n = 0; n < 2; ++n) _Pragma("unroll") for (int k = 0; k < 2; ++k) dst[n][k] = *(const LAS bf16x8*)(lds + PG8_SB(b, h) + boff + n * 2048 + k * 1024); } while (0)
; #define PG8_WAIT_V(n) asm volatile("s_waitcnt vmcnt(" #n ")" ::: "memory")
; #define PG8_WAIT_L(n) asm volatile("s_waitcnt lgkmcnt(" #n ")" ::: "memory")
; #define PG8_BAR __builtin_amdgcn_s_barrier()
; #define PG8_SCHED __builtin_amdgcn_sched_barrier(0)
; template <class Epi, bool ALIGN_EPI = true>
; DI void gemm_phase(int tb_, LAS unsigned char* lds, const Gemm g, const Sched& S, const Epi& E) {
;     ...
;         const bool has_next = S.next(ui + 1, nxt);
;         const char* nA = has_next ? PG8_APTR(nxt) : cA; const char* nB = has_next ? PG8_BPTR(nxt) : cB;
;         const int nt = cur.nt;
;         for (int t = 0; t < nt; t += 2) {
;             const bool last = (t == nt - 2);
;             const char* a1 = cA + (size_t)(t + 1) * kstep;
;             const char* a2 = last ? nA : cA + (size_t)(t + 2) * kstep; const char* b2 = last ? nB : cB + (size_t)(t + 2) * kstep;
;             const char* a3 = a2 + kstep; const char* b3 = b2 + kstep;
;             PG8_LDB(B0, 0, 0); PG8_LDB(B1, 0, 1); PG8_SCHED; PG8_LDA(At, 0, 0); PG8_STAGE(PG8_SA(1, 1), a1 + hstep, voffA);
;             PG8_WAIT_V(8); PG8_WAIT_L(0); PG8_BAR; PG8_MMA(0, 0, At, B0); PG8_MMA(0, 1, At, B1); PG8_BAR; PG8_SCHED;
;             PG8_LDA(At, 0, 1); PG8_STAGE(PG8_SB(0, 0), b2, voffB); PG8_STAGE(PG8_SB(0, 1), b2 + hstep, voffB); PG8_STAGE(PG8_SA(0, 0), a2, voffA);
;     ...
;         for (int a = 0; a < 2; ++a)
; #pragma unroll
;             for (int b = 0; b < 2; ++b)
; #pragma unroll
;                 for (int m = 0; m < 4; ++m)
; #pragma unroll
;                     for (int n = 0; n < 2; ++n) acc[a][b][m][n] = (f32x4){0.f, 0.f, 0.f, 0.f};
.LBB0_294:
	s_ashr_i32 s17, s16, 31
	s_lshl_b64 s[18:19], s[16:17], 19
	s_add_u32 s18, s27, s18
	s_addc_u32 s19, s34, s19
	s_and_b64 s[20:21], s[6:7], exec
	s_cselect_b32 s17, s19, s25
	s_cselect_b32 s23, s18, s24
	s_ashr_i32 s15, s14, 31
	s_lshl_b64 s[20:21], s[14:15], 19
	s_add_u32 s20, s35, s20
	s_addc_u32 s21, s36, s21
	s_and_b64 s[30:31], s[6:7], exec
	s_cselect_b32 s15, s21, s29
	s_cselect_b32 s33, s20, s28
	s_add_u32 s24, s24, 0x40080
	s_addc_u32 s25, s25, 0
	s_add_u32 s47, s28, 0x100
	s_addc_u32 s48, s29, 0
	s_mov_b32 s49, -2
	s_add_u32 s28, s24, 0xfffc0080
	s_addc_u32 s29, s25, -1
	s_add_i32 s50, 0, 0x10000
	s_cmp_eq_u32 s49, 12
	s_cselect_b32 s31, s17, s29
	s_cselect_b32 s30, s23, s28
	v_add_u32_e32 v138, s50, v141
	s_cselect_b32 s29, s15, s48
	s_cselect_b32 s28, s33, s47
	s_add_i32 s52, 0, 0x14000
	ds_read_b128 v[144:147], v138
	ds_read_b128 v[148:151], v138 offset:1024
	ds_read_b128 v[152:155], v138 offset:2048
	ds_read_b128 v[156:159], v138 offset:3072
	v_add_u32_e32 v138, s52, v141
	ds_read_b128 v[160:163], v138
	ds_read_b128 v[164:167], v138 offset:1024
	ds_read_b128 v[168:171], v138 offset:2048
	ds_read_b128 v[172:175], v138 offset:3072
	v_lshl_add_u64 v[138:139], s[24:25], 0, v[134:135]
	s_add_i32 m0, s39, 0xc000
	ds_read_b128 v[176:179], v143
	ds_read_b128 v[180:183], v143 offset:1024
	ds_read_b128 v[184:187], v143 offset:2048
	ds_read_b128 v[192:195], v143 offset:3072
	ds_read_b128 v[196:199], v143 offset:4096
	ds_read_b128 v[200:203], v143 offset:5120
	ds_read_b128 v[204:207], v143 offset:6144
	ds_read_b128 v[208:211], v143 offset:7168
	global_load_lds_dwordx4 v[138:139], off
	v_lshl_add_u64 v[138:139], s[24:25], 0, v[136:137]
	s_add_i32 m0, s39, 0xe000
	s_nop 0
	global_load_lds_dwordx4 v[138:139], off
	s_waitcnt vmcnt(8)
	s_waitcnt lgkmcnt(0)
	s_barrier
	s_setprio 1
	s_waitcnt lgkmcnt(0)
	v_mfma_f32_16x16x32_bf16 v[124:127], v[144:147], v[176:179], 0
	v_mfma_f32_16x16x32_bf16 v[116:119], v[152:155], v[176:179], 0
	v_mfma_f32_16x16x32_bf16 v[108:111], v[144:147], v[184:187], 0
	v_mfma_f32_16x16x32_bf16 v[100:103], v[152:155], v[184:187], 0
	v_mfma_f32_16x16x32_bf16 v[92:95], v[144:147], v[196:199], 0
	v_mfma_f32_16x16x32_bf16 v[84:87], v[152:155], v[196:199], 0
	v_mfma_f32_16x16x32_bf16 v[76:79], v[144:147], v[204:207], 0
	v_mfma_f32_16x16x32_bf16 v[68:71], v[152:155], v[204:207], 0
	v_mfma_f32_16x16x32_bf16 v[124:127], v[148:151], v[180:183], v[124:127]
	v_mfma_f32_16x16x32_bf16 v[116:119], v[156:159], v[180:183], v[116:119]
	v_mfma_f32_16x16x32_bf16 v[108:111], v[148:151], v[192:195], v[108:111]
	v_mfma_f32_16x16x32_bf16 v[100:103], v[156:159], v[192:195], v[100:103]
	v_mfma_f32_16x16x32_bf16 v[92:95], v[148:151], v[200:203], v[92:95]
	v_mfma_f32_16x16x32_bf16 v[84:87], v[156:159], v[200:203], v[84:87]
	v_mfma_f32_16x16x32_bf16 v[76:79], v[148:151], v[208:211], v[76:79]
	v_mfma_f32_16x16x32_bf16 v[68:71], v[156:159], v[208:211], v[68:71]
	s_setprio 0
	s_setprio 1
	v_mfma_f32_16x16x32_bf16 v[120:123], v[160:163], v[176:179], 0
	v_mfma_f32_16x16x32_bf16 v[112:115], v[168:171], v[176:179], 0
	v_mfma_f32_16x16x32_bf16 v[104:107], v[160:163], v[184:187], 0
	v_mfma_f32_16x16x32_bf16 v[96:99], v[168:171], v[184:187], 0
	v_mfma_f32_16x16x32_bf16 v[88:91], v[160:163], v[196:199], 0
	v_mfma_f32_16x16x32_bf16 v[80:83], v[168:171], v[196:199], 0
	v_mfma_f32_16x16x32_bf16 v[72:75], v[160:163], v[204:207], 0
	v_mfma_f32_16x16x32_bf16 v[64:67], v[168:171], v[204:207], 0
	v_mfma_f32_16x16x32_bf16 v[120:123], v[164:167], v[180:183], v[120:123]
	v_mfma_f32_16x16x32_bf16 v[112:115], v[172:175], v[180:183], v[112:115]
	v_mfma_f32_16x16x32_bf16 v[104:107], v[164:167], v[192:195], v[104:107]
	v_mfma_f32_16x16x32_bf16 v[96:99], v[172:175], v[192:195], v[96:99]
	v_mfma_f32_16x16x32_bf16 v[88:91], v[164:167], v[200:203], v[88:91]
	v_mfma_f32_16x16x32_bf16 v[80:83], v[172:175], v[200:203], v[80:83]
	v_mfma_f32_16x16x32_bf16 v[72:75], v[164:167], v[208:211], v[72:75]
	v_mfma_f32_16x16x32_bf16 v[64:67], v[172:175], v[208:211], v[64:67]
	s_setprio 0
	s_barrier
	s_add_i32 s50, s50, s38
	v_lshl_add_u64 v[138:139], s[28:29], 0, v[188:189]
	s_mov_b32 m0, s50
	ds_read_b128 v[176:179], v143 offset:16384
	ds_read_b128 v[180:183], v143 offset:17408
	ds_read_b128 v[184:187], v143 offset:18432
	ds_read_b128 v[192:195], v143 offset:19456
	ds_read_b128 v[196:199], v143 offset:20480
	ds_read_b128 v[200:203], v143 offset:21504
	ds_read_b128 v[204:207], v143 offset:22528
	ds_read_b128 v[208:211], v143 offset:23552
	global_load_lds_dwordx4 v[138:139], off
	s_add_i32 m0, s50, 0x2000
	s_add_u32 s50, s28, 0x40000
	v_lshl_add_u64 v[212:213], s[28:29], 0, v[128:129]
	s_addc_u32 s51, s29, 0
	s_add_i32 s52, s52, s38
	global_load_lds_dwordx4 v[212:213], off
	v_lshl_add_u64 v[214:215], s[50:51], 0, v[188:189]
	s_mov_b32 m0, s52
	v_lshl_add_u64 v[216:217], s[30:31], 0, v[130:131]
	global_load_lds_dwordx4 v[214:215], off
	v_lshl_add_u64 v[214:215], s[50:51], 0, v[128:129]
	s_add_i32 m0, s52, 0x2000
	s_nop 0
	global_load_lds_dwordx4 v[214:215], off
	v_lshl_add_u64 v[214:215], s[30:31], 0, v[132:133]
	s_mov_b32 m0, s39
	s_nop 0
	global_load_lds_dwordx4 v[214:215], off
	s_mov_b32 m0, s40
	s_nop 0
	global_load_lds_dwordx4 v[216:217], off
	s_waitcnt vmcnt(8)
	s_waitcnt lgkmcnt(0)
	s_barrier
; #define PG8_STAGE(bufoff, gbase, voff) do { _Pragma("unroll") for (int _i = 0; _i < 2; ++_i) \
;         __builtin_amdgcn_global_load_lds((const unsigned*)((const char*)(gbase) + (voff)[_i]), (LAS unsigned*)(lds + (bufoff) + ldsw + _i * 8192), 16, 0, 0); } while (0)
; #define PG8_LDA(dst, b, h) do { _Pragma("unroll") for (int m = 0; m < 4; ++m) _Pragma("unroll") for (int k = 0; k < 2; ++k) dst[m][k] = *(const LAS bf16x8*)(lds + PG8_SA(b, h) + aoff + m * 2048 + k * 1024); } while (0)
; #define PG8_LDB(dst, b, h) do { _Pragma("unroll") for (int n = 0; n < 2; ++n) _Pragma("unroll") for (int k = 0; k < 2; ++k) dst[n][k] = *(const LAS bf16x8*)(lds + PG8_SB(b, h) + boff + n * 2048 + k * 1024); } while (0)
; #define PG8_MMA(ai, bj, At, Bt) do { __builtin_amdgcn_s_setprio(1); _Pragma("unroll") for (int m = 0; m < 4; ++m) _Pragma("unroll") for (int n = 0; n < 2; ++n) _Pragma("unroll") for (int k = 0; k < 2; ++k) \
;         acc[ai][bj][m][n] = __builtin_amdgcn_mfma_f32_16x16x32_bf16(Bt[n][k], At[m][k], acc[ai][bj][m][n], 0, 0, 0); __builtin_amdgcn_s_setprio(0); } while (0)
; #define PG8_WAIT_V(n) asm volatile("s_waitcnt vmcnt(" #n ")" ::: "memory")
; #define PG8_WAIT_L(n) asm volatile("s_waitcnt lgkmcnt(" #n ")" ::: "memory")
; #define PG8_BAR __builtin_amdgcn_s_barrier()
; #define PG8_SCHED __builtin_amdgcn_sched_barrier(0)
; template <class Epi, bool ALIGN_EPI = true>
; DI void gemm_phase(int tb_, LAS unsigned char* lds, const Gemm g, const Sched& S, const Epi& E) {
;     ...
;             PG8_WAIT_V(8); PG8_WAIT_L(0); PG8_BAR; PG8_MMA(1, 0, At, B0); PG8_MMA(1, 1, At, B1); PG8_BAR; PG8_SCHED;
;             PG8_LDB(B0, 1, 0); PG8_LDB(B1, 1, 1); PG8_SCHED; PG8_LDA(At, 1, 0); PG8_STAGE(PG8_SA(0, 1), a2 + hstep, voffA);
;             PG8_WAIT_V(8); PG8_WAIT_L(0); PG8_BAR; PG8_MMA(0, 0, At, B0); PG8_MMA(0, 1, At, B1); PG8_BAR; PG8_SCHED;
	s_setprio 1
	s_waitcnt lgkmcnt(0)
	v_mfma_f32_16x16x32_bf16 v[60:63], v[144:147], v[176:179], 0
	v_mfma_f32_16x16x32_bf16 v[52:55], v[152:155], v[176:179], 0
	v_mfma_f32_16x16x32_bf16 v[44:47], v[144:147], v[184:187], 0
	v_mfma_f32_16x16x32_bf16 v[36:39], v[152:155], v[184:187], 0
	v_mfma_f32_16x16x32_bf16 v[28:31], v[144:147], v[196:199], 0
	v_mfma_f32_16x16x32_bf16 v[20:23], v[152:155], v[196:199], 0
	v_mfma_f32_16x16x32_bf16 v[12:15], v[144:147], v[204:207], 0
	v_mfma_f32_16x16x32_bf16 v[4:7], v[152:155], v[204:207], 0
	v_mfma_f32_16x16x32_bf16 v[60:63], v[148:151], v[180:183], v[60:63]
	v_mfma_f32_16x16x32_bf16 v[52:55], v[156:159], v[180:183], v[52:55]
	v_mfma_f32_16x16x32_bf16 v[44:47], v[148:151], v[192:195], v[44:47]
	v_mfma_f32_16x16x32_bf16 v[36:39], v[156:159], v[192:195], v[36:39]
	v_mfma_f32_16x16x32_bf16 v[28:31], v[148:151], v[200:203], v[28:31]
	v_mfma_f32_16x16x32_bf16 v[20:23], v[156:159], v[200:203], v[20:23]
	v_mfma_f32_16x16x32_bf16 v[12:15], v[148:151], v[208:211], v[12:15]
	v_mfma_f32_16x16x32_bf16 v[4:7], v[156:159], v[208:211], v[4:7]
	s_setprio 0
	s_setprio 1
	v_mfma_f32_16x16x32_bf16 v[56:59], v[160:163], v[176:179], 0
	v_mfma_f32_16x16x32_bf16 v[48:51], v[168:171], v[176:179], 0
	v_mfma_f32_16x16x32_bf16 v[40:43], v[160:163], v[184:187], 0
	v_mfma_f32_16x16x32_bf16 v[32:35], v[168:171], v[184:187], 0
	v_mfma_f32_16x16x32_bf16 v[24:27], v[160:163], v[196:199], 0
	v_mfma_f32_16x16x32_bf16 v[16:19], v[168:171], v[196:199], 0
	v_mfma_f32_16x16x32_bf16 v[8:11], v[160:163], v[204:207], 0
	v_mfma_f32_16x16x32_bf16 v[0:3], v[168:171], v[204:207], 0
	v_mfma_f32_16x16x32_bf16 v[56:59], v[164:167], v[180:183], v[56:59]
	v_mfma_f32_16x16x32_bf16 v[48:51], v[172:175], v[180:183], v[48:51]
	v_mfma_f32_16x16x32_bf16 v[40:43], v[164:167], v[192:195], v[40:43]
	v_mfma_f32_16x16x32_bf16 v[32:35], v[172:175], v[192:195], v[32:35]
	v_mfma_f32_16x16x32_bf16 v[24:27], v[164:167], v[200:203], v[24:27]
	v_mfma_f32_16x16x32_bf16 v[16:19], v[172:175], v[200:203], v[16:19]
	v_mfma_f32_16x16x32_bf16 v[8:11], v[164:167], v[208:211], v[8:11]
	v_mfma_f32_16x16x32_bf16 v[0:3], v[172:175], v[208:211], v[0:3]
	s_setprio 0
	s_barrier
	s_add_i32 s50, 0, 0x18000
	s_add_i32 s51, 0, 0x1c000
	v_add_u32_e32 v156, s50, v141
	v_add_u32_e32 v172, s51, v141
	ds_read_b128 v[144:147], v156
	ds_read_b128 v[148:151], v156 offset:1024
	ds_read_b128 v[152:155], v156 offset:2048
	ds_read_b128 v[156:159], v156 offset:3072
	ds_read_b128 v[160:163], v172
	ds_read_b128 v[164:167], v172 offset:1024
	ds_read_b128 v[168:171], v172 offset:2048
	ds_read_b128 v[172:175], v172 offset:3072
	s_add_u32 s30, s30, 0x40000
	s_addc_u32 s31, s31, 0
	s_mov_b32 m0, s41
	v_lshl_add_u64 v[218:219], s[30:31], 0, v[132:133]
	ds_read_b128 v[176:179], v143 offset:32768
	ds_read_b128 v[180:183], v143 offset:33792
	ds_read_b128 v[184:187], v143 offset:34816
	ds_read_b128 v[192:195], v143 offset:35840
	ds_read_b128 v[196:199], v143 offset:36864
	ds_read_b128 v[200:203], v143 offset:37888
	ds_read_b128 v[204:207], v143 offset:38912
	ds_read_b128 v[208:211], v143 offset:39936
	global_load_lds_dwordx4 v[218:219], off
	v_lshl_add_u64 v[218:219], s[30:31], 0, v[130:131]
	s_mov_b32 m0, s42
	s_nop 0
	global_load_lds_dwordx4 v[218:219], off
	s_waitcnt vmcnt(8)
	s_waitcnt lgkmcnt(0)
	s_barrier
	s_setprio 1
	s_waitcnt lgkmcnt(0)
	v_mfma_f32_16x16x32_bf16 v[124:127], v[144:147], v[176:179], v[124:127]
	v_mfma_f32_16x16x32_bf16 v[116:119], v[152:155], v[176:179], v[116:119]
	v_mfma_f32_16x16x32_bf16 v[108:111], v[144:147], v[184:187], v[108:111]
	v_mfma_f32_16x16x32_bf16 v[100:103], v[152:155], v[184:187], v[100:103]
	v_mfma_f32_16x16x32_bf16 v[92:95], v[144:147], v[196:199], v[92:95]
	v_mfma_f32_16x16x32_bf16 v[84:87], v[152:155], v[196:199], v[84:87]
	v_mfma_f32_16x16x32_bf16 v[76:79], v[144:147], v[204:207], v[76:79]
	v_mfma_f32_16x16x32_bf16 v[68:71], v[152:155], v[204:207], v[68:71]
	v_mfma_f32_16x16x32_bf16 v[124:127], v[148:151], v[180:183], v[124:127]
	v_mfma_f32_16x16x32_bf16 v[116:119], v[156:159], v[180:183], v[116:119]
	v_mfma_f32_16x16x32_bf16 v[108:111], v[148:151], v[192:195], v[108:111]
	v_mfma_f32_16x16x32_bf16 v[100:103], v[156:159], v[192:195], v[100:103]
	v_mfma_f32_16x16x32_bf16 v[92:95], v[148:151], v[200:203], v[92:95]
	v_mfma_f32_16x16x32_bf16 v[84:87], v[156:159], v[200:203], v[84:87]
	v_mfma_f32_16x16x32_bf16 v[76:79], v[148:151], v[208:211], v[76:79]
	v_mfma_f32_16x16x32_bf16 v[68:71], v[156:159], v[208:211], v[68:71]
	s_setprio 0
	s_setprio 1
	v_mfma_f32_16x16x32_bf16 v[120:123], v[160:163], v[176:179], v[120:123]
	v_mfma_f32_16x16x32_bf16 v[112:115], v[168:171], v[176:179], v[112:115]
	v_mfma_f32_16x16x32_bf16 v[104:107], v[160:163], v[184:187], v[104:107]
	v_mfma_f32_16x16x32_bf16 v[96:99], v[168:171], v[184:187], v[96:99]
	v_mfma_f32_16x16x32_bf16 v[88:91], v[160:163], v[196:199], v[88:91]
	v_mfma_f32_16x16x32_bf16 v[80:83], v[168:171], v[196:199], v[80:83]
	v_mfma_f32_16x16x32_bf16 v[72:75], v[160:163], v[204:207], v[72:75]
	v_mfma_f32_16x16x32_bf16 v[64:67], v[168:171], v[204:207], v[64:67]
	v_mfma_f32_16x16x32_bf16 v[120:123], v[164:167], v[180:183], v[120:123]
	v_mfma_f32_16x16x32_bf16 v[112:115], v[172:175], v[180:183], v[112:115]
	v_mfma_f32_16x16x32_bf16 v[104:107], v[164:167], v[192:195], v[104:107]
	v_mfma_f32_16x16x32_bf16 v[96:99], v[172:175], v[192:195], v[96:99]
	v_mfma_f32_16x16x32_bf16 v[88:91], v[164:167], v[200:203], v[88:91]
	v_mfma_f32_16x16x32_bf16 v[80:83], v[172:175], v[200:203], v[80:83]
	v_mfma_f32_16x16x32_bf16 v[72:75], v[164:167], v[208:211], v[72:75]
	v_mfma_f32_16x16x32_bf16 v[64:67], v[172:175], v[208:211], v[64:67]
	s_setprio 0
	s_barrier
; #define PG8_STAGE(bufoff, gbase, voff) do { _Pragma("unroll") for (int _i = 0; _i < 2; ++_i) \
;         __builtin_amdgcn_global_load_lds((const unsigned*)((const char*)(gbase) + (voff)[_i]), (LAS unsigned*)(lds + (bufoff) + ldsw + _i * 8192), 16, 0, 0); } while (0)
; #define PG8_LDA(dst, b, h) do { _Pragma("unroll") for (int m = 0; m < 4; ++m) _Pragma("unroll") for (int k = 0; k < 2; ++k) dst[m][k] = *(const LAS bf16x8*)(lds + PG8_SA(b, h) + aoff + m * 2048 + k * 1024); } while (0)
; #define PG8_MMA(ai, bj, At, Bt) do { __builtin_amdgcn_s_setprio(1); _Pragma("unroll") for (int m = 0; m < 4; ++m) _Pragma("unroll") for (int n = 0; n < 2; ++n) _Pragma("unroll") for (int k = 0; k < 2; ++k) \
;         acc[ai][bj][m][n] = __builtin_amdgcn_mfma_f32_16x16x32_bf16(Bt[n][k], At[m][k], acc[ai][bj][m][n], 0, 0, 0); __builtin_amdgcn_s_setprio(0); } while (0)
; #define PG8_WAIT_V(n) asm volatile("s_waitcnt vmcnt(" #n ")" ::: "memory")
; #define PG8_WAIT_L(n) asm volatile("s_waitcnt lgkmcnt(" #n ")" ::: "memory")
; #define PG8_BAR __builtin_amdgcn_s_barrier()
; #define PG8_SCHED __builtin_amdgcn_sched_barrier(0)
; template <class Epi, bool ALIGN_EPI = true>
; DI void gemm_phase(int tb_, LAS unsigned char* lds, const Gemm g, const Sched& S, const Epi& E) {
;     ...
;             PG8_LDA(At, 1, 1); PG8_STAGE(PG8_SB(1, 0), b3, voffB); PG8_STAGE(PG8_SB(1, 1), b3 + hstep, voffB); PG8_STAGE(PG8_SA(1, 0), a3, voffA);
;             PG8_WAIT_V(8); PG8_WAIT_L(0); PG8_BAR; PG8_MMA(1, 0, At, B0); PG8_MMA(1, 1, At, B1); PG8_BAR; PG8_SCHED;
;         }
	s_add_i32 s30, s50, s38
	v_lshl_add_u64 v[138:139], v[138:139], 0, s[72:73]
	s_mov_b32 m0, s30
	ds_read_b128 v[176:179], v143 offset:49152
	ds_read_b128 v[180:183], v143 offset:50176
	ds_read_b128 v[184:187], v143 offset:51200
	ds_read_b128 v[192:195], v143 offset:52224
	ds_read_b128 v[196:199], v143 offset:53248
	ds_read_b128 v[200:203], v143 offset:54272
	ds_read_b128 v[204:207], v143 offset:55296
	ds_read_b128 v[208:211], v143 offset:56320
	global_load_lds_dwordx4 v[138:139], off
	s_add_i32 m0, s30, 0x2000
	s_add_u32 s28, s28, 0x40080
	v_lshl_add_u64 v[138:139], v[212:213], 0, s[72:73]
	s_addc_u32 s29, s29, 0
	s_add_i32 s30, s51, s38
	global_load_lds_dwordx4 v[138:139], off
	v_lshl_add_u64 v[138:139], s[28:29], 0, v[188:189]
	s_mov_b32 m0, s30
	s_nop 0
	global_load_lds_dwordx4 v[138:139], off
	v_lshl_add_u64 v[138:139], s[28:29], 0, v[128:129]
	s_add_i32 m0, s30, 0x2000
	s_nop 0
	global_load_lds_dwordx4 v[138:139], off
	v_lshl_add_u64 v[138:139], v[214:215], 0, s[72:73]
	s_mov_b32 m0, s44
	s_nop 0
	global_load_lds_dwordx4 v[138:139], off
	v_lshl_add_u64 v[138:139], v[216:217], 0, s[72:73]
	s_mov_b32 m0, s45
	s_nop 0
	global_load_lds_dwordx4 v[138:139], off
	s_waitcnt vmcnt(8)
	s_waitcnt lgkmcnt(0)
	s_barrier
	s_setprio 1
	s_waitcnt lgkmcnt(0)
	v_mfma_f32_16x16x32_bf16 v[60:63], v[144:147], v[176:179], v[60:63]
	v_mfma_f32_16x16x32_bf16 v[52:55], v[152:155], v[176:179], v[52:55]
	v_mfma_f32_16x16x32_bf16 v[44:47], v[144:147], v[184:187], v[44:47]
	v_mfma_f32_16x16x32_bf16 v[36:39], v[152:155], v[184:187], v[36:39]
	v_mfma_f32_16x16x32_bf16 v[28:31], v[144:147], v[196:199], v[28:31]
	v_mfma_f32_16x16x32_bf16 v[20:23], v[152:155], v[196:199], v[20:23]
	v_mfma_f32_16x16x32_bf16 v[12:15], v[144:147], v[204:207], v[12:15]
	v_mfma_f32_16x16x32_bf16 v[4:7], v[152:155], v[204:207], v[4:7]
	v_mfma_f32_16x16x32_bf16 v[60:63], v[148:151], v[180:183], v[60:63]
	v_mfma_f32_16x16x32_bf16 v[52:55], v[156:159], v[180:183], v[52:55]
	v_mfma_f32_16x16x32_bf16 v[44:47], v[148:151], v[192:195], v[44:47]
	v_mfma_f32_16x16x32_bf16 v[36:39], v[156:159], v[192:195], v[36:39]
	v_mfma_f32_16x16x32_bf16 v[28:31], v[148:151], v[200:203], v[28:31]
	v_mfma_f32_16x16x32_bf16 v[20:23], v[156:159], v[200:203], v[20:23]
	v_mfma_f32_16x16x32_bf16 v[12:15], v[148:151], v[208:211], v[12:15]
	v_mfma_f32_16x16x32_bf16 v[4:7], v[156:159], v[208:211], v[4:7]
	s_setprio 0
	s_setprio 1
	v_mfma_f32_16x16x32_bf16 v[56:59], v[160:163], v[176:179], v[56:59]
	v_mfma_f32_16x16x32_bf16 v[48:51], v[168:171], v[176:179], v[48:51]
	v_mfma_f32_16x16x32_bf16 v[40:43], v[160:163], v[184:187], v[40:43]
	v_mfma_f32_16x16x32_bf16 v[32:35], v[168:171], v[184:187], v[32:35]
	v_mfma_f32_16x16x32_bf16 v[24:27], v[160:163], v[196:199], v[24:27]
	v_mfma_f32_16x16x32_bf16 v[16:19], v[168:171], v[196:199], v[16:19]
	v_mfma_f32_16x16x32_bf16 v[8:11], v[160:163], v[204:207], v[8:11]
	v_mfma_f32_16x16x32_bf16 v[0:3], v[168:171], v[204:207], v[0:3]
	v_mfma_f32_16x16x32_bf16 v[56:59], v[164:167], v[180:183], v[56:59]
	v_mfma_f32_16x16x32_bf16 v[48:51], v[172:175], v[180:183], v[48:51]
	v_mfma_f32_16x16x32_bf16 v[40:43], v[164:167], v[192:195], v[40:43]
	v_mfma_f32_16x16x32_bf16 v[32:35], v[172:175], v[192:195], v[32:35]
	v_mfma_f32_16x16x32_bf16 v[24:27], v[164:167], v[200:203], v[24:27]
	v_mfma_f32_16x16x32_bf16 v[16:19], v[172:175], v[200:203], v[16:19]
	v_mfma_f32_16x16x32_bf16 v[8:11], v[164:167], v[208:211], v[8:11]
	v_mfma_f32_16x16x32_bf16 v[0:3], v[172:175], v[208:211], v[0:3]
	s_setprio 0
	s_barrier
	s_add_i32 s49, s49, 2
	s_add_u32 s24, s24, 0x100
	s_addc_u32 s25, s25, 0
	s_add_u32 s47, s47, 0x100
	s_addc_u32 s48, s48, 0
	s_cmp_gt_u32 s49, 13
	s_cbranch_scc1 .Lpeel_exit_0

; #define PG8_BAR __builtin_amdgcn_s_barrier()
; template <class Epi, bool ALIGN_EPI = true>
; DI void gemm_phase(int tb_, LAS unsigned char* lds, const Gemm g, const Sched& S, const Epi& E) {
;     ...
;         if constexpr (ALIGN_EPI) { if (wr == 0) PG8_BAR; }
.Lpeel_exit_0:
	s_and_b64 vcc, exec, s[12:13]
	s_cbranch_vccz .LBB0_298
	s_barrier

; #define PG8_STAGE(bufoff, gbase, voff) do { _Pragma("unroll") for (int _i = 0; _i < 2; ++_i) \
;         __builtin_amdgcn_global_load_lds((const unsigned*)((const char*)(gbase) + (voff)[_i]), (LAS unsigned*)(lds + (bufoff) + ldsw + _i * 8192), 16, 0, 0); } while (0)
; #define PG8_LDA(dst, b, h) do { _Pragma("unroll") for (int m = 0; m < 4; ++m) _Pragma("unroll") for (int k = 0; k < 2; ++k) dst[m][k] = *(const LAS bf16x8*)(lds + PG8_SA(b, h) + aoff + m * 2048 + k * 1024); } while (0)
; #define PG8_LDB(dst, b, h) do { _Pragma("unroll") for (int n = 0; n < 2; ++n) _Pragma("unroll") for (int k = 0; k < 2; ++k) dst[n][k] = *(const LAS bf16x8*)(lds + PG8_SB(b, h) + boff + n * 2048 + k * 1024); } while (0)
; #define PG8_WAIT_V(n) asm volatile("s_waitcnt vmcnt(" #n ")" ::: "memory")
; #define PG8_WAIT_L(n) asm volatile("s_waitcnt lgkmcnt(" #n ")" ::: "memory")
; #define PG8_BAR __builtin_amdgcn_s_barrier()
; #define PG8_SCHED __builtin_amdgcn_sched_barrier(0)
; template <class Epi, bool ALIGN_EPI = true>
; DI void gemm_phase(int tb_, LAS unsigned char* lds, const Gemm g, const Sched& S, const Epi& E) {
;     ...
;         const bool has_next = S.next(ui + 1, nxt);
;         const char* nA = has_next ? PG8_APTR(nxt) : cA; const char* nB = has_next ? PG8_BPTR(nxt) : cB;
;         const int nt = cur.nt;
;         for (int t = 0; t < nt; t += 2) {
;             const bool last = (t == nt - 2);
;             const char* a1 = cA + (size_t)(t + 1) * kstep;
;             const char* a2 = last ? nA : cA + (size_t)(t + 2) * kstep; const char* b2 = last ? nB : cB + (size_t)(t + 2) * kstep;
;             const char* a3 = a2 + kstep; const char* b3 = b2 + kstep;
;             PG8_LDB(B0, 0, 0); PG8_LDB(B1, 0, 1); PG8_SCHED; PG8_LDA(At, 0, 0); PG8_STAGE(PG8_SA(1, 1), a1 + hstep, voffA);
;             PG8_WAIT_V(8); PG8_WAIT_L(0); PG8_BAR; PG8_MMA(0, 0, At, B0); PG8_MMA(0, 1, At, B1); PG8_BAR; PG8_SCHED;
;             PG8_LDA(At, 0, 1); PG8_STAGE(PG8_SB(0, 0), b2, voffB); PG8_STAGE(PG8_SB(0, 1), b2 + hstep, voffB); PG8_STAGE(PG8_SA(0, 0), a2, voffA);
;     ...
;         for (int a = 0; a < 2; ++a)
; #pragma unroll
;             for (int b = 0; b < 2; ++b)
; #pragma unroll
;                 for (int m = 0; m < 4; ++m)
; #pragma unroll
;                     for (int n = 0; n < 2; ++n) acc[a][b][m][n] = (f32x4){0.f, 0.f, 0.f, 0.f};
.LBB0_389:
	s_add_i32 s5, s4, -2
	s_add_u32 s15, s28, 0x100
	s_addc_u32 s25, s29, 0
	s_mov_b32 s30, 0
	s_add_i32 s33, s30, 2
	s_add_u32 s28, s8, 0x100
	s_addc_u32 s29, s9, 0
	s_add_i32 s52, 0, 0x10000
	s_cmp_eq_u32 s5, s30
	s_cselect_b32 s35, s21, s29
	s_cselect_b32 s34, s20, s28
	s_cselect_b32 s31, s23, s25
	s_cselect_b32 s30, s22, s15
	s_add_i32 s58, 0, 0x14000
	v_add_u32_e32 v140, s52, v241
	v_add_u32_e32 v156, s58, v241
	ds_read_b128 v[128:131], v140
	ds_read_b128 v[132:135], v140 offset:1024
	ds_read_b128 v[136:139], v140 offset:2048
	ds_read_b128 v[140:143], v140 offset:3072
	ds_read_b128 v[144:147], v156
	ds_read_b128 v[148:151], v156 offset:1024
	ds_read_b128 v[152:155], v156 offset:2048
	ds_read_b128 v[156:159], v156 offset:3072
	v_lshl_add_u64 v[248:249], s[8:9], 0, v[198:199]
	s_add_i32 m0, s44, 0xc000
	ds_read_b128 v[202:205], v243
	ds_read_b128 v[206:209], v243 offset:1024
	ds_read_b128 v[210:213], v243 offset:2048
	ds_read_b128 v[214:217], v243 offset:3072
	ds_read_b128 v[218:221], v243 offset:4096
	ds_read_b128 v[222:225], v243 offset:5120
	ds_read_b128 v[226:229], v243 offset:6144
	ds_read_b128 v[244:247], v243 offset:7168
	global_load_lds_dwordx4 v[248:249], off
	v_lshl_add_u64 v[248:249], s[8:9], 0, v[200:201]
	s_add_i32 m0, s44, 0xe000
	s_nop 0
	global_load_lds_dwordx4 v[248:249], off
	s_waitcnt vmcnt(8)
	s_waitcnt lgkmcnt(0)
	s_barrier
	s_setprio 1
	s_waitcnt lgkmcnt(0)
	v_mfma_f32_16x16x32_bf16 v[124:127], v[128:131], v[202:205], 0
	v_mfma_f32_16x16x32_bf16 v[120:123], v[136:139], v[202:205], 0
	v_mfma_f32_16x16x32_bf16 v[108:111], v[128:131], v[210:213], 0
	v_mfma_f32_16x16x32_bf16 v[104:107], v[136:139], v[210:213], 0
	v_mfma_f32_16x16x32_bf16 v[92:95], v[128:131], v[218:221], 0
	v_mfma_f32_16x16x32_bf16 v[88:91], v[136:139], v[218:221], 0
	v_mfma_f32_16x16x32_bf16 v[76:79], v[128:131], v[226:229], 0
	v_mfma_f32_16x16x32_bf16 v[72:75], v[136:139], v[226:229], 0
	v_mfma_f32_16x16x32_bf16 v[124:127], v[132:135], v[206:209], v[124:127]
	v_mfma_f32_16x16x32_bf16 v[120:123], v[140:143], v[206:209], v[120:123]
	v_mfma_f32_16x16x32_bf16 v[108:111], v[132:135], v[214:217], v[108:111]
	v_mfma_f32_16x16x32_bf16 v[104:107], v[140:143], v[214:217], v[104:107]
	v_mfma_f32_16x16x32_bf16 v[92:95], v[132:135], v[222:225], v[92:95]
	v_mfma_f32_16x16x32_bf16 v[88:91], v[140:143], v[222:225], v[88:91]
	v_mfma_f32_16x16x32_bf16 v[76:79], v[132:135], v[244:247], v[76:79]
	v_mfma_f32_16x16x32_bf16 v[72:75], v[140:143], v[244:247], v[72:75]
	s_setprio 0
	s_setprio 1
	v_mfma_f32_16x16x32_bf16 v[116:119], v[144:147], v[202:205], 0
	v_mfma_f32_16x16x32_bf16 v[112:115], v[152:155], v[202:205], 0
	v_mfma_f32_16x16x32_bf16 v[100:103], v[144:147], v[210:213], 0
	v_mfma_f32_16x16x32_bf16 v[96:99], v[152:155], v[210:213], 0
	v_mfma_f32_16x16x32_bf16 v[84:87], v[144:147], v[218:221], 0
	v_mfma_f32_16x16x32_bf16 v[80:83], v[152:155], v[218:221], 0
	v_mfma_f32_16x16x32_bf16 v[68:71], v[144:147], v[226:229], 0
	v_mfma_f32_16x16x32_bf16 v[64:67], v[152:155], v[226:229], 0
	v_mfma_f32_16x16x32_bf16 v[116:119], v[148:151], v[206:209], v[116:119]
	v_mfma_f32_16x16x32_bf16 v[112:115], v[156:159], v[206:209], v[112:115]
	v_mfma_f32_16x16x32_bf16 v[100:103], v[148:151], v[214:217], v[100:103]
	v_mfma_f32_16x16x32_bf16 v[96:99], v[156:159], v[214:217], v[96:99]
	v_mfma_f32_16x16x32_bf16 v[84:87], v[148:151], v[222:225], v[84:87]
	v_mfma_f32_16x16x32_bf16 v[80:83], v[156:159], v[222:225], v[80:83]
	v_mfma_f32_16x16x32_bf16 v[68:71], v[148:151], v[244:247], v[68:71]
	v_mfma_f32_16x16x32_bf16 v[64:67], v[156:159], v[244:247], v[64:67]
	s_setprio 0
	s_barrier
	s_add_i32 s8, s52, s43
	v_lshl_add_u64 v[248:249], s[30:31], 0, v[188:189]
	s_mov_b32 m0, s8
	ds_read_b128 v[202:205], v243 offset:16384
	ds_read_b128 v[206:209], v243 offset:17408
	ds_read_b128 v[210:213], v243 offset:18432
	ds_read_b128 v[214:217], v243 offset:19456
	ds_read_b128 v[218:221], v243 offset:20480
	ds_read_b128 v[222:225], v243 offset:21504
	ds_read_b128 v[226:229], v243 offset:22528
	ds_read_b128 v[244:247], v243 offset:23552
	global_load_lds_dwordx4 v[248:249], off
	s_add_i32 m0, s8, 0x2000
	s_add_u32 s8, s30, 0xb0000
	v_lshl_add_u64 v[250:251], s[30:31], 0, v[160:161]
	s_addc_u32 s9, s31, 0
	s_add_i32 s52, s58, s43
	global_load_lds_dwordx4 v[250:251], off
	v_lshl_add_u64 v[252:253], s[8:9], 0, v[188:189]
	s_mov_b32 m0, s52
	v_lshl_add_u64 v[232:233], s[34:35], 0, v[160:161]
	global_load_lds_dwordx4 v[252:253], off
	v_lshl_add_u64 v[252:253], s[8:9], 0, v[160:161]
	s_add_i32 m0, s52, 0x2000
	s_nop 0
	global_load_lds_dwordx4 v[252:253], off
	v_lshl_add_u64 v[252:253], s[34:35], 0, v[188:189]
	s_mov_b32 m0, s44
	s_nop 0
	global_load_lds_dwordx4 v[252:253], off
	s_mov_b32 m0, s45
	s_nop 0
	global_load_lds_dwordx4 v[232:233], off
	s_waitcnt vmcnt(8)
	s_waitcnt lgkmcnt(0)
	s_barrier
; #define PG8_STAGE(bufoff, gbase, voff) do { _Pragma("unroll") for (int _i = 0; _i < 2; ++_i) \
;         __builtin_amdgcn_global_load_lds((const unsigned*)((const char*)(gbase) + (voff)[_i]), (LAS unsigned*)(lds + (bufoff) + ldsw + _i * 8192), 16, 0, 0); } while (0)
; #define PG8_LDA(dst, b, h) do { _Pragma("unroll") for (int m = 0; m < 4; ++m) _Pragma("unroll") for (int k = 0; k < 2; ++k) dst[m][k] = *(const LAS bf16x8*)(lds + PG8_SA(b, h) + aoff + m * 2048 + k * 1024); } while (0)
; #define PG8_LDB(dst, b, h) do { _Pragma("unroll") for (int n = 0; n < 2; ++n) _Pragma("unroll") for (int k = 0; k < 2; ++k) dst[n][k] = *(const LAS bf16x8*)(lds + PG8_SB(b, h) + boff + n * 2048 + k * 1024); } while (0)
; #define PG8_MMA(ai, bj, At, Bt) do { __builtin_amdgcn_s_setprio(1); _Pragma("unroll") for (int m = 0; m < 4; ++m) _Pragma("unroll") for (int n = 0; n < 2; ++n) _Pragma("unroll") for (int k = 0; k < 2; ++k) \
;         acc[ai][bj][m][n] = __builtin_amdgcn_mfma_f32_16x16x32_bf16(Bt[n][k], At[m][k], acc[ai][bj][m][n], 0, 0, 0); __builtin_amdgcn_s_setprio(0); } while (0)
; #define PG8_WAIT_V(n) asm volatile("s_waitcnt vmcnt(" #n ")" ::: "memory")
; #define PG8_WAIT_L(n) asm volatile("s_waitcnt lgkmcnt(" #n ")" ::: "memory")
; #define PG8_BAR __builtin_amdgcn_s_barrier()
; #define PG8_SCHED __builtin_amdgcn_sched_barrier(0)
; template <class Epi, bool ALIGN_EPI = true>
; DI void gemm_phase(int tb_, LAS unsigned char* lds, const Gemm g, const Sched& S, const Epi& E) {
;     ...
;             PG8_WAIT_V(8); PG8_WAIT_L(0); PG8_BAR; PG8_MMA(1, 0, At, B0); PG8_MMA(1, 1, At, B1); PG8_BAR; PG8_SCHED;
;             PG8_LDB(B0, 1, 0); PG8_LDB(B1, 1, 1); PG8_SCHED; PG8_LDA(At, 1, 0); PG8_STAGE(PG8_SA(0, 1), a2 + hstep, voffA);
;             PG8_WAIT_V(8); PG8_WAIT_L(0); PG8_BAR; PG8_MMA(0, 0, At, B0); PG8_MMA(0, 1, At, B1); PG8_BAR; PG8_SCHED;
	s_setprio 1
	s_waitcnt lgkmcnt(0)
	v_mfma_f32_16x16x32_bf16 v[60:63], v[128:131], v[202:205], 0
	v_mfma_f32_16x16x32_bf16 v[56:59], v[136:139], v[202:205], 0
	v_mfma_f32_16x16x32_bf16 v[44:47], v[128:131], v[210:213], 0
	v_mfma_f32_16x16x32_bf16 v[40:43], v[136:139], v[210:213], 0
	v_mfma_f32_16x16x32_bf16 v[28:31], v[128:131], v[218:221], 0
	v_mfma_f32_16x16x32_bf16 v[24:27], v[136:139], v[218:221], 0
	v_mfma_f32_16x16x32_bf16 v[12:15], v[128:131], v[226:229], 0
	v_mfma_f32_16x16x32_bf16 v[8:11], v[136:139], v[226:229], 0
	v_mfma_f32_16x16x32_bf16 v[60:63], v[132:135], v[206:209], v[60:63]
	v_mfma_f32_16x16x32_bf16 v[56:59], v[140:143], v[206:209], v[56:59]
	v_mfma_f32_16x16x32_bf16 v[44:47], v[132:135], v[214:217], v[44:47]
	v_mfma_f32_16x16x32_bf16 v[40:43], v[140:143], v[214:217], v[40:43]
	v_mfma_f32_16x16x32_bf16 v[28:31], v[132:135], v[222:225], v[28:31]
	v_mfma_f32_16x16x32_bf16 v[24:27], v[140:143], v[222:225], v[24:27]
	v_mfma_f32_16x16x32_bf16 v[12:15], v[132:135], v[244:247], v[12:15]
	v_mfma_f32_16x16x32_bf16 v[8:11], v[140:143], v[244:247], v[8:11]
	s_setprio 0
	s_setprio 1
	v_mfma_f32_16x16x32_bf16 v[52:55], v[144:147], v[202:205], 0
	v_mfma_f32_16x16x32_bf16 v[48:51], v[152:155], v[202:205], 0
	v_mfma_f32_16x16x32_bf16 v[36:39], v[144:147], v[210:213], 0
	v_mfma_f32_16x16x32_bf16 v[32:35], v[152:155], v[210:213], 0
	v_mfma_f32_16x16x32_bf16 v[20:23], v[144:147], v[218:221], 0
	v_mfma_f32_16x16x32_bf16 v[16:19], v[152:155], v[218:221], 0
	v_mfma_f32_16x16x32_bf16 v[4:7], v[144:147], v[226:229], 0
	v_mfma_f32_16x16x32_bf16 v[0:3], v[152:155], v[226:229], 0
	v_mfma_f32_16x16x32_bf16 v[52:55], v[148:151], v[206:209], v[52:55]
	v_mfma_f32_16x16x32_bf16 v[48:51], v[156:159], v[206:209], v[48:51]
	v_mfma_f32_16x16x32_bf16 v[36:39], v[148:151], v[214:217], v[36:39]
	v_mfma_f32_16x16x32_bf16 v[32:35], v[156:159], v[214:217], v[32:35]
	v_mfma_f32_16x16x32_bf16 v[20:23], v[148:151], v[222:225], v[20:23]
	v_mfma_f32_16x16x32_bf16 v[16:19], v[156:159], v[222:225], v[16:19]
	v_mfma_f32_16x16x32_bf16 v[4:7], v[148:151], v[244:247], v[4:7]
	v_mfma_f32_16x16x32_bf16 v[0:3], v[156:159], v[244:247], v[0:3]
	s_setprio 0
	s_barrier
	s_add_i32 s52, 0, 0x18000
	s_add_i32 s58, 0, 0x1c000
	v_add_u32_e32 v140, s52, v241
	v_add_u32_e32 v156, s58, v241
	ds_read_b128 v[128:131], v140
	ds_read_b128 v[132:135], v140 offset:1024
	ds_read_b128 v[136:139], v140 offset:2048
	ds_read_b128 v[140:143], v140 offset:3072
	ds_read_b128 v[144:147], v156
	ds_read_b128 v[148:151], v156 offset:1024
	ds_read_b128 v[152:155], v156 offset:2048
	ds_read_b128 v[156:159], v156 offset:3072
	s_add_u32 s8, s34, 0xb0000
	s_addc_u32 s9, s35, 0
	s_mov_b32 m0, s46
	v_lshl_add_u64 v[234:235], s[8:9], 0, v[188:189]
	ds_read_b128 v[202:205], v243 offset:32768
	ds_read_b128 v[206:209], v243 offset:33792
	ds_read_b128 v[210:213], v243 offset:34816
	ds_read_b128 v[214:217], v243 offset:35840
	ds_read_b128 v[218:221], v243 offset:36864
	ds_read_b128 v[222:225], v243 offset:37888
	ds_read_b128 v[226:229], v243 offset:38912
	ds_read_b128 v[244:247], v243 offset:39936
	global_load_lds_dwordx4 v[234:235], off
	v_lshl_add_u64 v[234:235], s[8:9], 0, v[160:161]
	s_mov_b32 m0, s47
	s_nop 0
	global_load_lds_dwordx4 v[234:235], off
	s_waitcnt vmcnt(8)
	s_waitcnt lgkmcnt(0)
	s_barrier
	s_setprio 1
	s_waitcnt lgkmcnt(0)
	v_mfma_f32_16x16x32_bf16 v[124:127], v[128:131], v[202:205], v[124:127]
	v_mfma_f32_16x16x32_bf16 v[120:123], v[136:139], v[202:205], v[120:123]
	v_mfma_f32_16x16x32_bf16 v[108:111], v[128:131], v[210:213], v[108:111]
	v_mfma_f32_16x16x32_bf16 v[104:107], v[136:139], v[210:213], v[104:107]
	v_mfma_f32_16x16x32_bf16 v[92:95], v[128:131], v[218:221], v[92:95]
	v_mfma_f32_16x16x32_bf16 v[88:91], v[136:139], v[218:221], v[88:91]
	v_mfma_f32_16x16x32_bf16 v[76:79], v[128:131], v[226:229], v[76:79]
	v_mfma_f32_16x16x32_bf16 v[72:75], v[136:139], v[226:229], v[72:75]
	v_mfma_f32_16x16x32_bf16 v[124:127], v[132:135], v[206:209], v[124:127]
	v_mfma_f32_16x16x32_bf16 v[120:123], v[140:143], v[206:209], v[120:123]
	v_mfma_f32_16x16x32_bf16 v[108:111], v[132:135], v[214:217], v[108:111]
	v_mfma_f32_16x16x32_bf16 v[104:107], v[140:143], v[214:217], v[104:107]
	v_mfma_f32_16x16x32_bf16 v[92:95], v[132:135], v[222:225], v[92:95]
	v_mfma_f32_16x16x32_bf16 v[88:91], v[140:143], v[222:225], v[88:91]
	v_mfma_f32_16x16x32_bf16 v[76:79], v[132:135], v[244:247], v[76:79]
	v_mfma_f32_16x16x32_bf16 v[72:75], v[140:143], v[244:247], v[72:75]
	s_setprio 0
	s_setprio 1
	v_mfma_f32_16x16x32_bf16 v[116:119], v[144:147], v[202:205], v[116:119]
	v_mfma_f32_16x16x32_bf16 v[112:115], v[152:155], v[202:205], v[112:115]
	v_mfma_f32_16x16x32_bf16 v[100:103], v[144:147], v[210:213], v[100:103]
	v_mfma_f32_16x16x32_bf16 v[96:99], v[152:155], v[210:213], v[96:99]
	v_mfma_f32_16x16x32_bf16 v[84:87], v[144:147], v[218:221], v[84:87]
	v_mfma_f32_16x16x32_bf16 v[80:83], v[152:155], v[218:221], v[80:83]
	v_mfma_f32_16x16x32_bf16 v[68:71], v[144:147], v[226:229], v[68:71]
	v_mfma_f32_16x16x32_bf16 v[64:67], v[152:155], v[226:229], v[64:67]
	v_mfma_f32_16x16x32_bf16 v[116:119], v[148:151], v[206:209], v[116:119]
	v_mfma_f32_16x16x32_bf16 v[112:115], v[156:159], v[206:209], v[112:115]
	v_mfma_f32_16x16x32_bf16 v[100:103], v[148:151], v[214:217], v[100:103]
	v_mfma_f32_16x16x32_bf16 v[96:99], v[156:159], v[214:217], v[96:99]
	v_mfma_f32_16x16x32_bf16 v[84:87], v[148:151], v[222:225], v[84:87]
	v_mfma_f32_16x16x32_bf16 v[80:83], v[156:159], v[222:225], v[80:83]
	v_mfma_f32_16x16x32_bf16 v[68:71], v[148:151], v[244:247], v[68:71]
	v_mfma_f32_16x16x32_bf16 v[64:67], v[156:159], v[244:247], v[64:67]
	s_setprio 0
	s_barrier
; #define PG8_STAGE(bufoff, gbase, voff) do { _Pragma("unroll") for (int _i = 0; _i < 2; ++_i) \
;         __builtin_amdgcn_global_load_lds((const unsigned*)((const char*)(gbase) + (voff)[_i]), (LAS unsigned*)(lds + (bufoff) + ldsw + _i * 8192), 16, 0, 0); } while (0)
; #define PG8_LDA(dst, b, h) do { _Pragma("unroll") for (int m = 0; m < 4; ++m) _Pragma("unroll") for (int k = 0; k < 2; ++k) dst[m][k] = *(const LAS bf16x8*)(lds + PG8_SA(b, h) + aoff + m * 2048 + k * 1024); } while (0)
; #define PG8_MMA(ai, bj, At, Bt) do { __builtin_amdgcn_s_setprio(1); _Pragma("unroll") for (int m = 0; m < 4; ++m) _Pragma("unroll") for (int n = 0; n < 2; ++n) _Pragma("unroll") for (int k = 0; k < 2; ++k) \
;         acc[ai][bj][m][n] = __builtin_amdgcn_mfma_f32_16x16x32_bf16(Bt[n][k], At[m][k], acc[ai][bj][m][n], 0, 0, 0); __builtin_amdgcn_s_setprio(0); } while (0)
; #define PG8_WAIT_V(n) asm volatile("s_waitcnt vmcnt(" #n ")" ::: "memory")
; #define PG8_WAIT_L(n) asm volatile("s_waitcnt lgkmcnt(" #n ")" ::: "memory")
; #define PG8_BAR __builtin_amdgcn_s_barrier()
; #define PG8_SCHED __builtin_amdgcn_sched_barrier(0)
; template <class Epi, bool ALIGN_EPI = true>
; DI void gemm_phase(int tb_, LAS unsigned char* lds, const Gemm g, const Sched& S, const Epi& E) {
;     ...
;             PG8_LDA(At, 1, 1); PG8_STAGE(PG8_SB(1, 0), b3, voffB); PG8_STAGE(PG8_SB(1, 1), b3 + hstep, voffB); PG8_STAGE(PG8_SA(1, 0), a3, voffA);
;             PG8_WAIT_V(8); PG8_WAIT_L(0); PG8_BAR; PG8_MMA(1, 0, At, B0); PG8_MMA(1, 1, At, B1); PG8_BAR; PG8_SCHED;
;         }
	s_add_i32 s8, s52, s43
	v_lshl_add_u64 v[234:235], v[248:249], 0, s[72:73]
	s_mov_b32 m0, s8
	ds_read_b128 v[202:205], v243 offset:49152
	ds_read_b128 v[206:209], v243 offset:50176
	ds_read_b128 v[210:213], v243 offset:51200
	ds_read_b128 v[214:217], v243 offset:52224
	ds_read_b128 v[218:221], v243 offset:53248
	ds_read_b128 v[222:225], v243 offset:54272
	ds_read_b128 v[226:229], v243 offset:55296
	ds_read_b128 v[244:247], v243 offset:56320
	global_load_lds_dwordx4 v[234:235], off
	s_add_i32 m0, s8, 0x2000
	s_add_u32 s8, s30, 0xb0080
	v_lshl_add_u64 v[234:235], v[250:251], 0, s[72:73]
	s_addc_u32 s9, s31, 0
	s_add_i32 s30, s58, s43
	global_load_lds_dwordx4 v[234:235], off
	v_lshl_add_u64 v[234:235], s[8:9], 0, v[188:189]
	s_mov_b32 m0, s30
	v_lshl_add_u64 v[232:233], v[232:233], 0, s[72:73]
	global_load_lds_dwordx4 v[234:235], off
	v_lshl_add_u64 v[234:235], s[8:9], 0, v[160:161]
	s_add_i32 m0, s30, 0x2000
	s_nop 0
	global_load_lds_dwordx4 v[234:235], off
	v_lshl_add_u64 v[234:235], v[252:253], 0, s[72:73]
	s_mov_b32 m0, s48
	s_nop 0
	global_load_lds_dwordx4 v[234:235], off
	s_mov_b32 m0, s49
	s_nop 0
	global_load_lds_dwordx4 v[232:233], off
	s_waitcnt vmcnt(8)
	s_waitcnt lgkmcnt(0)
	s_barrier
	s_setprio 1
	s_waitcnt lgkmcnt(0)
	v_mfma_f32_16x16x32_bf16 v[60:63], v[128:131], v[202:205], v[60:63]
	v_mfma_f32_16x16x32_bf16 v[56:59], v[136:139], v[202:205], v[56:59]
	v_mfma_f32_16x16x32_bf16 v[44:47], v[128:131], v[210:213], v[44:47]
	v_mfma_f32_16x16x32_bf16 v[40:43], v[136:139], v[210:213], v[40:43]
	v_mfma_f32_16x16x32_bf16 v[28:31], v[128:131], v[218:221], v[28:31]
	v_mfma_f32_16x16x32_bf16 v[24:27], v[136:139], v[218:221], v[24:27]
	v_mfma_f32_16x16x32_bf16 v[12:15], v[128:131], v[226:229], v[12:15]
	v_mfma_f32_16x16x32_bf16 v[8:11], v[136:139], v[226:229], v[8:11]
	v_mfma_f32_16x16x32_bf16 v[60:63], v[132:135], v[206:209], v[60:63]
	v_mfma_f32_16x16x32_bf16 v[56:59], v[140:143], v[206:209], v[56:59]
	v_mfma_f32_16x16x32_bf16 v[44:47], v[132:135], v[214:217], v[44:47]
	v_mfma_f32_16x16x32_bf16 v[40:43], v[140:143], v[214:217], v[40:43]
	v_mfma_f32_16x16x32_bf16 v[28:31], v[132:135], v[222:225], v[28:31]
	v_mfma_f32_16x16x32_bf16 v[24:27], v[140:143], v[222:225], v[24:27]
	v_mfma_f32_16x16x32_bf16 v[12:15], v[132:135], v[244:247], v[12:15]
	v_mfma_f32_16x16x32_bf16 v[8:11], v[140:143], v[244:247], v[8:11]
	s_setprio 0
	s_setprio 1
	v_mfma_f32_16x16x32_bf16 v[52:55], v[144:147], v[202:205], v[52:55]
	v_mfma_f32_16x16x32_bf16 v[48:51], v[152:155], v[202:205], v[48:51]
	v_mfma_f32_16x16x32_bf16 v[36:39], v[144:147], v[210:213], v[36:39]
	v_mfma_f32_16x16x32_bf16 v[32:35], v[152:155], v[210:213], v[32:35]
	v_mfma_f32_16x16x32_bf16 v[20:23], v[144:147], v[218:221], v[20:23]
	v_mfma_f32_16x16x32_bf16 v[16:19], v[152:155], v[218:221], v[16:19]
	v_mfma_f32_16x16x32_bf16 v[4:7], v[144:147], v[226:229], v[4:7]
	v_mfma_f32_16x16x32_bf16 v[0:3], v[152:155], v[226:229], v[0:3]
	v_mfma_f32_16x16x32_bf16 v[52:55], v[148:151], v[206:209], v[52:55]
	v_mfma_f32_16x16x32_bf16 v[48:51], v[156:159], v[206:209], v[48:51]
	v_mfma_f32_16x16x32_bf16 v[36:39], v[148:151], v[214:217], v[36:39]
	v_mfma_f32_16x16x32_bf16 v[32:35], v[156:159], v[214:217], v[32:35]
	v_mfma_f32_16x16x32_bf16 v[20:23], v[148:151], v[222:225], v[20:23]
	v_mfma_f32_16x16x32_bf16 v[16:19], v[156:159], v[222:225], v[16:19]
	v_mfma_f32_16x16x32_bf16 v[4:7], v[148:151], v[244:247], v[4:7]
	v_mfma_f32_16x16x32_bf16 v[0:3], v[156:159], v[244:247], v[0:3]
	s_setprio 0
	s_barrier
	s_add_u32 s15, s15, 0x100
	s_addc_u32 s25, s25, 0
	s_cmp_ge_i32 s33, s4
	s_mov_b64 s[8:9], s[28:29]
	s_mov_b32 s30, s33
	s_cbranch_scc1 .Lpeel_exit_1

; #define PG8_BAR __builtin_amdgcn_s_barrier()
; template <class Epi, bool ALIGN_EPI = true>
; DI void gemm_phase(int tb_, LAS unsigned char* lds, const Gemm g, const Sched& S, const Epi& E) {
;     ...
;         if constexpr (ALIGN_EPI) { if (wr == 0) PG8_BAR; }
.Lpeel_exit_1:
	s_and_b64 vcc, exec, s[18:19]
	s_cbranch_vccz .LBB0_393

; #define PG8_STAGE(bufoff, gbase, voff) do { _Pragma("unroll") for (int _i = 0; _i < 2; ++_i) \
;         __builtin_amdgcn_global_load_lds((const unsigned*)((const char*)(gbase) + (voff)[_i]), (LAS unsigned*)(lds + (bufoff) + ldsw + _i * 8192), 16, 0, 0); } while (0)
; #define PG8_LDA(dst, b, h) do { _Pragma("unroll") for (int m = 0; m < 4; ++m) _Pragma("unroll") for (int k = 0; k < 2; ++k) dst[m][k] = *(const LAS bf16x8*)(lds + PG8_SA(b, h) + aoff + m * 2048 + k * 1024); } while (0)
; #define PG8_LDB(dst, b, h) do { _Pragma("unroll") for (int n = 0; n < 2; ++n) _Pragma("unroll") for (int k = 0; k < 2; ++k) dst[n][k] = *(const LAS bf16x8*)(lds + PG8_SB(b, h) + boff + n * 2048 + k * 1024); } while (0)
; #define PG8_WAIT_V(n) asm volatile("s_waitcnt vmcnt(" #n ")" ::: "memory")
; #define PG8_WAIT_L(n) asm volatile("s_waitcnt lgkmcnt(" #n ")" ::: "memory")
; #define PG8_BAR __builtin_amdgcn_s_barrier()
; #define PG8_SCHED __builtin_amdgcn_sched_barrier(0)
; template <class Epi, bool ALIGN_EPI = true>
; DI void gemm_phase(int tb_, LAS unsigned char* lds, const Gemm g, const Sched& S, const Epi& E) {
;     ...
;         const bool has_next = S.next(ui + 1, nxt);
;         const char* nA = has_next ? PG8_APTR(nxt) : cA; const char* nB = has_next ? PG8_BPTR(nxt) : cB;
;         const int nt = cur.nt;
;         for (int t = 0; t < nt; t += 2) {
;             const bool last = (t == nt - 2);
;             const char* a1 = cA + (size_t)(t + 1) * kstep;
;             const char* a2 = last ? nA : cA + (size_t)(t + 2) * kstep; const char* b2 = last ? nB : cB + (size_t)(t + 2) * kstep;
;             const char* a3 = a2 + kstep; const char* b3 = b2 + kstep;
;             PG8_LDB(B0, 0, 0); PG8_LDB(B1, 0, 1); PG8_SCHED; PG8_LDA(At, 0, 0); PG8_STAGE(PG8_SA(1, 1), a1 + hstep, voffA);
;             PG8_WAIT_V(8); PG8_WAIT_L(0); PG8_BAR; PG8_MMA(0, 0, At, B0); PG8_MMA(0, 1, At, B1); PG8_BAR; PG8_SCHED;
;             PG8_LDA(At, 0, 1); PG8_STAGE(PG8_SB(0, 0), b2, voffB); PG8_STAGE(PG8_SB(0, 1), b2 + hstep, voffB); PG8_STAGE(PG8_SA(0, 0), a2, voffA);
;     ...
;         for (int a = 0; a < 2; ++a)
; #pragma unroll
;             for (int b = 0; b < 2; ++b)
; #pragma unroll
;                 for (int m = 0; m < 4; ++m)
; #pragma unroll
;                     for (int n = 0; n < 2; ++n) acc[a][b][m][n] = (f32x4){0.f, 0.f, 0.f, 0.f};
.LBB0_812:
	s_ashr_i32 s19, s18, 31
	s_lshl_b64 s[34:35], s[18:19], 19
	s_add_u32 s19, s5, s34
	s_addc_u32 s23, s27, s35
	s_and_b64 s[8:9], s[8:9], exec
	s_cselect_b32 s9, s23, s29
	s_cselect_b32 s8, s19, s28
	s_add_u32 s28, s28, 0x40080
	s_addc_u32 s29, s29, 0
	s_add_u32 s19, s30, 0x100
	s_addc_u32 s23, s31, 0
	s_mov_b32 s48, -2
	s_add_u32 s30, s28, 0xfffc0080
	s_addc_u32 s31, s29, -1
	s_add_i32 s49, 0, 0x10000
	s_cmp_eq_u32 s48, 12
	s_cselect_b32 s35, s9, s31
	s_cselect_b32 s34, s8, s30
	v_add_u32_e32 v145, s49, v141
	s_cselect_b32 s31, s25, s23
	s_cselect_b32 s30, s24, s19
	s_add_i32 s52, 0, 0x14000
	ds_read_b128 v[146:149], v145
	ds_read_b128 v[150:153], v145 offset:1024
	ds_read_b128 v[154:157], v145 offset:2048
	ds_read_b128 v[158:161], v145 offset:3072
	v_add_u32_e32 v145, s52, v141
	ds_read_b128 v[162:165], v145
	ds_read_b128 v[166:169], v145 offset:1024
	ds_read_b128 v[170:173], v145 offset:2048
	ds_read_b128 v[174:177], v145 offset:3072
	v_lshl_add_u64 v[186:187], s[28:29], 0, v[136:137]
	s_add_i32 m0, s17, 0xc000
	ds_read_b128 v[178:181], v143
	ds_read_b128 v[182:185], v143 offset:1024
	ds_read_b128 v[192:195], v143 offset:2048
	ds_read_b128 v[196:199], v143 offset:3072
	ds_read_b128 v[200:203], v143 offset:4096
	ds_read_b128 v[204:207], v143 offset:5120
	ds_read_b128 v[208:211], v143 offset:6144
	ds_read_b128 v[212:215], v143 offset:7168
	global_load_lds_dwordx4 v[186:187], off
	v_lshl_add_u64 v[186:187], s[28:29], 0, v[138:139]
	s_add_i32 m0, s17, 0xe000
	s_nop 0
	global_load_lds_dwordx4 v[186:187], off
	s_waitcnt vmcnt(8)
	s_waitcnt lgkmcnt(0)
	s_barrier
	s_setprio 1
	s_waitcnt lgkmcnt(0)
	v_mfma_f32_16x16x32_bf16 v[124:127], v[146:149], v[178:181], 0
	v_mfma_f32_16x16x32_bf16 v[120:123], v[154:157], v[178:181], 0
	v_mfma_f32_16x16x32_bf16 v[116:119], v[146:149], v[192:195], 0
	v_mfma_f32_16x16x32_bf16 v[112:115], v[154:157], v[192:195], 0
	v_mfma_f32_16x16x32_bf16 v[100:103], v[146:149], v[200:203], 0
	v_mfma_f32_16x16x32_bf16 v[96:99], v[154:157], v[200:203], 0
	v_mfma_f32_16x16x32_bf16 v[84:87], v[146:149], v[208:211], 0
	v_mfma_f32_16x16x32_bf16 v[80:83], v[154:157], v[208:211], 0
	v_mfma_f32_16x16x32_bf16 v[124:127], v[150:153], v[182:185], v[124:127]
	v_mfma_f32_16x16x32_bf16 v[120:123], v[158:161], v[182:185], v[120:123]
	v_mfma_f32_16x16x32_bf16 v[116:119], v[150:153], v[196:199], v[116:119]
	v_mfma_f32_16x16x32_bf16 v[112:115], v[158:161], v[196:199], v[112:115]
	v_mfma_f32_16x16x32_bf16 v[100:103], v[150:153], v[204:207], v[100:103]
	v_mfma_f32_16x16x32_bf16 v[96:99], v[158:161], v[204:207], v[96:99]
	v_mfma_f32_16x16x32_bf16 v[84:87], v[150:153], v[212:215], v[84:87]
	v_mfma_f32_16x16x32_bf16 v[80:83], v[158:161], v[212:215], v[80:83]
	s_setprio 0
	s_setprio 1
	v_mfma_f32_16x16x32_bf16 v[108:111], v[162:165], v[178:181], 0
	v_mfma_f32_16x16x32_bf16 v[104:107], v[170:173], v[178:181], 0
	v_mfma_f32_16x16x32_bf16 v[92:95], v[162:165], v[192:195], 0
	v_mfma_f32_16x16x32_bf16 v[88:91], v[170:173], v[192:195], 0
	v_mfma_f32_16x16x32_bf16 v[76:79], v[162:165], v[200:203], 0
	v_mfma_f32_16x16x32_bf16 v[72:75], v[170:173], v[200:203], 0
	v_mfma_f32_16x16x32_bf16 v[68:71], v[162:165], v[208:211], 0
	v_mfma_f32_16x16x32_bf16 v[64:67], v[170:173], v[208:211], 0
	v_mfma_f32_16x16x32_bf16 v[108:111], v[166:169], v[182:185], v[108:111]
	v_mfma_f32_16x16x32_bf16 v[104:107], v[174:177], v[182:185], v[104:107]
	v_mfma_f32_16x16x32_bf16 v[92:95], v[166:169], v[196:199], v[92:95]
	v_mfma_f32_16x16x32_bf16 v[88:91], v[174:177], v[196:199], v[88:91]
	v_mfma_f32_16x16x32_bf16 v[76:79], v[166:169], v[204:207], v[76:79]
	v_mfma_f32_16x16x32_bf16 v[72:75], v[174:177], v[204:207], v[72:75]
	v_mfma_f32_16x16x32_bf16 v[68:71], v[166:169], v[212:215], v[68:71]
	v_mfma_f32_16x16x32_bf16 v[64:67], v[174:177], v[212:215], v[64:67]
	s_setprio 0
	s_barrier
	s_add_i32 s49, s49, s40
	v_lshl_add_u64 v[186:187], s[30:31], 0, v[132:133]
	s_mov_b32 m0, s49
	ds_read_b128 v[178:181], v143 offset:16384
	ds_read_b128 v[182:185], v143 offset:17408
	ds_read_b128 v[192:195], v143 offset:18432
	ds_read_b128 v[196:199], v143 offset:19456
	ds_read_b128 v[200:203], v143 offset:20480
	ds_read_b128 v[204:207], v143 offset:21504
	ds_read_b128 v[208:211], v143 offset:22528
	ds_read_b128 v[212:215], v143 offset:23552
	global_load_lds_dwordx4 v[186:187], off
	s_add_i32 m0, s49, 0x2000
	s_add_u32 s50, s30, 0x40000
	v_lshl_add_u64 v[216:217], s[30:31], 0, v[128:129]
	s_addc_u32 s51, s31, 0
	s_add_i32 s49, s52, s40
	global_load_lds_dwordx4 v[216:217], off
	v_lshl_add_u64 v[218:219], s[50:51], 0, v[132:133]
	s_mov_b32 m0, s49
	v_lshl_add_u64 v[220:221], s[34:35], 0, v[130:131]
	global_load_lds_dwordx4 v[218:219], off
	v_lshl_add_u64 v[218:219], s[50:51], 0, v[128:129]
	s_add_i32 m0, s49, 0x2000
	s_nop 0
	global_load_lds_dwordx4 v[218:219], off
	v_lshl_add_u64 v[218:219], s[34:35], 0, v[134:135]
	s_mov_b32 m0, s17
	s_nop 0
	global_load_lds_dwordx4 v[218:219], off
	s_mov_b32 m0, s21
	s_nop 0
	global_load_lds_dwordx4 v[220:221], off
	s_waitcnt vmcnt(8)
	s_waitcnt lgkmcnt(0)
	s_barrier
; #define PG8_STAGE(bufoff, gbase, voff) do { _Pragma("unroll") for (int _i = 0; _i < 2; ++_i) \
;         __builtin_amdgcn_global_load_lds((const unsigned*)((const char*)(gbase) + (voff)[_i]), (LAS unsigned*)(lds + (bufoff) + ldsw + _i * 8192), 16, 0, 0); } while (0)
; #define PG8_LDA(dst, b, h) do { _Pragma("unroll") for (int m = 0; m < 4; ++m) _Pragma("unroll") for (int k = 0; k < 2; ++k) dst[m][k] = *(const LAS bf16x8*)(lds + PG8_SA(b, h) + aoff + m * 2048 + k * 1024); } while (0)
; #define PG8_LDB(dst, b, h) do { _Pragma("unroll") for (int n = 0; n < 2; ++n) _Pragma("unroll") for (int k = 0; k < 2; ++k) dst[n][k] = *(const LAS bf16x8*)(lds + PG8_SB(b, h) + boff + n * 2048 + k * 1024); } while (0)
; #define PG8_MMA(ai, bj, At, Bt) do { __builtin_amdgcn_s_setprio(1); _Pragma("unroll") for (int m = 0; m < 4; ++m) _Pragma("unroll") for (int n = 0; n < 2; ++n) _Pragma("unroll") for (int k = 0; k < 2; ++k) \
;         acc[ai][bj][m][n] = __builtin_amdgcn_mfma_f32_16x16x32_bf16(Bt[n][k], At[m][k], acc[ai][bj][m][n], 0, 0, 0); __builtin_amdgcn_s_setprio(0); } while (0)
; #define PG8_WAIT_V(n) asm volatile("s_waitcnt vmcnt(" #n ")" ::: "memory")
; #define PG8_WAIT_L(n) asm volatile("s_waitcnt lgkmcnt(" #n ")" ::: "memory")
; #define PG8_BAR __builtin_amdgcn_s_barrier()
; #define PG8_SCHED __builtin_amdgcn_sched_barrier(0)
; template <class Epi, bool ALIGN_EPI = true>
; DI void gemm_phase(int tb_, LAS unsigned char* lds, const Gemm g, const Sched& S, const Epi& E) {
;     ...
;             PG8_WAIT_V(8); PG8_WAIT_L(0); PG8_BAR; PG8_MMA(1, 0, At, B0); PG8_MMA(1, 1, At, B1); PG8_BAR; PG8_SCHED;
;             PG8_LDB(B0, 1, 0); PG8_LDB(B1, 1, 1); PG8_SCHED; PG8_LDA(At, 1, 0); PG8_STAGE(PG8_SA(0, 1), a2 + hstep, voffA);
;             PG8_WAIT_V(8); PG8_WAIT_L(0); PG8_BAR; PG8_MMA(0, 0, At, B0); PG8_MMA(0, 1, At, B1); PG8_BAR; PG8_SCHED;
	s_setprio 1
	s_waitcnt lgkmcnt(0)
	v_mfma_f32_16x16x32_bf16 v[60:63], v[146:149], v[178:181], 0
	v_mfma_f32_16x16x32_bf16 v[56:59], v[154:157], v[178:181], 0
	v_mfma_f32_16x16x32_bf16 v[52:55], v[146:149], v[192:195], 0
	v_mfma_f32_16x16x32_bf16 v[48:51], v[154:157], v[192:195], 0
	v_mfma_f32_16x16x32_bf16 v[36:39], v[146:149], v[200:203], 0
	v_mfma_f32_16x16x32_bf16 v[32:35], v[154:157], v[200:203], 0
	v_mfma_f32_16x16x32_bf16 v[20:23], v[146:149], v[208:211], 0
	v_mfma_f32_16x16x32_bf16 v[16:19], v[154:157], v[208:211], 0
	v_mfma_f32_16x16x32_bf16 v[60:63], v[150:153], v[182:185], v[60:63]
	v_mfma_f32_16x16x32_bf16 v[56:59], v[158:161], v[182:185], v[56:59]
	v_mfma_f32_16x16x32_bf16 v[52:55], v[150:153], v[196:199], v[52:55]
	v_mfma_f32_16x16x32_bf16 v[48:51], v[158:161], v[196:199], v[48:51]
	v_mfma_f32_16x16x32_bf16 v[36:39], v[150:153], v[204:207], v[36:39]
	v_mfma_f32_16x16x32_bf16 v[32:35], v[158:161], v[204:207], v[32:35]
	v_mfma_f32_16x16x32_bf16 v[20:23], v[150:153], v[212:215], v[20:23]
	v_mfma_f32_16x16x32_bf16 v[16:19], v[158:161], v[212:215], v[16:19]
	s_setprio 0
	s_setprio 1
	v_mfma_f32_16x16x32_bf16 v[44:47], v[162:165], v[178:181], 0
	v_mfma_f32_16x16x32_bf16 v[40:43], v[170:173], v[178:181], 0
	v_mfma_f32_16x16x32_bf16 v[28:31], v[162:165], v[192:195], 0
	v_mfma_f32_16x16x32_bf16 v[24:27], v[170:173], v[192:195], 0
	v_mfma_f32_16x16x32_bf16 v[12:15], v[162:165], v[200:203], 0
	v_mfma_f32_16x16x32_bf16 v[8:11], v[170:173], v[200:203], 0
	v_mfma_f32_16x16x32_bf16 v[4:7], v[162:165], v[208:211], 0
	v_mfma_f32_16x16x32_bf16 v[0:3], v[170:173], v[208:211], 0
	v_mfma_f32_16x16x32_bf16 v[44:47], v[166:169], v[182:185], v[44:47]
	v_mfma_f32_16x16x32_bf16 v[40:43], v[174:177], v[182:185], v[40:43]
	v_mfma_f32_16x16x32_bf16 v[28:31], v[166:169], v[196:199], v[28:31]
	v_mfma_f32_16x16x32_bf16 v[24:27], v[174:177], v[196:199], v[24:27]
	v_mfma_f32_16x16x32_bf16 v[12:15], v[166:169], v[204:207], v[12:15]
	v_mfma_f32_16x16x32_bf16 v[8:11], v[174:177], v[204:207], v[8:11]
	v_mfma_f32_16x16x32_bf16 v[4:7], v[166:169], v[212:215], v[4:7]
	v_mfma_f32_16x16x32_bf16 v[0:3], v[174:177], v[212:215], v[0:3]
	s_setprio 0
	s_barrier
	s_add_i32 s49, 0, 0x18000
	v_add_u32_e32 v145, s49, v141
	s_add_i32 s50, 0, 0x1c000
	ds_read_b128 v[146:149], v145
	ds_read_b128 v[150:153], v145 offset:1024
	ds_read_b128 v[154:157], v145 offset:2048
	ds_read_b128 v[158:161], v145 offset:3072
	v_add_u32_e32 v145, s50, v141
	ds_read_b128 v[162:165], v145
	ds_read_b128 v[166:169], v145 offset:1024
	ds_read_b128 v[170:173], v145 offset:2048
	ds_read_b128 v[174:177], v145 offset:3072
	s_add_u32 s34, s34, 0x40000
	s_addc_u32 s35, s35, 0
	s_mov_b32 m0, s41
	v_lshl_add_u64 v[222:223], s[34:35], 0, v[134:135]
	ds_read_b128 v[178:181], v143 offset:32768
	ds_read_b128 v[182:185], v143 offset:33792
	ds_read_b128 v[192:195], v143 offset:34816
	ds_read_b128 v[196:199], v143 offset:35840
	ds_read_b128 v[200:203], v143 offset:36864
	ds_read_b128 v[204:207], v143 offset:37888
	ds_read_b128 v[208:211], v143 offset:38912
	ds_read_b128 v[212:215], v143 offset:39936
	global_load_lds_dwordx4 v[222:223], off
	v_lshl_add_u64 v[222:223], s[34:35], 0, v[130:131]
	s_mov_b32 m0, s42
	s_nop 0
	global_load_lds_dwordx4 v[222:223], off
	s_waitcnt vmcnt(8)
	s_waitcnt lgkmcnt(0)
	s_barrier
	s_setprio 1
	s_waitcnt lgkmcnt(0)
	v_mfma_f32_16x16x32_bf16 v[124:127], v[146:149], v[178:181], v[124:127]
	v_mfma_f32_16x16x32_bf16 v[120:123], v[154:157], v[178:181], v[120:123]
	v_mfma_f32_16x16x32_bf16 v[116:119], v[146:149], v[192:195], v[116:119]
	v_mfma_f32_16x16x32_bf16 v[112:115], v[154:157], v[192:195], v[112:115]
	v_mfma_f32_16x16x32_bf16 v[100:103], v[146:149], v[200:203], v[100:103]
	v_mfma_f32_16x16x32_bf16 v[96:99], v[154:157], v[200:203], v[96:99]
	v_mfma_f32_16x16x32_bf16 v[84:87], v[146:149], v[208:211], v[84:87]
	v_mfma_f32_16x16x32_bf16 v[80:83], v[154:157], v[208:211], v[80:83]
	v_mfma_f32_16x16x32_bf16 v[124:127], v[150:153], v[182:185], v[124:127]
	v_mfma_f32_16x16x32_bf16 v[120:123], v[158:161], v[182:185], v[120:123]
	v_mfma_f32_16x16x32_bf16 v[116:119], v[150:153], v[196:199], v[116:119]
	v_mfma_f32_16x16x32_bf16 v[112:115], v[158:161], v[196:199], v[112:115]
	v_mfma_f32_16x16x32_bf16 v[100:103], v[150:153], v[204:207], v[100:103]
	v_mfma_f32_16x16x32_bf16 v[96:99], v[158:161], v[204:207], v[96:99]
	v_mfma_f32_16x16x32_bf16 v[84:87], v[150:153], v[212:215], v[84:87]
	v_mfma_f32_16x16x32_bf16 v[80:83], v[158:161], v[212:215], v[80:83]
	s_setprio 0
	s_setprio 1
	v_mfma_f32_16x16x32_bf16 v[108:111], v[162:165], v[178:181], v[108:111]
	v_mfma_f32_16x16x32_bf16 v[104:107], v[170:173], v[178:181], v[104:107]
	v_mfma_f32_16x16x32_bf16 v[92:95], v[162:165], v[192:195], v[92:95]
	v_mfma_f32_16x16x32_bf16 v[88:91], v[170:173], v[192:195], v[88:91]
	v_mfma_f32_16x16x32_bf16 v[76:79], v[162:165], v[200:203], v[76:79]
	v_mfma_f32_16x16x32_bf16 v[72:75], v[170:173], v[200:203], v[72:75]
	v_mfma_f32_16x16x32_bf16 v[68:71], v[162:165], v[208:211], v[68:71]
	v_mfma_f32_16x16x32_bf16 v[64:67], v[170:173], v[208:211], v[64:67]
	v_mfma_f32_16x16x32_bf16 v[108:111], v[166:169], v[182:185], v[108:111]
	v_mfma_f32_16x16x32_bf16 v[104:107], v[174:177], v[182:185], v[104:107]
	v_mfma_f32_16x16x32_bf16 v[92:95], v[166:169], v[196:199], v[92:95]
	v_mfma_f32_16x16x32_bf16 v[88:91], v[174:177], v[196:199], v[88:91]
	v_mfma_f32_16x16x32_bf16 v[76:79], v[166:169], v[204:207], v[76:79]
	v_mfma_f32_16x16x32_bf16 v[72:75], v[174:177], v[204:207], v[72:75]
	v_mfma_f32_16x16x32_bf16 v[68:71], v[166:169], v[212:215], v[68:71]
	v_mfma_f32_16x16x32_bf16 v[64:67], v[174:177], v[212:215], v[64:67]
	s_setprio 0
	s_barrier
; #define PG8_STAGE(bufoff, gbase, voff) do { _Pragma("unroll") for (int _i = 0; _i < 2; ++_i) \
;         __builtin_amdgcn_global_load_lds((const unsigned*)((const char*)(gbase) + (voff)[_i]), (LAS unsigned*)(lds + (bufoff) + ldsw + _i * 8192), 16, 0, 0); } while (0)
; #define PG8_LDA(dst, b, h) do { _Pragma("unroll") for (int m = 0; m < 4; ++m) _Pragma("unroll") for (int k = 0; k < 2; ++k) dst[m][k] = *(const LAS bf16x8*)(lds + PG8_SA(b, h) + aoff + m * 2048 + k * 1024); } while (0)
; #define PG8_MMA(ai, bj, At, Bt) do { __builtin_amdgcn_s_setprio(1); _Pragma("unroll") for (int m = 0; m < 4; ++m) _Pragma("unroll") for (int n = 0; n < 2; ++n) _Pragma("unroll") for (int k = 0; k < 2; ++k) \
;         acc[ai][bj][m][n] = __builtin_amdgcn_mfma_f32_16x16x32_bf16(Bt[n][k], At[m][k], acc[ai][bj][m][n], 0, 0, 0); __builtin_amdgcn_s_setprio(0); } while (0)
; #define PG8_WAIT_V(n) asm volatile("s_waitcnt vmcnt(" #n ")" ::: "memory")
; #define PG8_WAIT_L(n) asm volatile("s_waitcnt lgkmcnt(" #n ")" ::: "memory")
; #define PG8_BAR __builtin_amdgcn_s_barrier()
; #define PG8_SCHED __builtin_amdgcn_sched_barrier(0)
; template <class Epi, bool ALIGN_EPI = true>
; DI void gemm_phase(int tb_, LAS unsigned char* lds, const Gemm g, const Sched& S, const Epi& E) {
;     ...
;             PG8_LDA(At, 1, 1); PG8_STAGE(PG8_SB(1, 0), b3, voffB); PG8_STAGE(PG8_SB(1, 1), b3 + hstep, voffB); PG8_STAGE(PG8_SA(1, 0), a3, voffA);
;             PG8_WAIT_V(8); PG8_WAIT_L(0); PG8_BAR; PG8_MMA(1, 0, At, B0); PG8_MMA(1, 1, At, B1); PG8_BAR; PG8_SCHED;
;         }
	s_add_i32 s34, s49, s40
	v_lshl_add_u64 v[186:187], v[186:187], 0, s[72:73]
	s_mov_b32 m0, s34
	ds_read_b128 v[178:181], v143 offset:49152
	ds_read_b128 v[182:185], v143 offset:50176
	ds_read_b128 v[192:195], v143 offset:51200
	ds_read_b128 v[196:199], v143 offset:52224
	ds_read_b128 v[200:203], v143 offset:53248
	ds_read_b128 v[204:207], v143 offset:54272
	ds_read_b128 v[208:211], v143 offset:55296
	ds_read_b128 v[212:215], v143 offset:56320
	global_load_lds_dwordx4 v[186:187], off
	s_add_i32 m0, s34, 0x2000
	s_add_u32 s30, s30, 0x40080
	v_lshl_add_u64 v[186:187], v[216:217], 0, s[72:73]
	s_addc_u32 s31, s31, 0
	s_add_i32 s34, s50, s40
	global_load_lds_dwordx4 v[186:187], off
	v_lshl_add_u64 v[186:187], s[30:31], 0, v[132:133]
	s_mov_b32 m0, s34
	s_nop 0
	global_load_lds_dwordx4 v[186:187], off
	v_lshl_add_u64 v[186:187], s[30:31], 0, v[128:129]
	s_add_i32 m0, s34, 0x2000
	s_nop 0
	global_load_lds_dwordx4 v[186:187], off
	v_lshl_add_u64 v[186:187], v[218:219], 0, s[72:73]
	s_mov_b32 m0, s43
	s_nop 0
	global_load_lds_dwordx4 v[186:187], off
	v_lshl_add_u64 v[186:187], v[220:221], 0, s[72:73]
	s_mov_b32 m0, s44
	s_nop 0
	global_load_lds_dwordx4 v[186:187], off
	s_waitcnt vmcnt(8)
	s_waitcnt lgkmcnt(0)
	s_barrier
	s_setprio 1
	s_waitcnt lgkmcnt(0)
	v_mfma_f32_16x16x32_bf16 v[60:63], v[146:149], v[178:181], v[60:63]
	v_mfma_f32_16x16x32_bf16 v[56:59], v[154:157], v[178:181], v[56:59]
	v_mfma_f32_16x16x32_bf16 v[52:55], v[146:149], v[192:195], v[52:55]
	v_mfma_f32_16x16x32_bf16 v[48:51], v[154:157], v[192:195], v[48:51]
	v_mfma_f32_16x16x32_bf16 v[36:39], v[146:149], v[200:203], v[36:39]
	v_mfma_f32_16x16x32_bf16 v[32:35], v[154:157], v[200:203], v[32:35]
	v_mfma_f32_16x16x32_bf16 v[20:23], v[146:149], v[208:211], v[20:23]
	v_mfma_f32_16x16x32_bf16 v[16:19], v[154:157], v[208:211], v[16:19]
	v_mfma_f32_16x16x32_bf16 v[60:63], v[150:153], v[182:185], v[60:63]
	v_mfma_f32_16x16x32_bf16 v[56:59], v[158:161], v[182:185], v[56:59]
	v_mfma_f32_16x16x32_bf16 v[52:55], v[150:153], v[196:199], v[52:55]
	v_mfma_f32_16x16x32_bf16 v[48:51], v[158:161], v[196:199], v[48:51]
	v_mfma_f32_16x16x32_bf16 v[36:39], v[150:153], v[204:207], v[36:39]
	v_mfma_f32_16x16x32_bf16 v[32:35], v[158:161], v[204:207], v[32:35]
	v_mfma_f32_16x16x32_bf16 v[20:23], v[150:153], v[212:215], v[20:23]
	v_mfma_f32_16x16x32_bf16 v[16:19], v[158:161], v[212:215], v[16:19]
	s_setprio 0
	s_setprio 1
	v_mfma_f32_16x16x32_bf16 v[44:47], v[162:165], v[178:181], v[44:47]
	v_mfma_f32_16x16x32_bf16 v[40:43], v[170:173], v[178:181], v[40:43]
	v_mfma_f32_16x16x32_bf16 v[28:31], v[162:165], v[192:195], v[28:31]
	v_mfma_f32_16x16x32_bf16 v[24:27], v[170:173], v[192:195], v[24:27]
	v_mfma_f32_16x16x32_bf16 v[12:15], v[162:165], v[200:203], v[12:15]
	v_mfma_f32_16x16x32_bf16 v[8:11], v[170:173], v[200:203], v[8:11]
	v_mfma_f32_16x16x32_bf16 v[4:7], v[162:165], v[208:211], v[4:7]
	v_mfma_f32_16x16x32_bf16 v[0:3], v[170:173], v[208:211], v[0:3]
	v_mfma_f32_16x16x32_bf16 v[44:47], v[166:169], v[182:185], v[44:47]
	v_mfma_f32_16x16x32_bf16 v[40:43], v[174:177], v[182:185], v[40:43]
	v_mfma_f32_16x16x32_bf16 v[28:31], v[166:169], v[196:199], v[28:31]
	v_mfma_f32_16x16x32_bf16 v[24:27], v[174:177], v[196:199], v[24:27]
	v_mfma_f32_16x16x32_bf16 v[12:15], v[166:169], v[204:207], v[12:15]
	v_mfma_f32_16x16x32_bf16 v[8:11], v[174:177], v[204:207], v[8:11]
	v_mfma_f32_16x16x32_bf16 v[4:7], v[166:169], v[212:215], v[4:7]
	v_mfma_f32_16x16x32_bf16 v[0:3], v[174:177], v[212:215], v[0:3]
	s_setprio 0
	s_barrier
	s_add_i32 s48, s48, 2
	s_add_u32 s28, s28, 0x100
	s_addc_u32 s29, s29, 0
	s_add_u32 s19, s19, 0x100
	s_addc_u32 s23, s23, 0
	s_cmp_gt_u32 s48, 13
	s_cbranch_scc1 .Lpeel_exit_2

; #define PG8_BAR __builtin_amdgcn_s_barrier()
; template <class Epi, bool ALIGN_EPI = true>
; DI void gemm_phase(int tb_, LAS unsigned char* lds, const Gemm g, const Sched& S, const Epi& E) {
;     ...
;         if constexpr (ALIGN_EPI) { if (wr == 0) PG8_BAR; }
.Lpeel_exit_2:
	s_and_b64 vcc, exec, s[14:15]
	s_cbranch_vccz .LBB0_816
	s_barrier

; #define PG8_STAGE(bufoff, gbase, voff) do { _Pragma("unroll") for (int _i = 0; _i < 2; ++_i) \
;         __builtin_amdgcn_global_load_lds((const unsigned*)((const char*)(gbase) + (voff)[_i]), (LAS unsigned*)(lds + (bufoff) + ldsw + _i * 8192), 16, 0, 0); } while (0)
; #define PG8_LDA(dst, b, h) do { _Pragma("unroll") for (int m = 0; m < 4; ++m) _Pragma("unroll") for (int k = 0; k < 2; ++k) dst[m][k] = *(const LAS bf16x8*)(lds + PG8_SA(b, h) + aoff + m * 2048 + k * 1024); } while (0)
; #define PG8_LDB(dst, b, h) do { _Pragma("unroll") for (int n = 0; n < 2; ++n) _Pragma("unroll") for (int k = 0; k < 2; ++k) dst[n][k] = *(const LAS bf16x8*)(lds + PG8_SB(b, h) + boff + n * 2048 + k * 1024); } while (0)
; #define PG8_WAIT_V(n) asm volatile("s_waitcnt vmcnt(" #n ")" ::: "memory")
; #define PG8_WAIT_L(n) asm volatile("s_waitcnt lgkmcnt(" #n ")" ::: "memory")
; #define PG8_BAR __builtin_amdgcn_s_barrier()
; #define PG8_SCHED __builtin_amdgcn_sched_barrier(0)
; template <class Epi, bool ALIGN_EPI = true>
; DI void gemm_phase(int tb_, LAS unsigned char* lds, const Gemm g, const Sched& S, const Epi& E) {
;     ...
;         const bool has_next = S.next(ui + 1, nxt);
;         const char* nA = has_next ? PG8_APTR(nxt) : cA; const char* nB = has_next ? PG8_BPTR(nxt) : cB;
;         const int nt = cur.nt;
;         for (int t = 0; t < nt; t += 2) {
;             const bool last = (t == nt - 2);
;             const char* a1 = cA + (size_t)(t + 1) * kstep;
;             const char* a2 = last ? nA : cA + (size_t)(t + 2) * kstep; const char* b2 = last ? nB : cB + (size_t)(t + 2) * kstep;
;             const char* a3 = a2 + kstep; const char* b3 = b2 + kstep;
;             PG8_LDB(B0, 0, 0); PG8_LDB(B1, 0, 1); PG8_SCHED; PG8_LDA(At, 0, 0); PG8_STAGE(PG8_SA(1, 1), a1 + hstep, voffA);
;             PG8_WAIT_V(8); PG8_WAIT_L(0); PG8_BAR; PG8_MMA(0, 0, At, B0); PG8_MMA(0, 1, At, B1); PG8_BAR; PG8_SCHED;
;             PG8_LDA(At, 0, 1); PG8_STAGE(PG8_SB(0, 0), b2, voffB); PG8_STAGE(PG8_SB(0, 1), b2 + hstep, voffB); PG8_STAGE(PG8_SA(0, 0), a2, voffA);
;     ...
;         for (int a = 0; a < 2; ++a)
; #pragma unroll
;             for (int b = 0; b < 2; ++b)
; #pragma unroll
;                 for (int m = 0; m < 4; ++m)
; #pragma unroll
;                     for (int n = 0; n < 2; ++n) acc[a][b][m][n] = (f32x4){0.f, 0.f, 0.f, 0.f};
.LBB0_892:
	s_mov_b32 s25, 0
	s_mov_b64 s[34:35], -1
	s_mov_b64 s[36:37], 0
	s_add_u32 s29, s20, s25
	s_addc_u32 s44, s21, 0
	s_add_u32 s40, s29, 0x100
	s_addc_u32 s41, s44, 0
	s_and_b64 s[38:39], s[36:37], exec
	s_cselect_b32 s41, s9, s41
	s_cselect_b32 s40, s8, s40
	s_add_u32 s25, s22, s25
	s_addc_u32 s38, s23, 0
	s_add_u32 s25, s25, 0x100
	s_addc_u32 s38, s38, 0
	s_add_i32 s82, 0, 0x10000
	s_and_b64 s[36:37], s[36:37], exec
	s_cselect_b32 s43, s31, s38
	s_cselect_b32 s42, s30, s25
	s_add_i32 s37, 0, 0x14000
	s_add_u32 s46, s29, 0x10080
	s_addc_u32 s47, s44, 0
	s_add_i32 s80, s82, s54
	s_add_i32 m0, s15, 0xc000
	s_add_i32 s85, s15, 0xe000
	s_add_i32 s71, s80, 0x2000
	v_add_u32_e32 v141, s82, v137
	s_add_u32 s44, s42, 0x10000
	ds_read_b128 v[142:145], v141
	ds_read_b128 v[146:149], v141 offset:1024
	ds_read_b128 v[150:153], v141 offset:2048
	ds_read_b128 v[154:157], v141 offset:3072
	v_add_u32_e32 v141, s37, v137
	s_addc_u32 s45, s43, 0
	s_add_i32 s75, s37, s54
	ds_read_b128 v[158:161], v141
	ds_read_b128 v[162:165], v141 offset:1024
	ds_read_b128 v[166:169], v141 offset:2048
	ds_read_b128 v[170:173], v141 offset:3072
	s_add_i32 s74, s75, 0x2000
	s_add_i32 s70, 0, 0x18000
	s_add_i32 s69, 0, 0x1c000
	s_add_u32 s38, s40, 0x10000
	s_addc_u32 s39, s41, 0
	s_add_i32 s29, s70, s54
	s_add_i32 s25, s29, 0x2000
	s_add_u32 s36, s42, 0x10080
	s_addc_u32 s37, s43, 0
	s_add_i32 s83, s69, s54
	s_add_i32 s82, s83, 0x2000
	v_lshl_add_u64 v[186:187], s[46:47], 0, v[134:135]
	ds_read_b128 v[174:177], v139
	ds_read_b128 v[178:181], v139 offset:1024
	ds_read_b128 v[182:185], v139 offset:2048
	ds_read_b128 v[192:195], v139 offset:3072
	ds_read_b128 v[196:199], v139 offset:4096
	ds_read_b128 v[200:203], v139 offset:5120
	ds_read_b128 v[204:207], v139 offset:6144
	ds_read_b128 v[208:211], v139 offset:7168
	global_load_lds_dwordx4 v[186:187], off
	v_lshl_add_u64 v[186:187], s[46:47], 0, v[130:131]
	s_mov_b32 m0, s85
	s_nop 0
	global_load_lds_dwordx4 v[186:187], off
	s_waitcnt vmcnt(8)
	s_waitcnt lgkmcnt(0)
	s_barrier
	s_setprio 1
	s_waitcnt lgkmcnt(0)
	v_mfma_f32_16x16x32_bf16 v[124:127], v[142:145], v[174:177], 0
	v_mfma_f32_16x16x32_bf16 v[120:123], v[150:153], v[174:177], 0
	v_mfma_f32_16x16x32_bf16 v[116:119], v[142:145], v[182:185], 0
	v_mfma_f32_16x16x32_bf16 v[112:115], v[150:153], v[182:185], 0
	v_mfma_f32_16x16x32_bf16 v[100:103], v[142:145], v[196:199], 0
	v_mfma_f32_16x16x32_bf16 v[96:99], v[150:153], v[196:199], 0
	v_mfma_f32_16x16x32_bf16 v[84:87], v[142:145], v[204:207], 0
	v_mfma_f32_16x16x32_bf16 v[80:83], v[150:153], v[204:207], 0
	v_mfma_f32_16x16x32_bf16 v[124:127], v[146:149], v[178:181], v[124:127]
	v_mfma_f32_16x16x32_bf16 v[120:123], v[154:157], v[178:181], v[120:123]
	v_mfma_f32_16x16x32_bf16 v[116:119], v[146:149], v[192:195], v[116:119]
	v_mfma_f32_16x16x32_bf16 v[112:115], v[154:157], v[192:195], v[112:115]
	v_mfma_f32_16x16x32_bf16 v[100:103], v[146:149], v[200:203], v[100:103]
	v_mfma_f32_16x16x32_bf16 v[96:99], v[154:157], v[200:203], v[96:99]
	v_mfma_f32_16x16x32_bf16 v[84:87], v[146:149], v[208:211], v[84:87]
	v_mfma_f32_16x16x32_bf16 v[80:83], v[154:157], v[208:211], v[80:83]
	s_setprio 0
	s_setprio 1
	v_mfma_f32_16x16x32_bf16 v[108:111], v[158:161], v[174:177], 0
	v_mfma_f32_16x16x32_bf16 v[104:107], v[166:169], v[174:177], 0
	v_mfma_f32_16x16x32_bf16 v[92:95], v[158:161], v[182:185], 0
	v_mfma_f32_16x16x32_bf16 v[88:91], v[166:169], v[182:185], 0
	v_mfma_f32_16x16x32_bf16 v[76:79], v[158:161], v[196:199], 0
	v_mfma_f32_16x16x32_bf16 v[72:75], v[166:169], v[196:199], 0
	v_mfma_f32_16x16x32_bf16 v[68:71], v[158:161], v[204:207], 0
	v_mfma_f32_16x16x32_bf16 v[64:67], v[166:169], v[204:207], 0
	v_mfma_f32_16x16x32_bf16 v[108:111], v[162:165], v[178:181], v[108:111]
	v_mfma_f32_16x16x32_bf16 v[104:107], v[170:173], v[178:181], v[104:107]
	v_mfma_f32_16x16x32_bf16 v[92:95], v[162:165], v[192:195], v[92:95]
	v_mfma_f32_16x16x32_bf16 v[88:91], v[170:173], v[192:195], v[88:91]
	v_mfma_f32_16x16x32_bf16 v[76:79], v[162:165], v[200:203], v[76:79]
	v_mfma_f32_16x16x32_bf16 v[72:75], v[170:173], v[200:203], v[72:75]
	v_mfma_f32_16x16x32_bf16 v[68:71], v[162:165], v[208:211], v[68:71]
	v_mfma_f32_16x16x32_bf16 v[64:67], v[170:173], v[208:211], v[64:67]
	s_setprio 0
	s_barrier
	s_mov_b32 m0, s80
	v_lshl_add_u64 v[186:187], s[42:43], 0, v[132:133]
	ds_read_b128 v[174:177], v139 offset:16384
	ds_read_b128 v[178:181], v139 offset:17408
	ds_read_b128 v[182:185], v139 offset:18432
	ds_read_b128 v[192:195], v139 offset:19456
	ds_read_b128 v[196:199], v139 offset:20480
	ds_read_b128 v[200:203], v139 offset:21504
	ds_read_b128 v[204:207], v139 offset:22528
	ds_read_b128 v[208:211], v139 offset:23552
	global_load_lds_dwordx4 v[186:187], off
	v_lshl_add_u64 v[212:213], s[42:43], 0, v[128:129]
	s_mov_b32 m0, s71
	v_lshl_add_u64 v[214:215], s[44:45], 0, v[132:133]
	global_load_lds_dwordx4 v[212:213], off
	s_mov_b32 m0, s75
	v_lshl_add_u64 v[216:217], s[40:41], 0, v[130:131]
	global_load_lds_dwordx4 v[214:215], off
	v_lshl_add_u64 v[214:215], s[44:45], 0, v[128:129]
	s_mov_b32 m0, s74
	s_nop 0
	global_load_lds_dwordx4 v[214:215], off
	v_lshl_add_u64 v[214:215], s[40:41], 0, v[134:135]
	s_mov_b32 m0, s15
	s_nop 0
	global_load_lds_dwordx4 v[214:215], off
	s_mov_b32 m0, s19
	s_nop 0
	global_load_lds_dwordx4 v[216:217], off
	s_waitcnt vmcnt(8)
	s_waitcnt lgkmcnt(0)
	s_barrier
; #define PG8_STAGE(bufoff, gbase, voff) do { _Pragma("unroll") for (int _i = 0; _i < 2; ++_i) \
;         __builtin_amdgcn_global_load_lds((const unsigned*)((const char*)(gbase) + (voff)[_i]), (LAS unsigned*)(lds + (bufoff) + ldsw + _i * 8192), 16, 0, 0); } while (0)
; #define PG8_LDA(dst, b, h) do { _Pragma("unroll") for (int m = 0; m < 4; ++m) _Pragma("unroll") for (int k = 0; k < 2; ++k) dst[m][k] = *(const LAS bf16x8*)(lds + PG8_SA(b, h) + aoff + m * 2048 + k * 1024); } while (0)
; #define PG8_LDB(dst, b, h) do { _Pragma("unroll") for (int n = 0; n < 2; ++n) _Pragma("unroll") for (int k = 0; k < 2; ++k) dst[n][k] = *(const LAS bf16x8*)(lds + PG8_SB(b, h) + boff + n * 2048 + k * 1024); } while (0)
; #define PG8_MMA(ai, bj, At, Bt) do { __builtin_amdgcn_s_setprio(1); _Pragma("unroll") for (int m = 0; m < 4; ++m) _Pragma("unroll") for (int n = 0; n < 2; ++n) _Pragma("unroll") for (int k = 0; k < 2; ++k) \
;         acc[ai][bj][m][n] = __builtin_amdgcn_mfma_f32_16x16x32_bf16(Bt[n][k], At[m][k], acc[ai][bj][m][n], 0, 0, 0); __builtin_amdgcn_s_setprio(0); } while (0)
; #define PG8_WAIT_V(n) asm volatile("s_waitcnt vmcnt(" #n ")" ::: "memory")
; #define PG8_WAIT_L(n) asm volatile("s_waitcnt lgkmcnt(" #n ")" ::: "memory")
; #define PG8_BAR __builtin_amdgcn_s_barrier()
; #define PG8_SCHED __builtin_amdgcn_sched_barrier(0)
; template <class Epi, bool ALIGN_EPI = true>
; DI void gemm_phase(int tb_, LAS unsigned char* lds, const Gemm g, const Sched& S, const Epi& E) {
;     ...
;             PG8_WAIT_V(8); PG8_WAIT_L(0); PG8_BAR; PG8_MMA(1, 0, At, B0); PG8_MMA(1, 1, At, B1); PG8_BAR; PG8_SCHED;
;             PG8_LDB(B0, 1, 0); PG8_LDB(B1, 1, 1); PG8_SCHED; PG8_LDA(At, 1, 0); PG8_STAGE(PG8_SA(0, 1), a2 + hstep, voffA);
;             PG8_WAIT_V(8); PG8_WAIT_L(0); PG8_BAR; PG8_MMA(0, 0, At, B0); PG8_MMA(0, 1, At, B1); PG8_BAR; PG8_SCHED;
	s_setprio 1
	s_waitcnt lgkmcnt(0)
	v_mfma_f32_16x16x32_bf16 v[60:63], v[142:145], v[174:177], 0
	v_mfma_f32_16x16x32_bf16 v[56:59], v[150:153], v[174:177], 0
	v_mfma_f32_16x16x32_bf16 v[52:55], v[142:145], v[182:185], 0
	v_mfma_f32_16x16x32_bf16 v[48:51], v[150:153], v[182:185], 0
	v_mfma_f32_16x16x32_bf16 v[36:39], v[142:145], v[196:199], 0
	v_mfma_f32_16x16x32_bf16 v[32:35], v[150:153], v[196:199], 0
	v_mfma_f32_16x16x32_bf16 v[20:23], v[142:145], v[204:207], 0
	v_mfma_f32_16x16x32_bf16 v[16:19], v[150:153], v[204:207], 0
	v_mfma_f32_16x16x32_bf16 v[60:63], v[146:149], v[178:181], v[60:63]
	v_mfma_f32_16x16x32_bf16 v[56:59], v[154:157], v[178:181], v[56:59]
	v_mfma_f32_16x16x32_bf16 v[52:55], v[146:149], v[192:195], v[52:55]
	v_mfma_f32_16x16x32_bf16 v[48:51], v[154:157], v[192:195], v[48:51]
	v_mfma_f32_16x16x32_bf16 v[36:39], v[146:149], v[200:203], v[36:39]
	v_mfma_f32_16x16x32_bf16 v[32:35], v[154:157], v[200:203], v[32:35]
	v_mfma_f32_16x16x32_bf16 v[20:23], v[146:149], v[208:211], v[20:23]
	v_mfma_f32_16x16x32_bf16 v[16:19], v[154:157], v[208:211], v[16:19]
	s_setprio 0
	s_setprio 1
	v_mfma_f32_16x16x32_bf16 v[44:47], v[158:161], v[174:177], 0
	v_mfma_f32_16x16x32_bf16 v[40:43], v[166:169], v[174:177], 0
	v_mfma_f32_16x16x32_bf16 v[28:31], v[158:161], v[182:185], 0
	v_mfma_f32_16x16x32_bf16 v[24:27], v[166:169], v[182:185], 0
	v_mfma_f32_16x16x32_bf16 v[12:15], v[158:161], v[196:199], 0
	v_mfma_f32_16x16x32_bf16 v[8:11], v[166:169], v[196:199], 0
	v_mfma_f32_16x16x32_bf16 v[4:7], v[158:161], v[204:207], 0
	v_mfma_f32_16x16x32_bf16 v[0:3], v[166:169], v[204:207], 0
	v_mfma_f32_16x16x32_bf16 v[44:47], v[162:165], v[178:181], v[44:47]
	v_mfma_f32_16x16x32_bf16 v[40:43], v[170:173], v[178:181], v[40:43]
	v_mfma_f32_16x16x32_bf16 v[28:31], v[162:165], v[192:195], v[28:31]
	v_mfma_f32_16x16x32_bf16 v[24:27], v[170:173], v[192:195], v[24:27]
	v_mfma_f32_16x16x32_bf16 v[12:15], v[162:165], v[200:203], v[12:15]
	v_mfma_f32_16x16x32_bf16 v[8:11], v[170:173], v[200:203], v[8:11]
	v_mfma_f32_16x16x32_bf16 v[4:7], v[162:165], v[208:211], v[4:7]
	v_mfma_f32_16x16x32_bf16 v[0:3], v[170:173], v[208:211], v[0:3]
	s_setprio 0
	s_barrier
	v_add_u32_e32 v141, s70, v137
	ds_read_b128 v[142:145], v141
	ds_read_b128 v[146:149], v141 offset:1024
	ds_read_b128 v[150:153], v141 offset:2048
	ds_read_b128 v[154:157], v141 offset:3072
	v_add_u32_e32 v141, s69, v137
	ds_read_b128 v[158:161], v141
	ds_read_b128 v[162:165], v141 offset:1024
	ds_read_b128 v[166:169], v141 offset:2048
	ds_read_b128 v[170:173], v141 offset:3072
	s_mov_b32 m0, s58
	v_lshl_add_u64 v[218:219], s[38:39], 0, v[134:135]
	ds_read_b128 v[174:177], v139 offset:32768
	ds_read_b128 v[178:181], v139 offset:33792
	ds_read_b128 v[182:185], v139 offset:34816
	ds_read_b128 v[192:195], v139 offset:35840
	ds_read_b128 v[196:199], v139 offset:36864
	ds_read_b128 v[200:203], v139 offset:37888
	ds_read_b128 v[204:207], v139 offset:38912
	ds_read_b128 v[208:211], v139 offset:39936
	global_load_lds_dwordx4 v[218:219], off
	v_lshl_add_u64 v[218:219], s[38:39], 0, v[130:131]
	s_mov_b32 m0, s60
	s_nop 0
	global_load_lds_dwordx4 v[218:219], off
	s_waitcnt vmcnt(8)
	s_waitcnt lgkmcnt(0)
	s_barrier
	s_setprio 1
	s_waitcnt lgkmcnt(0)
	v_mfma_f32_16x16x32_bf16 v[124:127], v[142:145], v[174:177], v[124:127]
	v_mfma_f32_16x16x32_bf16 v[120:123], v[150:153], v[174:177], v[120:123]
	v_mfma_f32_16x16x32_bf16 v[116:119], v[142:145], v[182:185], v[116:119]
	v_mfma_f32_16x16x32_bf16 v[112:115], v[150:153], v[182:185], v[112:115]
	v_mfma_f32_16x16x32_bf16 v[100:103], v[142:145], v[196:199], v[100:103]
	v_mfma_f32_16x16x32_bf16 v[96:99], v[150:153], v[196:199], v[96:99]
	v_mfma_f32_16x16x32_bf16 v[84:87], v[142:145], v[204:207], v[84:87]
	v_mfma_f32_16x16x32_bf16 v[80:83], v[150:153], v[204:207], v[80:83]
	v_mfma_f32_16x16x32_bf16 v[124:127], v[146:149], v[178:181], v[124:127]
	v_mfma_f32_16x16x32_bf16 v[120:123], v[154:157], v[178:181], v[120:123]
	v_mfma_f32_16x16x32_bf16 v[116:119], v[146:149], v[192:195], v[116:119]
	v_mfma_f32_16x16x32_bf16 v[112:115], v[154:157], v[192:195], v[112:115]
	v_mfma_f32_16x16x32_bf16 v[100:103], v[146:149], v[200:203], v[100:103]
	v_mfma_f32_16x16x32_bf16 v[96:99], v[154:157], v[200:203], v[96:99]
	v_mfma_f32_16x16x32_bf16 v[84:87], v[146:149], v[208:211], v[84:87]
	v_mfma_f32_16x16x32_bf16 v[80:83], v[154:157], v[208:211], v[80:83]
	s_setprio 0
	s_setprio 1
	v_mfma_f32_16x16x32_bf16 v[108:111], v[158:161], v[174:177], v[108:111]
	v_mfma_f32_16x16x32_bf16 v[104:107], v[166:169], v[174:177], v[104:107]
	v_mfma_f32_16x16x32_bf16 v[92:95], v[158:161], v[182:185], v[92:95]
	v_mfma_f32_16x16x32_bf16 v[88:91], v[166:169], v[182:185], v[88:91]
	v_mfma_f32_16x16x32_bf16 v[76:79], v[158:161], v[196:199], v[76:79]
	v_mfma_f32_16x16x32_bf16 v[72:75], v[166:169], v[196:199], v[72:75]
	v_mfma_f32_16x16x32_bf16 v[68:71], v[158:161], v[204:207], v[68:71]
	v_mfma_f32_16x16x32_bf16 v[64:67], v[166:169], v[204:207], v[64:67]
	v_mfma_f32_16x16x32_bf16 v[108:111], v[162:165], v[178:181], v[108:111]
	v_mfma_f32_16x16x32_bf16 v[104:107], v[170:173], v[178:181], v[104:107]
	v_mfma_f32_16x16x32_bf16 v[92:95], v[162:165], v[192:195], v[92:95]
	v_mfma_f32_16x16x32_bf16 v[88:91], v[170:173], v[192:195], v[88:91]
	v_mfma_f32_16x16x32_bf16 v[76:79], v[162:165], v[200:203], v[76:79]
	v_mfma_f32_16x16x32_bf16 v[72:75], v[170:173], v[200:203], v[72:75]
	v_mfma_f32_16x16x32_bf16 v[68:71], v[162:165], v[208:211], v[68:71]
	v_mfma_f32_16x16x32_bf16 v[64:67], v[170:173], v[208:211], v[64:67]
	s_setprio 0
	s_barrier
; #define PG8_STAGE(bufoff, gbase, voff) do { _Pragma("unroll") for (int _i = 0; _i < 2; ++_i) \
;         __builtin_amdgcn_global_load_lds((const unsigned*)((const char*)(gbase) + (voff)[_i]), (LAS unsigned*)(lds + (bufoff) + ldsw + _i * 8192), 16, 0, 0); } while (0)
; #define PG8_LDA(dst, b, h) do { _Pragma("unroll") for (int m = 0; m < 4; ++m) _Pragma("unroll") for (int k = 0; k < 2; ++k) dst[m][k] = *(const LAS bf16x8*)(lds + PG8_SA(b, h) + aoff + m * 2048 + k * 1024); } while (0)
; #define PG8_MMA(ai, bj, At, Bt) do { __builtin_amdgcn_s_setprio(1); _Pragma("unroll") for (int m = 0; m < 4; ++m) _Pragma("unroll") for (int n = 0; n < 2; ++n) _Pragma("unroll") for (int k = 0; k < 2; ++k) \
;         acc[ai][bj][m][n] = __builtin_amdgcn_mfma_f32_16x16x32_bf16(Bt[n][k], At[m][k], acc[ai][bj][m][n], 0, 0, 0); __builtin_amdgcn_s_setprio(0); } while (0)
; #define PG8_WAIT_V(n) asm volatile("s_waitcnt vmcnt(" #n ")" ::: "memory")
; #define PG8_WAIT_L(n) asm volatile("s_waitcnt lgkmcnt(" #n ")" ::: "memory")
; #define PG8_BAR __builtin_amdgcn_s_barrier()
; #define PG8_SCHED __builtin_amdgcn_sched_barrier(0)
; template <class Epi, bool ALIGN_EPI = true>
; DI void gemm_phase(int tb_, LAS unsigned char* lds, const Gemm g, const Sched& S, const Epi& E) {
;     ...
;             PG8_LDA(At, 1, 1); PG8_STAGE(PG8_SB(1, 0), b3, voffB); PG8_STAGE(PG8_SB(1, 1), b3 + hstep, voffB); PG8_STAGE(PG8_SA(1, 0), a3, voffA);
;             PG8_WAIT_V(8); PG8_WAIT_L(0); PG8_BAR; PG8_MMA(1, 0, At, B0); PG8_MMA(1, 1, At, B1); PG8_BAR; PG8_SCHED;
;         }
	s_mov_b32 m0, s29
	v_lshl_add_u64 v[186:187], v[186:187], 0, s[72:73]
	ds_read_b128 v[174:177], v139 offset:49152
	ds_read_b128 v[178:181], v139 offset:50176
	ds_read_b128 v[182:185], v139 offset:51200
	ds_read_b128 v[192:195], v139 offset:52224
	ds_read_b128 v[196:199], v139 offset:53248
	ds_read_b128 v[200:203], v139 offset:54272
	ds_read_b128 v[204:207], v139 offset:55296
	ds_read_b128 v[208:211], v139 offset:56320
	global_load_lds_dwordx4 v[186:187], off
	v_lshl_add_u64 v[186:187], v[212:213], 0, s[72:73]
	s_mov_b32 m0, s25
	s_nop 0
	global_load_lds_dwordx4 v[186:187], off
	v_lshl_add_u64 v[186:187], s[36:37], 0, v[132:133]
	s_mov_b32 m0, s83
	s_nop 0
	global_load_lds_dwordx4 v[186:187], off
	v_lshl_add_u64 v[186:187], s[36:37], 0, v[128:129]
	s_mov_b32 m0, s82
	s_nop 0
	global_load_lds_dwordx4 v[186:187], off
	v_lshl_add_u64 v[186:187], v[214:215], 0, s[72:73]
	s_mov_b32 m0, s61
	s_nop 0
	global_load_lds_dwordx4 v[186:187], off
	v_lshl_add_u64 v[186:187], v[216:217], 0, s[72:73]
	s_mov_b32 m0, s63
	s_nop 0
	global_load_lds_dwordx4 v[186:187], off
	s_waitcnt vmcnt(8)
	s_waitcnt lgkmcnt(0)
	s_barrier
	s_setprio 1
	s_waitcnt lgkmcnt(0)
	v_mfma_f32_16x16x32_bf16 v[60:63], v[142:145], v[174:177], v[60:63]
	v_mfma_f32_16x16x32_bf16 v[56:59], v[150:153], v[174:177], v[56:59]
	v_mfma_f32_16x16x32_bf16 v[52:55], v[142:145], v[182:185], v[52:55]
	v_mfma_f32_16x16x32_bf16 v[48:51], v[150:153], v[182:185], v[48:51]
	v_mfma_f32_16x16x32_bf16 v[36:39], v[142:145], v[196:199], v[36:39]
	v_mfma_f32_16x16x32_bf16 v[32:35], v[150:153], v[196:199], v[32:35]
	v_mfma_f32_16x16x32_bf16 v[20:23], v[142:145], v[204:207], v[20:23]
	v_mfma_f32_16x16x32_bf16 v[16:19], v[150:153], v[204:207], v[16:19]
	v_mfma_f32_16x16x32_bf16 v[60:63], v[146:149], v[178:181], v[60:63]
	v_mfma_f32_16x16x32_bf16 v[56:59], v[154:157], v[178:181], v[56:59]
	v_mfma_f32_16x16x32_bf16 v[52:55], v[146:149], v[192:195], v[52:55]
	v_mfma_f32_16x16x32_bf16 v[48:51], v[154:157], v[192:195], v[48:51]
	v_mfma_f32_16x16x32_bf16 v[36:39], v[146:149], v[200:203], v[36:39]
	v_mfma_f32_16x16x32_bf16 v[32:35], v[154:157], v[200:203], v[32:35]
	v_mfma_f32_16x16x32_bf16 v[20:23], v[146:149], v[208:211], v[20:23]
	v_mfma_f32_16x16x32_bf16 v[16:19], v[154:157], v[208:211], v[16:19]
	s_setprio 0
	s_setprio 1
	v_mfma_f32_16x16x32_bf16 v[44:47], v[158:161], v[174:177], v[44:47]
	v_mfma_f32_16x16x32_bf16 v[40:43], v[166:169], v[174:177], v[40:43]
	v_mfma_f32_16x16x32_bf16 v[28:31], v[158:161], v[182:185], v[28:31]
	v_mfma_f32_16x16x32_bf16 v[24:27], v[166:169], v[182:185], v[24:27]
	v_mfma_f32_16x16x32_bf16 v[12:15], v[158:161], v[196:199], v[12:15]
	v_mfma_f32_16x16x32_bf16 v[8:11], v[166:169], v[196:199], v[8:11]
	v_mfma_f32_16x16x32_bf16 v[4:7], v[158:161], v[204:207], v[4:7]
	v_mfma_f32_16x16x32_bf16 v[0:3], v[166:169], v[204:207], v[0:3]
	v_mfma_f32_16x16x32_bf16 v[44:47], v[162:165], v[178:181], v[44:47]
	v_mfma_f32_16x16x32_bf16 v[40:43], v[170:173], v[178:181], v[40:43]
	v_mfma_f32_16x16x32_bf16 v[28:31], v[162:165], v[192:195], v[28:31]
	v_mfma_f32_16x16x32_bf16 v[24:27], v[170:173], v[192:195], v[24:27]
	v_mfma_f32_16x16x32_bf16 v[12:15], v[162:165], v[200:203], v[12:15]
	v_mfma_f32_16x16x32_bf16 v[8:11], v[170:173], v[200:203], v[8:11]
	v_mfma_f32_16x16x32_bf16 v[4:7], v[162:165], v[208:211], v[4:7]
	v_mfma_f32_16x16x32_bf16 v[0:3], v[170:173], v[208:211], v[0:3]
	s_setprio 0
	s_barrier
	s_movk_i32 s25, 0x100
	s_andn2_b64 vcc, exec, s[34:35]
	s_mov_b64 s[36:37], -1
	s_mov_b64 s[34:35], 0
	s_cbranch_vccnz .Lpeel_exit_3

; #define PG8_BAR __builtin_amdgcn_s_barrier()
; template <class Epi, bool ALIGN_EPI = true>
; DI void gemm_phase(int tb_, LAS unsigned char* lds, const Gemm g, const Sched& S, const Epi& E) {
;     ...
;         if constexpr (ALIGN_EPI) { if (wr == 0) PG8_BAR; }
.Lpeel_exit_3:
	s_and_b64 vcc, exec, s[16:17]
	s_cbranch_vccz .LBB0_896
	s_barrier

; #define PG8_STAGE(bufoff, gbase, voff) do { _Pragma("unroll") for (int _i = 0; _i < 2; ++_i) \
;         __builtin_amdgcn_global_load_lds((const unsigned*)((const char*)(gbase) + (voff)[_i]), (LAS unsigned*)(lds + (bufoff) + ldsw + _i * 8192), 16, 0, 0); } while (0)
; #define PG8_LDA(dst, b, h) do { _Pragma("unroll") for (int m = 0; m < 4; ++m) _Pragma("unroll") for (int k = 0; k < 2; ++k) dst[m][k] = *(const LAS bf16x8*)(lds + PG8_SA(b, h) + aoff + m * 2048 + k * 1024); } while (0)
; #define PG8_LDB(dst, b, h) do { _Pragma("unroll") for (int n = 0; n < 2; ++n) _Pragma("unroll") for (int k = 0; k < 2; ++k) dst[n][k] = *(const LAS bf16x8*)(lds + PG8_SB(b, h) + boff + n * 2048 + k * 1024); } while (0)
; #define PG8_WAIT_V(n) asm volatile("s_waitcnt vmcnt(" #n ")" ::: "memory")
; #define PG8_WAIT_L(n) asm volatile("s_waitcnt lgkmcnt(" #n ")" ::: "memory")
; #define PG8_BAR __builtin_amdgcn_s_barrier()
; #define PG8_SCHED __builtin_amdgcn_sched_barrier(0)
; template <class Epi, bool ALIGN_EPI = true>
; DI void gemm_phase(int tb_, LAS unsigned char* lds, const Gemm g, const Sched& S, const Epi& E) {
;     ...
;         const bool has_next = S.next(ui + 1, nxt);
;         const char* nA = has_next ? PG8_APTR(nxt) : cA; const char* nB = has_next ? PG8_BPTR(nxt) : cB;
;         const int nt = cur.nt;
;         for (int t = 0; t < nt; t += 2) {
;             const bool last = (t == nt - 2);
;             const char* a1 = cA + (size_t)(t + 1) * kstep;
;             const char* a2 = last ? nA : cA + (size_t)(t + 2) * kstep; const char* b2 = last ? nB : cB + (size_t)(t + 2) * kstep;
;             const char* a3 = a2 + kstep; const char* b3 = b2 + kstep;
;             PG8_LDB(B0, 0, 0); PG8_LDB(B1, 0, 1); PG8_SCHED; PG8_LDA(At, 0, 0); PG8_STAGE(PG8_SA(1, 1), a1 + hstep, voffA);
;             PG8_WAIT_V(8); PG8_WAIT_L(0); PG8_BAR; PG8_MMA(0, 0, At, B0); PG8_MMA(0, 1, At, B1); PG8_BAR; PG8_SCHED;
;             PG8_LDA(At, 0, 1); PG8_STAGE(PG8_SB(0, 0), b2, voffB); PG8_STAGE(PG8_SB(0, 1), b2 + hstep, voffB); PG8_STAGE(PG8_SA(0, 0), a2, voffA);
;     ...
;         for (int a = 0; a < 2; ++a)
; #pragma unroll
;             for (int b = 0; b < 2; ++b)
; #pragma unroll
;                 for (int m = 0; m < 4; ++m)
; #pragma unroll
;                     for (int n = 0; n < 2; ++n) acc[a][b][m][n] = (f32x4){0.f, 0.f, 0.f, 0.f};
.LBB0_1150:
	s_ashr_i32 s19, s18, 31
	s_lshl_b64 s[20:21], s[18:19], 19
	s_add_u32 s17, s5, s20
	s_addc_u32 s19, s27, s21
	s_and_b64 s[20:21], s[6:7], exec
	s_cselect_b32 s21, s19, s25
	s_cselect_b32 s20, s17, s24
	s_ashr_i32 s17, s16, 31
	s_lshl_b64 s[22:23], s[16:17], 19
	s_add_u32 s17, s33, s22
	s_addc_u32 s19, s34, s23
	s_and_b64 s[22:23], s[6:7], exec
	s_cselect_b32 s23, s19, s29
	s_cselect_b32 s22, s17, s28
	s_add_u32 s24, s24, 0x40080
	s_addc_u32 s25, s25, 0
	s_add_u32 s17, s28, 0x100
	s_addc_u32 s19, s29, 0
	s_mov_b32 s45, -2
	s_add_u32 s28, s24, 0xfffc0080
	s_addc_u32 s29, s25, -1
	s_add_i32 s46, 0, 0x10000
	s_cmp_eq_u32 s45, 12
	s_cselect_b32 s31, s21, s29
	s_cselect_b32 s30, s20, s28
	s_cselect_b32 s29, s23, s19
	s_cselect_b32 s28, s22, s17
	s_add_i32 s48, 0, 0x14000
	v_add_u32_e32 v154, s46, v139
	v_add_u32_e32 v170, s48, v139
	ds_read_b128 v[142:145], v154
	ds_read_b128 v[146:149], v154 offset:1024
	ds_read_b128 v[150:153], v154 offset:2048
	ds_read_b128 v[154:157], v154 offset:3072
	ds_read_b128 v[158:161], v170
	ds_read_b128 v[162:165], v170 offset:1024
	ds_read_b128 v[166:169], v170 offset:2048
	ds_read_b128 v[170:173], v170 offset:3072
	v_lshl_add_u64 v[186:187], s[24:25], 0, v[134:135]
	s_add_i32 m0, s13, 0xc000
	ds_read_b128 v[174:177], v141
	ds_read_b128 v[178:181], v141 offset:1024
	ds_read_b128 v[182:185], v141 offset:2048
	ds_read_b128 v[192:195], v141 offset:3072
	ds_read_b128 v[196:199], v141 offset:4096
	ds_read_b128 v[200:203], v141 offset:5120
	ds_read_b128 v[204:207], v141 offset:6144
	ds_read_b128 v[208:211], v141 offset:7168
	global_load_lds_dwordx4 v[186:187], off
	v_lshl_add_u64 v[186:187], s[24:25], 0, v[136:137]
	s_add_i32 m0, s13, 0xe000
	s_nop 0
	global_load_lds_dwordx4 v[186:187], off
	s_waitcnt vmcnt(8)
	s_waitcnt lgkmcnt(0)
	s_barrier
	s_setprio 1
	s_waitcnt lgkmcnt(0)
	v_mfma_f32_16x16x32_bf16 v[124:127], v[142:145], v[174:177], 0
	v_mfma_f32_16x16x32_bf16 v[120:123], v[150:153], v[174:177], 0
	v_mfma_f32_16x16x32_bf16 v[116:119], v[142:145], v[182:185], 0
	v_mfma_f32_16x16x32_bf16 v[112:115], v[150:153], v[182:185], 0
	v_mfma_f32_16x16x32_bf16 v[100:103], v[142:145], v[196:199], 0
	v_mfma_f32_16x16x32_bf16 v[96:99], v[150:153], v[196:199], 0
	v_mfma_f32_16x16x32_bf16 v[84:87], v[142:145], v[204:207], 0
	v_mfma_f32_16x16x32_bf16 v[80:83], v[150:153], v[204:207], 0
	v_mfma_f32_16x16x32_bf16 v[124:127], v[146:149], v[178:181], v[124:127]
	v_mfma_f32_16x16x32_bf16 v[120:123], v[154:157], v[178:181], v[120:123]
	v_mfma_f32_16x16x32_bf16 v[116:119], v[146:149], v[192:195], v[116:119]
	v_mfma_f32_16x16x32_bf16 v[112:115], v[154:157], v[192:195], v[112:115]
	v_mfma_f32_16x16x32_bf16 v[100:103], v[146:149], v[200:203], v[100:103]
	v_mfma_f32_16x16x32_bf16 v[96:99], v[154:157], v[200:203], v[96:99]
	v_mfma_f32_16x16x32_bf16 v[84:87], v[146:149], v[208:211], v[84:87]
	v_mfma_f32_16x16x32_bf16 v[80:83], v[154:157], v[208:211], v[80:83]
	s_setprio 0
	s_setprio 1
	v_mfma_f32_16x16x32_bf16 v[108:111], v[158:161], v[174:177], 0
	v_mfma_f32_16x16x32_bf16 v[104:107], v[166:169], v[174:177], 0
	v_mfma_f32_16x16x32_bf16 v[92:95], v[158:161], v[182:185], 0
	v_mfma_f32_16x16x32_bf16 v[88:91], v[166:169], v[182:185], 0
	v_mfma_f32_16x16x32_bf16 v[76:79], v[158:161], v[196:199], 0
	v_mfma_f32_16x16x32_bf16 v[72:75], v[166:169], v[196:199], 0
	v_mfma_f32_16x16x32_bf16 v[68:71], v[158:161], v[204:207], 0
	v_mfma_f32_16x16x32_bf16 v[64:67], v[166:169], v[204:207], 0
	v_mfma_f32_16x16x32_bf16 v[108:111], v[162:165], v[178:181], v[108:111]
	v_mfma_f32_16x16x32_bf16 v[104:107], v[170:173], v[178:181], v[104:107]
	v_mfma_f32_16x16x32_bf16 v[92:95], v[162:165], v[192:195], v[92:95]
	v_mfma_f32_16x16x32_bf16 v[88:91], v[170:173], v[192:195], v[88:91]
	v_mfma_f32_16x16x32_bf16 v[76:79], v[162:165], v[200:203], v[76:79]
	v_mfma_f32_16x16x32_bf16 v[72:75], v[170:173], v[200:203], v[72:75]
	v_mfma_f32_16x16x32_bf16 v[68:71], v[162:165], v[208:211], v[68:71]
	v_mfma_f32_16x16x32_bf16 v[64:67], v[170:173], v[208:211], v[64:67]
	s_setprio 0
	s_barrier
	s_add_i32 s46, s46, s36
	v_lshl_add_u64 v[186:187], s[28:29], 0, v[188:189]
	s_mov_b32 m0, s46
	ds_read_b128 v[174:177], v141 offset:16384
	ds_read_b128 v[178:181], v141 offset:17408
	ds_read_b128 v[182:185], v141 offset:18432
	ds_read_b128 v[192:195], v141 offset:19456
	ds_read_b128 v[196:199], v141 offset:20480
	ds_read_b128 v[200:203], v141 offset:21504
	ds_read_b128 v[204:207], v141 offset:22528
	ds_read_b128 v[208:211], v141 offset:23552
	global_load_lds_dwordx4 v[186:187], off
	s_add_i32 m0, s46, 0x2000
	s_add_u32 s46, s28, 0x40000
	v_lshl_add_u64 v[212:213], s[28:29], 0, v[128:129]
	s_addc_u32 s47, s29, 0
	s_add_i32 s48, s48, s36
	global_load_lds_dwordx4 v[212:213], off
	v_lshl_add_u64 v[214:215], s[46:47], 0, v[188:189]
	s_mov_b32 m0, s48
	v_lshl_add_u64 v[216:217], s[30:31], 0, v[130:131]
	global_load_lds_dwordx4 v[214:215], off
	v_lshl_add_u64 v[214:215], s[46:47], 0, v[128:129]
	s_add_i32 m0, s48, 0x2000
	s_nop 0
	global_load_lds_dwordx4 v[214:215], off
	v_lshl_add_u64 v[214:215], s[30:31], 0, v[132:133]
	s_mov_b32 m0, s13
	s_nop 0
	global_load_lds_dwordx4 v[214:215], off
	s_mov_b32 m0, s37
	s_nop 0
	global_load_lds_dwordx4 v[216:217], off
	s_waitcnt vmcnt(8)
	s_waitcnt lgkmcnt(0)
	s_barrier
; #define PG8_STAGE(bufoff, gbase, voff) do { _Pragma("unroll") for (int _i = 0; _i < 2; ++_i) \
;         __builtin_amdgcn_global_load_lds((const unsigned*)((const char*)(gbase) + (voff)[_i]), (LAS unsigned*)(lds + (bufoff) + ldsw + _i * 8192), 16, 0, 0); } while (0)
; #define PG8_LDA(dst, b, h) do { _Pragma("unroll") for (int m = 0; m < 4; ++m) _Pragma("unroll") for (int k = 0; k < 2; ++k) dst[m][k] = *(const LAS bf16x8*)(lds + PG8_SA(b, h) + aoff + m * 2048 + k * 1024); } while (0)
; #define PG8_LDB(dst, b, h) do { _Pragma("unroll") for (int n = 0; n < 2; ++n) _Pragma("unroll") for (int k = 0; k < 2; ++k) dst[n][k] = *(const LAS bf16x8*)(lds + PG8_SB(b, h) + boff + n * 2048 + k * 1024); } while (0)
; #define PG8_MMA(ai, bj, At, Bt) do { __builtin_amdgcn_s_setprio(1); _Pragma("unroll") for (int m = 0; m < 4; ++m) _Pragma("unroll") for (int n = 0; n < 2; ++n) _Pragma("unroll") for (int k = 0; k < 2; ++k) \
;         acc[ai][bj][m][n] = __builtin_amdgcn_mfma_f32_16x16x32_bf16(Bt[n][k], At[m][k], acc[ai][bj][m][n], 0, 0, 0); __builtin_amdgcn_s_setprio(0); } while (0)
; #define PG8_WAIT_V(n) asm volatile("s_waitcnt vmcnt(" #n ")" ::: "memory")
; #define PG8_WAIT_L(n) asm volatile("s_waitcnt lgkmcnt(" #n ")" ::: "memory")
; #define PG8_BAR __builtin_amdgcn_s_barrier()
; #define PG8_SCHED __builtin_amdgcn_sched_barrier(0)
; template <class Epi, bool ALIGN_EPI = true>
; DI void gemm_phase(int tb_, LAS unsigned char* lds, const Gemm g, const Sched& S, const Epi& E) {
;     ...
;             PG8_WAIT_V(8); PG8_WAIT_L(0); PG8_BAR; PG8_MMA(1, 0, At, B0); PG8_MMA(1, 1, At, B1); PG8_BAR; PG8_SCHED;
;             PG8_LDB(B0, 1, 0); PG8_LDB(B1, 1, 1); PG8_SCHED; PG8_LDA(At, 1, 0); PG8_STAGE(PG8_SA(0, 1), a2 + hstep, voffA);
;             PG8_WAIT_V(8); PG8_WAIT_L(0); PG8_BAR; PG8_MMA(0, 0, At, B0); PG8_MMA(0, 1, At, B1); PG8_BAR; PG8_SCHED;
	s_setprio 1
	s_waitcnt lgkmcnt(0)
	v_mfma_f32_16x16x32_bf16 v[60:63], v[142:145], v[174:177], 0
	v_mfma_f32_16x16x32_bf16 v[56:59], v[150:153], v[174:177], 0
	v_mfma_f32_16x16x32_bf16 v[52:55], v[142:145], v[182:185], 0
	v_mfma_f32_16x16x32_bf16 v[48:51], v[150:153], v[182:185], 0
	v_mfma_f32_16x16x32_bf16 v[36:39], v[142:145], v[196:199], 0
	v_mfma_f32_16x16x32_bf16 v[32:35], v[150:153], v[196:199], 0
	v_mfma_f32_16x16x32_bf16 v[20:23], v[142:145], v[204:207], 0
	v_mfma_f32_16x16x32_bf16 v[16:19], v[150:153], v[204:207], 0
	v_mfma_f32_16x16x32_bf16 v[60:63], v[146:149], v[178:181], v[60:63]
	v_mfma_f32_16x16x32_bf16 v[56:59], v[154:157], v[178:181], v[56:59]
	v_mfma_f32_16x16x32_bf16 v[52:55], v[146:149], v[192:195], v[52:55]
	v_mfma_f32_16x16x32_bf16 v[48:51], v[154:157], v[192:195], v[48:51]
	v_mfma_f32_16x16x32_bf16 v[36:39], v[146:149], v[200:203], v[36:39]
	v_mfma_f32_16x16x32_bf16 v[32:35], v[154:157], v[200:203], v[32:35]
	v_mfma_f32_16x16x32_bf16 v[20:23], v[146:149], v[208:211], v[20:23]
	v_mfma_f32_16x16x32_bf16 v[16:19], v[154:157], v[208:211], v[16:19]
	s_setprio 0
	s_setprio 1
	v_mfma_f32_16x16x32_bf16 v[44:47], v[158:161], v[174:177], 0
	v_mfma_f32_16x16x32_bf16 v[40:43], v[166:169], v[174:177], 0
	v_mfma_f32_16x16x32_bf16 v[28:31], v[158:161], v[182:185], 0
	v_mfma_f32_16x16x32_bf16 v[24:27], v[166:169], v[182:185], 0
	v_mfma_f32_16x16x32_bf16 v[12:15], v[158:161], v[196:199], 0
	v_mfma_f32_16x16x32_bf16 v[8:11], v[166:169], v[196:199], 0
	v_mfma_f32_16x16x32_bf16 v[4:7], v[158:161], v[204:207], 0
	v_mfma_f32_16x16x32_bf16 v[0:3], v[166:169], v[204:207], 0
	v_mfma_f32_16x16x32_bf16 v[44:47], v[162:165], v[178:181], v[44:47]
	v_mfma_f32_16x16x32_bf16 v[40:43], v[170:173], v[178:181], v[40:43]
	v_mfma_f32_16x16x32_bf16 v[28:31], v[162:165], v[192:195], v[28:31]
	v_mfma_f32_16x16x32_bf16 v[24:27], v[170:173], v[192:195], v[24:27]
	v_mfma_f32_16x16x32_bf16 v[12:15], v[162:165], v[200:203], v[12:15]
	v_mfma_f32_16x16x32_bf16 v[8:11], v[170:173], v[200:203], v[8:11]
	v_mfma_f32_16x16x32_bf16 v[4:7], v[162:165], v[208:211], v[4:7]
	v_mfma_f32_16x16x32_bf16 v[0:3], v[170:173], v[208:211], v[0:3]
	s_setprio 0
	s_barrier
	s_add_i32 s46, 0, 0x18000
	s_add_i32 s47, 0, 0x1c000
	v_add_u32_e32 v154, s46, v139
	v_add_u32_e32 v170, s47, v139
	ds_read_b128 v[142:145], v154
	ds_read_b128 v[146:149], v154 offset:1024
	ds_read_b128 v[150:153], v154 offset:2048
	ds_read_b128 v[154:157], v154 offset:3072
	ds_read_b128 v[158:161], v170
	ds_read_b128 v[162:165], v170 offset:1024
	ds_read_b128 v[166:169], v170 offset:2048
	ds_read_b128 v[170:173], v170 offset:3072
	s_add_u32 s30, s30, 0x40000
	s_addc_u32 s31, s31, 0
	s_mov_b32 m0, s38
	v_lshl_add_u64 v[218:219], s[30:31], 0, v[132:133]
	ds_read_b128 v[174:177], v141 offset:32768
	ds_read_b128 v[178:181], v141 offset:33792
	ds_read_b128 v[182:185], v141 offset:34816
	ds_read_b128 v[192:195], v141 offset:35840
	ds_read_b128 v[196:199], v141 offset:36864
	ds_read_b128 v[200:203], v141 offset:37888
	ds_read_b128 v[204:207], v141 offset:38912
	ds_read_b128 v[208:211], v141 offset:39936
	global_load_lds_dwordx4 v[218:219], off
	v_lshl_add_u64 v[218:219], s[30:31], 0, v[130:131]
	s_mov_b32 m0, s39
	s_nop 0
	global_load_lds_dwordx4 v[218:219], off
	s_waitcnt vmcnt(8)
	s_waitcnt lgkmcnt(0)
	s_barrier
	s_setprio 1
	s_waitcnt lgkmcnt(0)
	v_mfma_f32_16x16x32_bf16 v[124:127], v[142:145], v[174:177], v[124:127]
	v_mfma_f32_16x16x32_bf16 v[120:123], v[150:153], v[174:177], v[120:123]
	v_mfma_f32_16x16x32_bf16 v[116:119], v[142:145], v[182:185], v[116:119]
	v_mfma_f32_16x16x32_bf16 v[112:115], v[150:153], v[182:185], v[112:115]
	v_mfma_f32_16x16x32_bf16 v[100:103], v[142:145], v[196:199], v[100:103]
	v_mfma_f32_16x16x32_bf16 v[96:99], v[150:153], v[196:199], v[96:99]
	v_mfma_f32_16x16x32_bf16 v[84:87], v[142:145], v[204:207], v[84:87]
	v_mfma_f32_16x16x32_bf16 v[80:83], v[150:153], v[204:207], v[80:83]
	v_mfma_f32_16x16x32_bf16 v[124:127], v[146:149], v[178:181], v[124:127]
	v_mfma_f32_16x16x32_bf16 v[120:123], v[154:157], v[178:181], v[120:123]
	v_mfma_f32_16x16x32_bf16 v[116:119], v[146:149], v[192:195], v[116:119]
	v_mfma_f32_16x16x32_bf16 v[112:115], v[154:157], v[192:195], v[112:115]
	v_mfma_f32_16x16x32_bf16 v[100:103], v[146:149], v[200:203], v[100:103]
	v_mfma_f32_16x16x32_bf16 v[96:99], v[154:157], v[200:203], v[96:99]
	v_mfma_f32_16x16x32_bf16 v[84:87], v[146:149], v[208:211], v[84:87]
	v_mfma_f32_16x16x32_bf16 v[80:83], v[154:157], v[208:211], v[80:83]
	s_setprio 0
	s_setprio 1
	v_mfma_f32_16x16x32_bf16 v[108:111], v[158:161], v[174:177], v[108:111]
	v_mfma_f32_16x16x32_bf16 v[104:107], v[166:169], v[174:177], v[104:107]
	v_mfma_f32_16x16x32_bf16 v[92:95], v[158:161], v[182:185], v[92:95]
	v_mfma_f32_16x16x32_bf16 v[88:91], v[166:169], v[182:185], v[88:91]
	v_mfma_f32_16x16x32_bf16 v[76:79], v[158:161], v[196:199], v[76:79]
	v_mfma_f32_16x16x32_bf16 v[72:75], v[166:169], v[196:199], v[72:75]
	v_mfma_f32_16x16x32_bf16 v[68:71], v[158:161], v[204:207], v[68:71]
	v_mfma_f32_16x16x32_bf16 v[64:67], v[166:169], v[204:207], v[64:67]
	v_mfma_f32_16x16x32_bf16 v[108:111], v[162:165], v[178:181], v[108:111]
	v_mfma_f32_16x16x32_bf16 v[104:107], v[170:173], v[178:181], v[104:107]
	v_mfma_f32_16x16x32_bf16 v[92:95], v[162:165], v[192:195], v[92:95]
	v_mfma_f32_16x16x32_bf16 v[88:91], v[170:173], v[192:195], v[88:91]
	v_mfma_f32_16x16x32_bf16 v[76:79], v[162:165], v[200:203], v[76:79]
	v_mfma_f32_16x16x32_bf16 v[72:75], v[170:173], v[200:203], v[72:75]
	v_mfma_f32_16x16x32_bf16 v[68:71], v[162:165], v[208:211], v[68:71]
	v_mfma_f32_16x16x32_bf16 v[64:67], v[170:173], v[208:211], v[64:67]
	s_setprio 0
	s_barrier
; #define PG8_STAGE(bufoff, gbase, voff) do { _Pragma("unroll") for (int _i = 0; _i < 2; ++_i) \
;         __builtin_amdgcn_global_load_lds((const unsigned*)((const char*)(gbase) + (voff)[_i]), (LAS unsigned*)(lds + (bufoff) + ldsw + _i * 8192), 16, 0, 0); } while (0)
; #define PG8_LDA(dst, b, h) do { _Pragma("unroll") for (int m = 0; m < 4; ++m) _Pragma("unroll") for (int k = 0; k < 2; ++k) dst[m][k] = *(const LAS bf16x8*)(lds + PG8_SA(b, h) + aoff + m * 2048 + k * 1024); } while (0)
; #define PG8_MMA(ai, bj, At, Bt) do { __builtin_amdgcn_s_setprio(1); _Pragma("unroll") for (int m = 0; m < 4; ++m) _Pragma("unroll") for (int n = 0; n < 2; ++n) _Pragma("unroll") for (int k = 0; k < 2; ++k) \
;         acc[ai][bj][m][n] = __builtin_amdgcn_mfma_f32_16x16x32_bf16(Bt[n][k], At[m][k], acc[ai][bj][m][n], 0, 0, 0); __builtin_amdgcn_s_setprio(0); } while (0)
; #define PG8_WAIT_V(n) asm volatile("s_waitcnt vmcnt(" #n ")" ::: "memory")
; #define PG8_WAIT_L(n) asm volatile("s_waitcnt lgkmcnt(" #n ")" ::: "memory")
; #define PG8_BAR __builtin_amdgcn_s_barrier()
; #define PG8_SCHED __builtin_amdgcn_sched_barrier(0)
; template <class Epi, bool ALIGN_EPI = true>
; DI void gemm_phase(int tb_, LAS unsigned char* lds, const Gemm g, const Sched& S, const Epi& E) {
;     ...
;             PG8_LDA(At, 1, 1); PG8_STAGE(PG8_SB(1, 0), b3, voffB); PG8_STAGE(PG8_SB(1, 1), b3 + hstep, voffB); PG8_STAGE(PG8_SA(1, 0), a3, voffA);
;             PG8_WAIT_V(8); PG8_WAIT_L(0); PG8_BAR; PG8_MMA(1, 0, At, B0); PG8_MMA(1, 1, At, B1); PG8_BAR; PG8_SCHED;
;         }
	s_add_i32 s30, s46, s36
	v_lshl_add_u64 v[186:187], v[186:187], 0, s[72:73]
	s_mov_b32 m0, s30
	ds_read_b128 v[174:177], v141 offset:49152
	ds_read_b128 v[178:181], v141 offset:50176
	ds_read_b128 v[182:185], v141 offset:51200
	ds_read_b128 v[192:195], v141 offset:52224
	ds_read_b128 v[196:199], v141 offset:53248
	ds_read_b128 v[200:203], v141 offset:54272
	ds_read_b128 v[204:207], v141 offset:55296
	ds_read_b128 v[208:211], v141 offset:56320
	global_load_lds_dwordx4 v[186:187], off
	s_add_i32 m0, s30, 0x2000
	s_add_u32 s28, s28, 0x40080
	v_lshl_add_u64 v[186:187], v[212:213], 0, s[72:73]
	s_addc_u32 s29, s29, 0
	s_add_i32 s30, s47, s36
	global_load_lds_dwordx4 v[186:187], off
	v_lshl_add_u64 v[186:187], s[28:29], 0, v[188:189]
	s_mov_b32 m0, s30
	s_nop 0
	global_load_lds_dwordx4 v[186:187], off
	v_lshl_add_u64 v[186:187], s[28:29], 0, v[128:129]
	s_add_i32 m0, s30, 0x2000
	s_nop 0
	global_load_lds_dwordx4 v[186:187], off
	v_lshl_add_u64 v[186:187], v[214:215], 0, s[72:73]
	s_mov_b32 m0, s40
	s_nop 0
	global_load_lds_dwordx4 v[186:187], off
	v_lshl_add_u64 v[186:187], v[216:217], 0, s[72:73]
	s_mov_b32 m0, s41
	s_nop 0
	global_load_lds_dwordx4 v[186:187], off
	s_waitcnt vmcnt(8)
	s_waitcnt lgkmcnt(0)
	s_barrier
	s_setprio 1
	s_waitcnt lgkmcnt(0)
	v_mfma_f32_16x16x32_bf16 v[60:63], v[142:145], v[174:177], v[60:63]
	v_mfma_f32_16x16x32_bf16 v[56:59], v[150:153], v[174:177], v[56:59]
	v_mfma_f32_16x16x32_bf16 v[52:55], v[142:145], v[182:185], v[52:55]
	v_mfma_f32_16x16x32_bf16 v[48:51], v[150:153], v[182:185], v[48:51]
	v_mfma_f32_16x16x32_bf16 v[36:39], v[142:145], v[196:199], v[36:39]
	v_mfma_f32_16x16x32_bf16 v[32:35], v[150:153], v[196:199], v[32:35]
	v_mfma_f32_16x16x32_bf16 v[20:23], v[142:145], v[204:207], v[20:23]
	v_mfma_f32_16x16x32_bf16 v[16:19], v[150:153], v[204:207], v[16:19]
	v_mfma_f32_16x16x32_bf16 v[60:63], v[146:149], v[178:181], v[60:63]
	v_mfma_f32_16x16x32_bf16 v[56:59], v[154:157], v[178:181], v[56:59]
	v_mfma_f32_16x16x32_bf16 v[52:55], v[146:149], v[192:195], v[52:55]
	v_mfma_f32_16x16x32_bf16 v[48:51], v[154:157], v[192:195], v[48:51]
	v_mfma_f32_16x16x32_bf16 v[36:39], v[146:149], v[200:203], v[36:39]
	v_mfma_f32_16x16x32_bf16 v[32:35], v[154:157], v[200:203], v[32:35]
	v_mfma_f32_16x16x32_bf16 v[20:23], v[146:149], v[208:211], v[20:23]
	v_mfma_f32_16x16x32_bf16 v[16:19], v[154:157], v[208:211], v[16:19]
	s_setprio 0
	s_setprio 1
	v_mfma_f32_16x16x32_bf16 v[44:47], v[158:161], v[174:177], v[44:47]
	v_mfma_f32_16x16x32_bf16 v[40:43], v[166:169], v[174:177], v[40:43]
	v_mfma_f32_16x16x32_bf16 v[28:31], v[158:161], v[182:185], v[28:31]
	v_mfma_f32_16x16x32_bf16 v[24:27], v[166:169], v[182:185], v[24:27]
	v_mfma_f32_16x16x32_bf16 v[12:15], v[158:161], v[196:199], v[12:15]
	v_mfma_f32_16x16x32_bf16 v[8:11], v[166:169], v[196:199], v[8:11]
	v_mfma_f32_16x16x32_bf16 v[4:7], v[158:161], v[204:207], v[4:7]
	v_mfma_f32_16x16x32_bf16 v[0:3], v[166:169], v[204:207], v[0:3]
	v_mfma_f32_16x16x32_bf16 v[44:47], v[162:165], v[178:181], v[44:47]
	v_mfma_f32_16x16x32_bf16 v[40:43], v[170:173], v[178:181], v[40:43]
	v_mfma_f32_16x16x32_bf16 v[28:31], v[162:165], v[192:195], v[28:31]
	v_mfma_f32_16x16x32_bf16 v[24:27], v[170:173], v[192:195], v[24:27]
	v_mfma_f32_16x16x32_bf16 v[12:15], v[162:165], v[200:203], v[12:15]
	v_mfma_f32_16x16x32_bf16 v[8:11], v[170:173], v[200:203], v[8:11]
	v_mfma_f32_16x16x32_bf16 v[4:7], v[162:165], v[208:211], v[4:7]
	v_mfma_f32_16x16x32_bf16 v[0:3], v[170:173], v[208:211], v[0:3]
	s_setprio 0
	s_barrier
	s_add_i32 s45, s45, 2
	s_add_u32 s24, s24, 0x100
	s_addc_u32 s25, s25, 0
	s_add_u32 s17, s17, 0x100
	s_addc_u32 s19, s19, 0
	s_cmp_gt_u32 s45, 13
	s_cbranch_scc1 .Lpeel_exit_4

; #define PG8_STAGE(bufoff, gbase, voff) do { _Pragma("unroll") for (int _i = 0; _i < 2; ++_i) \
;         __builtin_amdgcn_global_load_lds((const unsigned*)((const char*)(gbase) + (voff)[_i]), (LAS unsigned*)(lds + (bufoff) + ldsw + _i * 8192), 16, 0, 0); } while (0)
; #define PG8_LDA(dst, b, h) do { _Pragma("unroll") for (int m = 0; m < 4; ++m) _Pragma("unroll") for (int k = 0; k < 2; ++k) dst[m][k] = *(const LAS bf16x8*)(lds + PG8_SA(b, h) + aoff + m * 2048 + k * 1024); } while (0)
; #define PG8_LDB(dst, b, h) do { _Pragma("unroll") for (int n = 0; n < 2; ++n) _Pragma("unroll") for (int k = 0; k < 2; ++k) dst[n][k] = *(const LAS bf16x8*)(lds + PG8_SB(b, h) + boff + n * 2048 + k * 1024); } while (0)
; #define PG8_WAIT_V(n) asm volatile("s_waitcnt vmcnt(" #n ")" ::: "memory")
; #define PG8_WAIT_L(n) asm volatile("s_waitcnt lgkmcnt(" #n ")" ::: "memory")
; #define PG8_BAR __builtin_amdgcn_s_barrier()
; #define PG8_SCHED __builtin_amdgcn_sched_barrier(0)
; template <class Epi, bool ALIGN_EPI = true>
; DI void gemm_phase(int tb_, LAS unsigned char* lds, const Gemm g, const Sched& S, const Epi& E) {
;     ...
;         const bool has_next = S.next(ui + 1, nxt);
;         const char* nA = has_next ? PG8_APTR(nxt) : cA; const char* nB = has_next ? PG8_BPTR(nxt) : cB;
;         const int nt = cur.nt;
;         for (int t = 0; t < nt; t += 2) {
;             const bool last = (t == nt - 2);
;             const char* a1 = cA + (size_t)(t + 1) * kstep;
;             const char* a2 = last ? nA : cA + (size_t)(t + 2) * kstep; const char* b2 = last ? nB : cB + (size_t)(t + 2) * kstep;
;             const char* a3 = a2 + kstep; const char* b3 = b2 + kstep;
;             PG8_LDB(B0, 0, 0); PG8_LDB(B1, 0, 1); PG8_SCHED; PG8_LDA(At, 0, 0); PG8_STAGE(PG8_SA(1, 1), a1 + hstep, voffA);
;             PG8_WAIT_V(8); PG8_WAIT_L(0); PG8_BAR; PG8_MMA(0, 0, At, B0); PG8_MMA(0, 1, At, B1); PG8_BAR; PG8_SCHED;
;             PG8_LDA(At, 0, 1); PG8_STAGE(PG8_SB(0, 0), b2, voffB); PG8_STAGE(PG8_SB(0, 1), b2 + hstep, voffB); PG8_STAGE(PG8_SA(0, 0), a2, voffA);
;     ...
;         for (int a = 0; a < 2; ++a)
; #pragma unroll
;             for (int b = 0; b < 2; ++b)
; #pragma unroll
;                 for (int m = 0; m < 4; ++m)
; #pragma unroll
;                     for (int n = 0; n < 2; ++n) acc[a][b][m][n] = (f32x4){0.f, 0.f, 0.f, 0.f};
.LBB0_1343:
	s_ashr_i32 s19, s18, 31
	s_lshl_b64 s[20:21], s[18:19], 18
	s_add_u32 s17, s2, s20
	s_addc_u32 s19, s27, s21
	s_and_b64 s[20:21], s[6:7], exec
	s_cselect_b32 s21, s19, s25
	s_cselect_b32 s20, s17, s24
	s_ashr_i32 s17, s16, 31
	s_lshl_b64 s[22:23], s[16:17], 18
	s_add_u32 s17, s33, s22
	s_addc_u32 s19, s35, s23
	s_and_b64 s[22:23], s[6:7], exec
	s_cselect_b32 s23, s19, s29
	s_cselect_b32 s22, s17, s28
	s_add_u32 s24, s24, 0x20080
	s_addc_u32 s25, s25, 0
	s_add_u32 s17, s28, 0x100
	s_addc_u32 s19, s29, 0
	s_mov_b32 s47, -2
	s_add_u32 s28, s24, 0xfffe0080
	s_addc_u32 s29, s25, -1
	s_add_i32 s48, 0, 0x10000
	s_cmp_eq_u32 s47, 4
	s_cselect_b32 s31, s21, s29
	s_cselect_b32 s30, s20, s28
	s_cselect_b32 s29, s23, s19
	s_cselect_b32 s28, s22, s17
	s_add_i32 s50, 0, 0x14000
	v_add_u32_e32 v154, s48, v139
	v_add_u32_e32 v170, s50, v139
	ds_read_b128 v[142:145], v154
	ds_read_b128 v[146:149], v154 offset:1024
	ds_read_b128 v[150:153], v154 offset:2048
	ds_read_b128 v[154:157], v154 offset:3072
	ds_read_b128 v[158:161], v170
	ds_read_b128 v[162:165], v170 offset:1024
	ds_read_b128 v[166:169], v170 offset:2048
	ds_read_b128 v[170:173], v170 offset:3072
	v_lshl_add_u64 v[186:187], s[24:25], 0, v[134:135]
	s_add_i32 m0, s15, 0xc000
	ds_read_b128 v[174:177], v141
	ds_read_b128 v[178:181], v141 offset:1024
	ds_read_b128 v[182:185], v141 offset:2048
	ds_read_b128 v[192:195], v141 offset:3072
	ds_read_b128 v[196:199], v141 offset:4096
	ds_read_b128 v[200:203], v141 offset:5120
	ds_read_b128 v[204:207], v141 offset:6144
	ds_read_b128 v[208:211], v141 offset:7168
	global_load_lds_dwordx4 v[186:187], off
	v_lshl_add_u64 v[186:187], s[24:25], 0, v[136:137]
	s_add_i32 m0, s15, 0xe000
	s_nop 0
	global_load_lds_dwordx4 v[186:187], off
	s_waitcnt vmcnt(8)
	s_waitcnt lgkmcnt(0)
	s_barrier
	s_setprio 1
	s_waitcnt lgkmcnt(0)
	v_mfma_f32_16x16x32_bf16 v[124:127], v[142:145], v[174:177], 0
	v_mfma_f32_16x16x32_bf16 v[120:123], v[150:153], v[174:177], 0
	v_mfma_f32_16x16x32_bf16 v[116:119], v[142:145], v[182:185], 0
	v_mfma_f32_16x16x32_bf16 v[112:115], v[150:153], v[182:185], 0
	v_mfma_f32_16x16x32_bf16 v[100:103], v[142:145], v[196:199], 0
	v_mfma_f32_16x16x32_bf16 v[96:99], v[150:153], v[196:199], 0
	v_mfma_f32_16x16x32_bf16 v[84:87], v[142:145], v[204:207], 0
	v_mfma_f32_16x16x32_bf16 v[80:83], v[150:153], v[204:207], 0
	v_mfma_f32_16x16x32_bf16 v[124:127], v[146:149], v[178:181], v[124:127]
	v_mfma_f32_16x16x32_bf16 v[120:123], v[154:157], v[178:181], v[120:123]
	v_mfma_f32_16x16x32_bf16 v[116:119], v[146:149], v[192:195], v[116:119]
	v_mfma_f32_16x16x32_bf16 v[112:115], v[154:157], v[192:195], v[112:115]
	v_mfma_f32_16x16x32_bf16 v[100:103], v[146:149], v[200:203], v[100:103]
	v_mfma_f32_16x16x32_bf16 v[96:99], v[154:157], v[200:203], v[96:99]
	v_mfma_f32_16x16x32_bf16 v[84:87], v[146:149], v[208:211], v[84:87]
	v_mfma_f32_16x16x32_bf16 v[80:83], v[154:157], v[208:211], v[80:83]
	s_setprio 0
	s_setprio 1
	v_mfma_f32_16x16x32_bf16 v[108:111], v[158:161], v[174:177], 0
	v_mfma_f32_16x16x32_bf16 v[104:107], v[166:169], v[174:177], 0
	v_mfma_f32_16x16x32_bf16 v[92:95], v[158:161], v[182:185], 0
	v_mfma_f32_16x16x32_bf16 v[88:91], v[166:169], v[182:185], 0
	v_mfma_f32_16x16x32_bf16 v[76:79], v[158:161], v[196:199], 0
	v_mfma_f32_16x16x32_bf16 v[72:75], v[166:169], v[196:199], 0
	v_mfma_f32_16x16x32_bf16 v[68:71], v[158:161], v[204:207], 0
	v_mfma_f32_16x16x32_bf16 v[64:67], v[166:169], v[204:207], 0
	v_mfma_f32_16x16x32_bf16 v[108:111], v[162:165], v[178:181], v[108:111]
	v_mfma_f32_16x16x32_bf16 v[104:107], v[170:173], v[178:181], v[104:107]
	v_mfma_f32_16x16x32_bf16 v[92:95], v[162:165], v[192:195], v[92:95]
	v_mfma_f32_16x16x32_bf16 v[88:91], v[170:173], v[192:195], v[88:91]
	v_mfma_f32_16x16x32_bf16 v[76:79], v[162:165], v[200:203], v[76:79]
	v_mfma_f32_16x16x32_bf16 v[72:75], v[170:173], v[200:203], v[72:75]
	v_mfma_f32_16x16x32_bf16 v[68:71], v[162:165], v[208:211], v[68:71]
	v_mfma_f32_16x16x32_bf16 v[64:67], v[170:173], v[208:211], v[64:67]
	s_setprio 0
	s_barrier
	s_add_i32 s48, s48, s36
	v_lshl_add_u64 v[186:187], s[28:29], 0, v[188:189]
	s_mov_b32 m0, s48
	ds_read_b128 v[174:177], v141 offset:16384
	ds_read_b128 v[178:181], v141 offset:17408
	ds_read_b128 v[182:185], v141 offset:18432
	ds_read_b128 v[192:195], v141 offset:19456
	ds_read_b128 v[196:199], v141 offset:20480
	ds_read_b128 v[200:203], v141 offset:21504
	ds_read_b128 v[204:207], v141 offset:22528
	ds_read_b128 v[208:211], v141 offset:23552
	global_load_lds_dwordx4 v[186:187], off
	s_add_i32 m0, s48, 0x2000
	s_add_u32 s48, s28, 0x20000
	v_lshl_add_u64 v[212:213], s[28:29], 0, v[128:129]
	s_addc_u32 s49, s29, 0
	s_add_i32 s50, s50, s36
	global_load_lds_dwordx4 v[212:213], off
	v_lshl_add_u64 v[214:215], s[48:49], 0, v[188:189]
	s_mov_b32 m0, s50
	v_lshl_add_u64 v[216:217], s[30:31], 0, v[130:131]
	global_load_lds_dwordx4 v[214:215], off
	v_lshl_add_u64 v[214:215], s[48:49], 0, v[128:129]
	s_add_i32 m0, s50, 0x2000
	s_nop 0
	global_load_lds_dwordx4 v[214:215], off
	v_lshl_add_u64 v[214:215], s[30:31], 0, v[132:133]
	s_mov_b32 m0, s15
	s_nop 0
	global_load_lds_dwordx4 v[214:215], off
	s_mov_b32 m0, s39
	s_nop 0
	global_load_lds_dwordx4 v[216:217], off
	s_waitcnt vmcnt(8)
	s_waitcnt lgkmcnt(0)
	s_barrier
; #define PG8_STAGE(bufoff, gbase, voff) do { _Pragma("unroll") for (int _i = 0; _i < 2; ++_i) \
;         __builtin_amdgcn_global_load_lds((const unsigned*)((const char*)(gbase) + (voff)[_i]), (LAS unsigned*)(lds + (bufoff) + ldsw + _i * 8192), 16, 0, 0); } while (0)
; #define PG8_LDA(dst, b, h) do { _Pragma("unroll") for (int m = 0; m < 4; ++m) _Pragma("unroll") for (int k = 0; k < 2; ++k) dst[m][k] = *(const LAS bf16x8*)(lds + PG8_SA(b, h) + aoff + m * 2048 + k * 1024); } while (0)
; #define PG8_LDB(dst, b, h) do { _Pragma("unroll") for (int n = 0; n < 2; ++n) _Pragma("unroll") for (int k = 0; k < 2; ++k) dst[n][k] = *(const LAS bf16x8*)(lds + PG8_SB(b, h) + boff + n * 2048 + k * 1024); } while (0)
; #define PG8_MMA(ai, bj, At, Bt) do { __builtin_amdgcn_s_setprio(1); _Pragma("unroll") for (int m = 0; m < 4; ++m) _Pragma("unroll") for (int n = 0; n < 2; ++n) _Pragma("unroll") for (int k = 0; k < 2; ++k) \
;         acc[ai][bj][m][n] = __builtin_amdgcn_mfma_f32_16x16x32_bf16(Bt[n][k], At[m][k], acc[ai][bj][m][n], 0, 0, 0); __builtin_amdgcn_s_setprio(0); } while (0)
; #define PG8_WAIT_V(n) asm volatile("s_waitcnt vmcnt(" #n ")" ::: "memory")
; #define PG8_WAIT_L(n) asm volatile("s_waitcnt lgkmcnt(" #n ")" ::: "memory")
; #define PG8_BAR __builtin_amdgcn_s_barrier()
; #define PG8_SCHED __builtin_amdgcn_sched_barrier(0)
; template <class Epi, bool ALIGN_EPI = true>
; DI void gemm_phase(int tb_, LAS unsigned char* lds, const Gemm g, const Sched& S, const Epi& E) {
;     ...
;             PG8_WAIT_V(8); PG8_WAIT_L(0); PG8_BAR; PG8_MMA(1, 0, At, B0); PG8_MMA(1, 1, At, B1); PG8_BAR; PG8_SCHED;
;             PG8_LDB(B0, 1, 0); PG8_LDB(B1, 1, 1); PG8_SCHED; PG8_LDA(At, 1, 0); PG8_STAGE(PG8_SA(0, 1), a2 + hstep, voffA);
;             PG8_WAIT_V(8); PG8_WAIT_L(0); PG8_BAR; PG8_MMA(0, 0, At, B0); PG8_MMA(0, 1, At, B1); PG8_BAR; PG8_SCHED;
	s_setprio 1
	s_waitcnt lgkmcnt(0)
	v_mfma_f32_16x16x32_bf16 v[60:63], v[142:145], v[174:177], 0
	v_mfma_f32_16x16x32_bf16 v[56:59], v[150:153], v[174:177], 0
	v_mfma_f32_16x16x32_bf16 v[52:55], v[142:145], v[182:185], 0
	v_mfma_f32_16x16x32_bf16 v[48:51], v[150:153], v[182:185], 0
	v_mfma_f32_16x16x32_bf16 v[36:39], v[142:145], v[196:199], 0
	v_mfma_f32_16x16x32_bf16 v[32:35], v[150:153], v[196:199], 0
	v_mfma_f32_16x16x32_bf16 v[20:23], v[142:145], v[204:207], 0
	v_mfma_f32_16x16x32_bf16 v[16:19], v[150:153], v[204:207], 0
	v_mfma_f32_16x16x32_bf16 v[60:63], v[146:149], v[178:181], v[60:63]
	v_mfma_f32_16x16x32_bf16 v[56:59], v[154:157], v[178:181], v[56:59]
	v_mfma_f32_16x16x32_bf16 v[52:55], v[146:149], v[192:195], v[52:55]
	v_mfma_f32_16x16x32_bf16 v[48:51], v[154:157], v[192:195], v[48:51]
	v_mfma_f32_16x16x32_bf16 v[36:39], v[146:149], v[200:203], v[36:39]
	v_mfma_f32_16x16x32_bf16 v[32:35], v[154:157], v[200:203], v[32:35]
	v_mfma_f32_16x16x32_bf16 v[20:23], v[146:149], v[208:211], v[20:23]
	v_mfma_f32_16x16x32_bf16 v[16:19], v[154:157], v[208:211], v[16:19]
	s_setprio 0
	s_setprio 1
	v_mfma_f32_16x16x32_bf16 v[44:47], v[158:161], v[174:177], 0
	v_mfma_f32_16x16x32_bf16 v[40:43], v[166:169], v[174:177], 0
	v_mfma_f32_16x16x32_bf16 v[28:31], v[158:161], v[182:185], 0
	v_mfma_f32_16x16x32_bf16 v[24:27], v[166:169], v[182:185], 0
	v_mfma_f32_16x16x32_bf16 v[12:15], v[158:161], v[196:199], 0
	v_mfma_f32_16x16x32_bf16 v[8:11], v[166:169], v[196:199], 0
	v_mfma_f32_16x16x32_bf16 v[4:7], v[158:161], v[204:207], 0
	v_mfma_f32_16x16x32_bf16 v[0:3], v[166:169], v[204:207], 0
	v_mfma_f32_16x16x32_bf16 v[44:47], v[162:165], v[178:181], v[44:47]
	v_mfma_f32_16x16x32_bf16 v[40:43], v[170:173], v[178:181], v[40:43]
	v_mfma_f32_16x16x32_bf16 v[28:31], v[162:165], v[192:195], v[28:31]
	v_mfma_f32_16x16x32_bf16 v[24:27], v[170:173], v[192:195], v[24:27]
	v_mfma_f32_16x16x32_bf16 v[12:15], v[162:165], v[200:203], v[12:15]
	v_mfma_f32_16x16x32_bf16 v[8:11], v[170:173], v[200:203], v[8:11]
	v_mfma_f32_16x16x32_bf16 v[4:7], v[162:165], v[208:211], v[4:7]
	v_mfma_f32_16x16x32_bf16 v[0:3], v[170:173], v[208:211], v[0:3]
	s_setprio 0
	s_barrier
	s_add_i32 s48, 0, 0x18000
	s_add_i32 s49, 0, 0x1c000
	v_add_u32_e32 v154, s48, v139
	v_add_u32_e32 v170, s49, v139
	ds_read_b128 v[142:145], v154
	ds_read_b128 v[146:149], v154 offset:1024
	ds_read_b128 v[150:153], v154 offset:2048
	ds_read_b128 v[154:157], v154 offset:3072
	ds_read_b128 v[158:161], v170
	ds_read_b128 v[162:165], v170 offset:1024
	ds_read_b128 v[166:169], v170 offset:2048
	ds_read_b128 v[170:173], v170 offset:3072
	s_add_u32 s30, s30, 0x20000
	s_addc_u32 s31, s31, 0
	s_mov_b32 m0, s40
	v_lshl_add_u64 v[218:219], s[30:31], 0, v[132:133]
	ds_read_b128 v[174:177], v141 offset:32768
	ds_read_b128 v[178:181], v141 offset:33792
	ds_read_b128 v[182:185], v141 offset:34816
	ds_read_b128 v[192:195], v141 offset:35840
	ds_read_b128 v[196:199], v141 offset:36864
	ds_read_b128 v[200:203], v141 offset:37888
	ds_read_b128 v[204:207], v141 offset:38912
	ds_read_b128 v[208:211], v141 offset:39936
	global_load_lds_dwordx4 v[218:219], off
	v_lshl_add_u64 v[218:219], s[30:31], 0, v[130:131]
	s_mov_b32 m0, s41
	s_nop 0
	global_load_lds_dwordx4 v[218:219], off
	s_waitcnt vmcnt(8)
	s_waitcnt lgkmcnt(0)
	s_barrier
	s_setprio 1
	s_waitcnt lgkmcnt(0)
	v_mfma_f32_16x16x32_bf16 v[124:127], v[142:145], v[174:177], v[124:127]
	v_mfma_f32_16x16x32_bf16 v[120:123], v[150:153], v[174:177], v[120:123]
	v_mfma_f32_16x16x32_bf16 v[116:119], v[142:145], v[182:185], v[116:119]
	v_mfma_f32_16x16x32_bf16 v[112:115], v[150:153], v[182:185], v[112:115]
	v_mfma_f32_16x16x32_bf16 v[100:103], v[142:145], v[196:199], v[100:103]
	v_mfma_f32_16x16x32_bf16 v[96:99], v[150:153], v[196:199], v[96:99]
	v_mfma_f32_16x16x32_bf16 v[84:87], v[142:145], v[204:207], v[84:87]
	v_mfma_f32_16x16x32_bf16 v[80:83], v[150:153], v[204:207], v[80:83]
	v_mfma_f32_16x16x32_bf16 v[124:127], v[146:149], v[178:181], v[124:127]
	v_mfma_f32_16x16x32_bf16 v[120:123], v[154:157], v[178:181], v[120:123]
	v_mfma_f32_16x16x32_bf16 v[116:119], v[146:149], v[192:195], v[116:119]
	v_mfma_f32_16x16x32_bf16 v[112:115], v[154:157], v[192:195], v[112:115]
	v_mfma_f32_16x16x32_bf16 v[100:103], v[146:149], v[200:203], v[100:103]
	v_mfma_f32_16x16x32_bf16 v[96:99], v[154:157], v[200:203], v[96:99]
	v_mfma_f32_16x16x32_bf16 v[84:87], v[146:149], v[208:211], v[84:87]
	v_mfma_f32_16x16x32_bf16 v[80:83], v[154:157], v[208:211], v[80:83]
	s_setprio 0
	s_setprio 1
	v_mfma_f32_16x16x32_bf16 v[108:111], v[158:161], v[174:177], v[108:111]
	v_mfma_f32_16x16x32_bf16 v[104:107], v[166:169], v[174:177], v[104:107]
	v_mfma_f32_16x16x32_bf16 v[92:95], v[158:161], v[182:185], v[92:95]
	v_mfma_f32_16x16x32_bf16 v[88:91], v[166:169], v[182:185], v[88:91]
	v_mfma_f32_16x16x32_bf16 v[76:79], v[158:161], v[196:199], v[76:79]
	v_mfma_f32_16x16x32_bf16 v[72:75], v[166:169], v[196:199], v[72:75]
	v_mfma_f32_16x16x32_bf16 v[68:71], v[158:161], v[204:207], v[68:71]
	v_mfma_f32_16x16x32_bf16 v[64:67], v[166:169], v[204:207], v[64:67]
	v_mfma_f32_16x16x32_bf16 v[108:111], v[162:165], v[178:181], v[108:111]
	v_mfma_f32_16x16x32_bf16 v[104:107], v[170:173], v[178:181], v[104:107]
	v_mfma_f32_16x16x32_bf16 v[92:95], v[162:165], v[192:195], v[92:95]
	v_mfma_f32_16x16x32_bf16 v[88:91], v[170:173], v[192:195], v[88:91]
	v_mfma_f32_16x16x32_bf16 v[76:79], v[162:165], v[200:203], v[76:79]
	v_mfma_f32_16x16x32_bf16 v[72:75], v[170:173], v[200:203], v[72:75]
	v_mfma_f32_16x16x32_bf16 v[68:71], v[162:165], v[208:211], v[68:71]
	v_mfma_f32_16x16x32_bf16 v[64:67], v[170:173], v[208:211], v[64:67]
	s_setprio 0
	s_barrier
; #define PG8_STAGE(bufoff, gbase, voff) do { _Pragma("unroll") for (int _i = 0; _i < 2; ++_i) \
;         __builtin_amdgcn_global_load_lds((const unsigned*)((const char*)(gbase) + (voff)[_i]), (LAS unsigned*)(lds + (bufoff) + ldsw + _i * 8192), 16, 0, 0); } while (0)
; #define PG8_LDA(dst, b, h) do { _Pragma("unroll") for (int m = 0; m < 4; ++m) _Pragma("unroll") for (int k = 0; k < 2; ++k) dst[m][k] = *(const LAS bf16x8*)(lds + PG8_SA(b, h) + aoff + m * 2048 + k * 1024); } while (0)
; #define PG8_MMA(ai, bj, At, Bt) do { __builtin_amdgcn_s_setprio(1); _Pragma("unroll") for (int m = 0; m < 4; ++m) _Pragma("unroll") for (int n = 0; n < 2; ++n) _Pragma("unroll") for (int k = 0; k < 2; ++k) \
;         acc[ai][bj][m][n] = __builtin_amdgcn_mfma_f32_16x16x32_bf16(Bt[n][k], At[m][k], acc[ai][bj][m][n], 0, 0, 0); __builtin_amdgcn_s_setprio(0); } while (0)
; #define PG8_WAIT_V(n) asm volatile("s_waitcnt vmcnt(" #n ")" ::: "memory")
; #define PG8_WAIT_L(n) asm volatile("s_waitcnt lgkmcnt(" #n ")" ::: "memory")
; #define PG8_BAR __builtin_amdgcn_s_barrier()
; #define PG8_SCHED __builtin_amdgcn_sched_barrier(0)
; template <class Epi, bool ALIGN_EPI = true>
; DI void gemm_phase(int tb_, LAS unsigned char* lds, const Gemm g, const Sched& S, const Epi& E) {
;     ...
;             PG8_LDA(At, 1, 1); PG8_STAGE(PG8_SB(1, 0), b3, voffB); PG8_STAGE(PG8_SB(1, 1), b3 + hstep, voffB); PG8_STAGE(PG8_SA(1, 0), a3, voffA);
;             PG8_WAIT_V(8); PG8_WAIT_L(0); PG8_BAR; PG8_MMA(1, 0, At, B0); PG8_MMA(1, 1, At, B1); PG8_BAR; PG8_SCHED;
;         }
	s_add_i32 s30, s48, s36
	v_lshl_add_u64 v[186:187], v[186:187], 0, s[72:73]
	s_mov_b32 m0, s30
	ds_read_b128 v[174:177], v141 offset:49152
	ds_read_b128 v[178:181], v141 offset:50176
	ds_read_b128 v[182:185], v141 offset:51200
	ds_read_b128 v[192:195], v141 offset:52224
	ds_read_b128 v[196:199], v141 offset:53248
	ds_read_b128 v[200:203], v141 offset:54272
	ds_read_b128 v[204:207], v141 offset:55296
	ds_read_b128 v[208:211], v141 offset:56320
	global_load_lds_dwordx4 v[186:187], off
	s_add_i32 m0, s30, 0x2000
	s_add_u32 s28, s28, 0x20080
	v_lshl_add_u64 v[186:187], v[212:213], 0, s[72:73]
	s_addc_u32 s29, s29, 0
	s_add_i32 s30, s49, s36
	global_load_lds_dwordx4 v[186:187], off
	v_lshl_add_u64 v[186:187], s[28:29], 0, v[188:189]
	s_mov_b32 m0, s30
	s_nop 0
	global_load_lds_dwordx4 v[186:187], off
	v_lshl_add_u64 v[186:187], s[28:29], 0, v[128:129]
	s_add_i32 m0, s30, 0x2000
	s_nop 0
	global_load_lds_dwordx4 v[186:187], off
	v_lshl_add_u64 v[186:187], v[214:215], 0, s[72:73]
	s_mov_b32 m0, s42
	s_nop 0
	global_load_lds_dwordx4 v[186:187], off
	v_lshl_add_u64 v[186:187], v[216:217], 0, s[72:73]
	s_mov_b32 m0, s43
	s_nop 0
	global_load_lds_dwordx4 v[186:187], off
	s_waitcnt vmcnt(8)
	s_waitcnt lgkmcnt(0)
	s_barrier
	s_setprio 1
	s_waitcnt lgkmcnt(0)
	v_mfma_f32_16x16x32_bf16 v[60:63], v[142:145], v[174:177], v[60:63]
	v_mfma_f32_16x16x32_bf16 v[56:59], v[150:153], v[174:177], v[56:59]
	v_mfma_f32_16x16x32_bf16 v[52:55], v[142:145], v[182:185], v[52:55]
	v_mfma_f32_16x16x32_bf16 v[48:51], v[150:153], v[182:185], v[48:51]
	v_mfma_f32_16x16x32_bf16 v[36:39], v[142:145], v[196:199], v[36:39]
	v_mfma_f32_16x16x32_bf16 v[32:35], v[150:153], v[196:199], v[32:35]
	v_mfma_f32_16x16x32_bf16 v[20:23], v[142:145], v[204:207], v[20:23]
	v_mfma_f32_16x16x32_bf16 v[16:19], v[150:153], v[204:207], v[16:19]
	v_mfma_f32_16x16x32_bf16 v[60:63], v[146:149], v[178:181], v[60:63]
	v_mfma_f32_16x16x32_bf16 v[56:59], v[154:157], v[178:181], v[56:59]
	v_mfma_f32_16x16x32_bf16 v[52:55], v[146:149], v[192:195], v[52:55]
	v_mfma_f32_16x16x32_bf16 v[48:51], v[154:157], v[192:195], v[48:51]
	v_mfma_f32_16x16x32_bf16 v[36:39], v[146:149], v[200:203], v[36:39]
	v_mfma_f32_16x16x32_bf16 v[32:35], v[154:157], v[200:203], v[32:35]
	v_mfma_f32_16x16x32_bf16 v[20:23], v[146:149], v[208:211], v[20:23]
	v_mfma_f32_16x16x32_bf16 v[16:19], v[154:157], v[208:211], v[16:19]
	s_setprio 0
	s_setprio 1
	v_mfma_f32_16x16x32_bf16 v[44:47], v[158:161], v[174:177], v[44:47]
	v_mfma_f32_16x16x32_bf16 v[40:43], v[166:169], v[174:177], v[40:43]
	v_mfma_f32_16x16x32_bf16 v[28:31], v[158:161], v[182:185], v[28:31]
	v_mfma_f32_16x16x32_bf16 v[24:27], v[166:169], v[182:185], v[24:27]
	v_mfma_f32_16x16x32_bf16 v[12:15], v[158:161], v[196:199], v[12:15]
	v_mfma_f32_16x16x32_bf16 v[8:11], v[166:169], v[196:199], v[8:11]
	v_mfma_f32_16x16x32_bf16 v[4:7], v[158:161], v[204:207], v[4:7]
	v_mfma_f32_16x16x32_bf16 v[0:3], v[166:169], v[204:207], v[0:3]
	v_mfma_f32_16x16x32_bf16 v[44:47], v[162:165], v[178:181], v[44:47]
	v_mfma_f32_16x16x32_bf16 v[40:43], v[170:173], v[178:181], v[40:43]
	v_mfma_f32_16x16x32_bf16 v[28:31], v[162:165], v[192:195], v[28:31]
	v_mfma_f32_16x16x32_bf16 v[24:27], v[170:173], v[192:195], v[24:27]
	v_mfma_f32_16x16x32_bf16 v[12:15], v[162:165], v[200:203], v[12:15]
	v_mfma_f32_16x16x32_bf16 v[8:11], v[170:173], v[200:203], v[8:11]
	v_mfma_f32_16x16x32_bf16 v[4:7], v[162:165], v[208:211], v[4:7]
	v_mfma_f32_16x16x32_bf16 v[0:3], v[170:173], v[208:211], v[0:3]
	s_setprio 0
	s_barrier
	s_add_i32 s47, s47, 2
	s_add_u32 s24, s24, 0x100
	s_addc_u32 s25, s25, 0
	s_add_u32 s17, s17, 0x100
	s_addc_u32 s19, s19, 0
	s_cmp_gt_u32 s47, 5
	s_cbranch_scc1 .Lpeel_exit_5

; #define PG8_STAGE(bufoff, gbase, voff) do { _Pragma("unroll") for (int _i = 0; _i < 2; ++_i) \
;         __builtin_amdgcn_global_load_lds((const unsigned*)((const char*)(gbase) + (voff)[_i]), (LAS unsigned*)(lds + (bufoff) + ldsw + _i * 8192), 16, 0, 0); } while (0)
; #define PG8_LDA(dst, b, h) do { _Pragma("unroll") for (int m = 0; m < 4; ++m) _Pragma("unroll") for (int k = 0; k < 2; ++k) dst[m][k] = *(const LAS bf16x8*)(lds + PG8_SA(b, h) + aoff + m * 2048 + k * 1024); } while (0)
; #define PG8_LDB(dst, b, h) do { _Pragma("unroll") for (int n = 0; n < 2; ++n) _Pragma("unroll") for (int k = 0; k < 2; ++k) dst[n][k] = *(const LAS bf16x8*)(lds + PG8_SB(b, h) + boff + n * 2048 + k * 1024); } while (0)
; #define PG8_WAIT_V(n) asm volatile("s_waitcnt vmcnt(" #n ")" ::: "memory")
; #define PG8_WAIT_L(n) asm volatile("s_waitcnt lgkmcnt(" #n ")" ::: "memory")
; #define PG8_BAR __builtin_amdgcn_s_barrier()
; #define PG8_SCHED __builtin_amdgcn_sched_barrier(0)
; template <class Epi, bool ALIGN_EPI = true>
; DI void gemm_phase(int tb_, LAS unsigned char* lds, const Gemm g, const Sched& S, const Epi& E) {
;     ...
;         const bool has_next = S.next(ui + 1, nxt);
;         const char* nA = has_next ? PG8_APTR(nxt) : cA; const char* nB = has_next ? PG8_BPTR(nxt) : cB;
;         const int nt = cur.nt;
;         for (int t = 0; t < nt; t += 2) {
;             const bool last = (t == nt - 2);
;             const char* a1 = cA + (size_t)(t + 1) * kstep;
;             const char* a2 = last ? nA : cA + (size_t)(t + 2) * kstep; const char* b2 = last ? nB : cB + (size_t)(t + 2) * kstep;
;             const char* a3 = a2 + kstep; const char* b3 = b2 + kstep;
;             PG8_LDB(B0, 0, 0); PG8_LDB(B1, 0, 1); PG8_SCHED; PG8_LDA(At, 0, 0); PG8_STAGE(PG8_SA(1, 1), a1 + hstep, voffA);
;             PG8_WAIT_V(8); PG8_WAIT_L(0); PG8_BAR; PG8_MMA(0, 0, At, B0); PG8_MMA(0, 1, At, B1); PG8_BAR; PG8_SCHED;
;             PG8_LDA(At, 0, 1); PG8_STAGE(PG8_SB(0, 0), b2, voffB); PG8_STAGE(PG8_SB(0, 1), b2 + hstep, voffB); PG8_STAGE(PG8_SA(0, 0), a2, voffA);
;     ...
;         for (int a = 0; a < 2; ++a)
; #pragma unroll
;             for (int b = 0; b < 2; ++b)
; #pragma unroll
;                 for (int m = 0; m < 4; ++m)
; #pragma unroll
;                     for (int n = 0; n < 2; ++n) acc[a][b][m][n] = (f32x4){0.f, 0.f, 0.f, 0.f};
.LBB0_1489:
	s_ashr_i32 s15, s14, 31
	s_lshl_b64 s[16:17], s[14:15], 19
	s_add_u32 s16, s30, s16
	s_addc_u32 s17, s31, s17
	s_and_b64 s[18:19], s[6:7], exec
	s_cselect_b32 s15, s17, s25
	s_cselect_b32 s45, s16, s24
	s_ashr_i32 s13, s12, 31
	s_lshl_b64 s[18:19], s[12:13], 19
	s_add_u32 s18, s34, s18
	s_addc_u32 s19, s35, s19
	s_and_b64 s[28:29], s[6:7], exec
	s_cselect_b32 s13, s19, s27
	s_cselect_b32 s46, s18, s26
	s_add_u32 s24, s24, 0x40080
	s_addc_u32 s25, s25, 0
	s_add_u32 s47, s26, 0x100
	s_addc_u32 s48, s27, 0
	s_mov_b32 s49, -2
	s_add_u32 s26, s24, 0xfffc0080
	s_addc_u32 s27, s25, -1
	s_add_i32 s50, 0, 0x10000
	s_cmp_eq_u32 s49, 12
	s_cselect_b32 s29, s15, s27
	s_cselect_b32 s28, s45, s26
	v_add_u32_e32 v142, s50, v145
	s_cselect_b32 s27, s13, s48
	s_cselect_b32 s26, s46, s47
	s_add_i32 s52, 0, 0x14000
	ds_read_b128 v[138:141], v142
	ds_read_b128 v[148:151], v142 offset:1024
	ds_read_b128 v[152:155], v142 offset:2048
	ds_read_b128 v[156:159], v142 offset:3072
	v_add_u32_e32 v142, s52, v145
	ds_read_b128 v[160:163], v142
	ds_read_b128 v[164:167], v142 offset:1024
	ds_read_b128 v[168:171], v142 offset:2048
	ds_read_b128 v[172:175], v142 offset:3072
	v_lshl_add_u64 v[142:143], s[24:25], 0, v[134:135]
	s_add_i32 m0, s2, 0xc000
	ds_read_b128 v[176:179], v147
	ds_read_b128 v[180:183], v147 offset:1024
	ds_read_b128 v[184:187], v147 offset:2048
	ds_read_b128 v[192:195], v147 offset:3072
	ds_read_b128 v[196:199], v147 offset:4096
	ds_read_b128 v[200:203], v147 offset:5120
	ds_read_b128 v[204:207], v147 offset:6144
	ds_read_b128 v[208:211], v147 offset:7168
	global_load_lds_dwordx4 v[142:143], off
	v_lshl_add_u64 v[142:143], s[24:25], 0, v[136:137]
	s_add_i32 m0, s2, 0xe000
	s_nop 0
	global_load_lds_dwordx4 v[142:143], off
	s_waitcnt vmcnt(8)
	s_waitcnt lgkmcnt(0)
	s_barrier
	s_setprio 1
	s_waitcnt lgkmcnt(0)
	v_mfma_f32_16x16x32_bf16 v[124:127], v[138:141], v[176:179], 0
	v_mfma_f32_16x16x32_bf16 v[120:123], v[152:155], v[176:179], 0
	v_mfma_f32_16x16x32_bf16 v[108:111], v[138:141], v[184:187], 0
	v_mfma_f32_16x16x32_bf16 v[104:107], v[152:155], v[184:187], 0
	v_mfma_f32_16x16x32_bf16 v[92:95], v[138:141], v[196:199], 0
	v_mfma_f32_16x16x32_bf16 v[88:91], v[152:155], v[196:199], 0
	v_mfma_f32_16x16x32_bf16 v[76:79], v[138:141], v[204:207], 0
	v_mfma_f32_16x16x32_bf16 v[72:75], v[152:155], v[204:207], 0
	v_mfma_f32_16x16x32_bf16 v[124:127], v[148:151], v[180:183], v[124:127]
	v_mfma_f32_16x16x32_bf16 v[120:123], v[156:159], v[180:183], v[120:123]
	v_mfma_f32_16x16x32_bf16 v[108:111], v[148:151], v[192:195], v[108:111]
	v_mfma_f32_16x16x32_bf16 v[104:107], v[156:159], v[192:195], v[104:107]
	v_mfma_f32_16x16x32_bf16 v[92:95], v[148:151], v[200:203], v[92:95]
	v_mfma_f32_16x16x32_bf16 v[88:91], v[156:159], v[200:203], v[88:91]
	v_mfma_f32_16x16x32_bf16 v[76:79], v[148:151], v[208:211], v[76:79]
	v_mfma_f32_16x16x32_bf16 v[72:75], v[156:159], v[208:211], v[72:75]
	s_setprio 0
	s_setprio 1
	v_mfma_f32_16x16x32_bf16 v[116:119], v[160:163], v[176:179], 0
	v_mfma_f32_16x16x32_bf16 v[112:115], v[168:171], v[176:179], 0
	v_mfma_f32_16x16x32_bf16 v[100:103], v[160:163], v[184:187], 0
	v_mfma_f32_16x16x32_bf16 v[96:99], v[168:171], v[184:187], 0
	v_mfma_f32_16x16x32_bf16 v[84:87], v[160:163], v[196:199], 0
	v_mfma_f32_16x16x32_bf16 v[80:83], v[168:171], v[196:199], 0
	v_mfma_f32_16x16x32_bf16 v[68:71], v[160:163], v[204:207], 0
	v_mfma_f32_16x16x32_bf16 v[64:67], v[168:171], v[204:207], 0
	v_mfma_f32_16x16x32_bf16 v[116:119], v[164:167], v[180:183], v[116:119]
	v_mfma_f32_16x16x32_bf16 v[112:115], v[172:175], v[180:183], v[112:115]
	v_mfma_f32_16x16x32_bf16 v[100:103], v[164:167], v[192:195], v[100:103]
	v_mfma_f32_16x16x32_bf16 v[96:99], v[172:175], v[192:195], v[96:99]
	v_mfma_f32_16x16x32_bf16 v[84:87], v[164:167], v[200:203], v[84:87]
	v_mfma_f32_16x16x32_bf16 v[80:83], v[172:175], v[200:203], v[80:83]
	v_mfma_f32_16x16x32_bf16 v[68:71], v[164:167], v[208:211], v[68:71]
	v_mfma_f32_16x16x32_bf16 v[64:67], v[172:175], v[208:211], v[64:67]
	s_setprio 0
	s_barrier
	s_add_i32 s50, s50, s38
	v_lshl_add_u64 v[142:143], s[26:27], 0, v[188:189]
	s_mov_b32 m0, s50
	ds_read_b128 v[176:179], v147 offset:16384
	ds_read_b128 v[180:183], v147 offset:17408
	ds_read_b128 v[184:187], v147 offset:18432
	ds_read_b128 v[192:195], v147 offset:19456
	ds_read_b128 v[196:199], v147 offset:20480
	ds_read_b128 v[200:203], v147 offset:21504
	ds_read_b128 v[204:207], v147 offset:22528
	ds_read_b128 v[208:211], v147 offset:23552
	global_load_lds_dwordx4 v[142:143], off
	s_add_i32 m0, s50, 0x2000
	s_add_u32 s50, s26, 0x40000
	v_lshl_add_u64 v[212:213], s[26:27], 0, v[128:129]
	s_addc_u32 s51, s27, 0
	s_add_i32 s52, s52, s38
	global_load_lds_dwordx4 v[212:213], off
	v_lshl_add_u64 v[214:215], s[50:51], 0, v[188:189]
	s_mov_b32 m0, s52
	v_lshl_add_u64 v[216:217], s[28:29], 0, v[130:131]
	global_load_lds_dwordx4 v[214:215], off
	v_lshl_add_u64 v[214:215], s[50:51], 0, v[128:129]
	s_add_i32 m0, s52, 0x2000
	s_nop 0
	global_load_lds_dwordx4 v[214:215], off
	v_lshl_add_u64 v[214:215], s[28:29], 0, v[132:133]
	s_mov_b32 m0, s2
	s_nop 0
	global_load_lds_dwordx4 v[214:215], off
	s_mov_b32 m0, s21
	s_nop 0
	global_load_lds_dwordx4 v[216:217], off
	s_waitcnt vmcnt(8)
	s_waitcnt lgkmcnt(0)
	s_barrier
; #define PG8_STAGE(bufoff, gbase, voff) do { _Pragma("unroll") for (int _i = 0; _i < 2; ++_i) \
;         __builtin_amdgcn_global_load_lds((const unsigned*)((const char*)(gbase) + (voff)[_i]), (LAS unsigned*)(lds + (bufoff) + ldsw + _i * 8192), 16, 0, 0); } while (0)
; #define PG8_LDA(dst, b, h) do { _Pragma("unroll") for (int m = 0; m < 4; ++m) _Pragma("unroll") for (int k = 0; k < 2; ++k) dst[m][k] = *(const LAS bf16x8*)(lds + PG8_SA(b, h) + aoff + m * 2048 + k * 1024); } while (0)
; #define PG8_LDB(dst, b, h) do { _Pragma("unroll") for (int n = 0; n < 2; ++n) _Pragma("unroll") for (int k = 0; k < 2; ++k) dst[n][k] = *(const LAS bf16x8*)(lds + PG8_SB(b, h) + boff + n * 2048 + k * 1024); } while (0)
; #define PG8_MMA(ai, bj, At, Bt) do { __builtin_amdgcn_s_setprio(1); _Pragma("unroll") for (int m = 0; m < 4; ++m) _Pragma("unroll") for (int n = 0; n < 2; ++n) _Pragma("unroll") for (int k = 0; k < 2; ++k) \
;         acc[ai][bj][m][n] = __builtin_amdgcn_mfma_f32_16x16x32_bf16(Bt[n][k], At[m][k], acc[ai][bj][m][n], 0, 0, 0); __builtin_amdgcn_s_setprio(0); } while (0)
; #define PG8_WAIT_V(n) asm volatile("s_waitcnt vmcnt(" #n ")" ::: "memory")
; #define PG8_WAIT_L(n) asm volatile("s_waitcnt lgkmcnt(" #n ")" ::: "memory")
; #define PG8_BAR __builtin_amdgcn_s_barrier()
; #define PG8_SCHED __builtin_amdgcn_sched_barrier(0)
; template <class Epi, bool ALIGN_EPI = true>
; DI void gemm_phase(int tb_, LAS unsigned char* lds, const Gemm g, const Sched& S, const Epi& E) {
;     ...
;             PG8_WAIT_V(8); PG8_WAIT_L(0); PG8_BAR; PG8_MMA(1, 0, At, B0); PG8_MMA(1, 1, At, B1); PG8_BAR; PG8_SCHED;
;             PG8_LDB(B0, 1, 0); PG8_LDB(B1, 1, 1); PG8_SCHED; PG8_LDA(At, 1, 0); PG8_STAGE(PG8_SA(0, 1), a2 + hstep, voffA);
;             PG8_WAIT_V(8); PG8_WAIT_L(0); PG8_BAR; PG8_MMA(0, 0, At, B0); PG8_MMA(0, 1, At, B1); PG8_BAR; PG8_SCHED;
	s_setprio 1
	s_waitcnt lgkmcnt(0)
	v_mfma_f32_16x16x32_bf16 v[60:63], v[138:141], v[176:179], 0
	v_mfma_f32_16x16x32_bf16 v[56:59], v[152:155], v[176:179], 0
	v_mfma_f32_16x16x32_bf16 v[44:47], v[138:141], v[184:187], 0
	v_mfma_f32_16x16x32_bf16 v[40:43], v[152:155], v[184:187], 0
	v_mfma_f32_16x16x32_bf16 v[28:31], v[138:141], v[196:199], 0
	v_mfma_f32_16x16x32_bf16 v[24:27], v[152:155], v[196:199], 0
	v_mfma_f32_16x16x32_bf16 v[12:15], v[138:141], v[204:207], 0
	v_mfma_f32_16x16x32_bf16 v[8:11], v[152:155], v[204:207], 0
	v_mfma_f32_16x16x32_bf16 v[60:63], v[148:151], v[180:183], v[60:63]
	v_mfma_f32_16x16x32_bf16 v[56:59], v[156:159], v[180:183], v[56:59]
	v_mfma_f32_16x16x32_bf16 v[44:47], v[148:151], v[192:195], v[44:47]
	v_mfma_f32_16x16x32_bf16 v[40:43], v[156:159], v[192:195], v[40:43]
	v_mfma_f32_16x16x32_bf16 v[28:31], v[148:151], v[200:203], v[28:31]
	v_mfma_f32_16x16x32_bf16 v[24:27], v[156:159], v[200:203], v[24:27]
	v_mfma_f32_16x16x32_bf16 v[12:15], v[148:151], v[208:211], v[12:15]
	v_mfma_f32_16x16x32_bf16 v[8:11], v[156:159], v[208:211], v[8:11]
	s_setprio 0
	s_setprio 1
	v_mfma_f32_16x16x32_bf16 v[52:55], v[160:163], v[176:179], 0
	v_mfma_f32_16x16x32_bf16 v[48:51], v[168:171], v[176:179], 0
	v_mfma_f32_16x16x32_bf16 v[36:39], v[160:163], v[184:187], 0
	v_mfma_f32_16x16x32_bf16 v[32:35], v[168:171], v[184:187], 0
	v_mfma_f32_16x16x32_bf16 v[20:23], v[160:163], v[196:199], 0
	v_mfma_f32_16x16x32_bf16 v[16:19], v[168:171], v[196:199], 0
	v_mfma_f32_16x16x32_bf16 v[4:7], v[160:163], v[204:207], 0
	v_mfma_f32_16x16x32_bf16 v[0:3], v[168:171], v[204:207], 0
	v_mfma_f32_16x16x32_bf16 v[52:55], v[164:167], v[180:183], v[52:55]
	v_mfma_f32_16x16x32_bf16 v[48:51], v[172:175], v[180:183], v[48:51]
	v_mfma_f32_16x16x32_bf16 v[36:39], v[164:167], v[192:195], v[36:39]
	v_mfma_f32_16x16x32_bf16 v[32:35], v[172:175], v[192:195], v[32:35]
	v_mfma_f32_16x16x32_bf16 v[20:23], v[164:167], v[200:203], v[20:23]
	v_mfma_f32_16x16x32_bf16 v[16:19], v[172:175], v[200:203], v[16:19]
	v_mfma_f32_16x16x32_bf16 v[4:7], v[164:167], v[208:211], v[4:7]
	v_mfma_f32_16x16x32_bf16 v[0:3], v[172:175], v[208:211], v[0:3]
	s_setprio 0
	s_barrier
	s_add_i32 s50, 0, 0x18000
	s_add_i32 s51, 0, 0x1c000
	v_add_u32_e32 v156, s50, v145
	v_add_u32_e32 v172, s51, v145
	ds_read_b128 v[138:141], v156
	ds_read_b128 v[148:151], v156 offset:1024
	ds_read_b128 v[152:155], v156 offset:2048
	ds_read_b128 v[156:159], v156 offset:3072
	ds_read_b128 v[160:163], v172
	ds_read_b128 v[164:167], v172 offset:1024
	ds_read_b128 v[168:171], v172 offset:2048
	ds_read_b128 v[172:175], v172 offset:3072
	s_add_u32 s28, s28, 0x40000
	s_addc_u32 s29, s29, 0
	s_mov_b32 m0, s23
	v_lshl_add_u64 v[218:219], s[28:29], 0, v[132:133]
	ds_read_b128 v[176:179], v147 offset:32768
	ds_read_b128 v[180:183], v147 offset:33792
	ds_read_b128 v[184:187], v147 offset:34816
	ds_read_b128 v[192:195], v147 offset:35840
	ds_read_b128 v[196:199], v147 offset:36864
	ds_read_b128 v[200:203], v147 offset:37888
	ds_read_b128 v[204:207], v147 offset:38912
	ds_read_b128 v[208:211], v147 offset:39936
	global_load_lds_dwordx4 v[218:219], off
	v_lshl_add_u64 v[218:219], s[28:29], 0, v[130:131]
	s_mov_b32 m0, s33
	s_nop 0
	global_load_lds_dwordx4 v[218:219], off
	s_waitcnt vmcnt(8)
	s_waitcnt lgkmcnt(0)
	s_barrier
	s_setprio 1
	s_waitcnt lgkmcnt(0)
	v_mfma_f32_16x16x32_bf16 v[124:127], v[138:141], v[176:179], v[124:127]
	v_mfma_f32_16x16x32_bf16 v[120:123], v[152:155], v[176:179], v[120:123]
	v_mfma_f32_16x16x32_bf16 v[108:111], v[138:141], v[184:187], v[108:111]
	v_mfma_f32_16x16x32_bf16 v[104:107], v[152:155], v[184:187], v[104:107]
	v_mfma_f32_16x16x32_bf16 v[92:95], v[138:141], v[196:199], v[92:95]
	v_mfma_f32_16x16x32_bf16 v[88:91], v[152:155], v[196:199], v[88:91]
	v_mfma_f32_16x16x32_bf16 v[76:79], v[138:141], v[204:207], v[76:79]
	v_mfma_f32_16x16x32_bf16 v[72:75], v[152:155], v[204:207], v[72:75]
	v_mfma_f32_16x16x32_bf16 v[124:127], v[148:151], v[180:183], v[124:127]
	v_mfma_f32_16x16x32_bf16 v[120:123], v[156:159], v[180:183], v[120:123]
	v_mfma_f32_16x16x32_bf16 v[108:111], v[148:151], v[192:195], v[108:111]
	v_mfma_f32_16x16x32_bf16 v[104:107], v[156:159], v[192:195], v[104:107]
	v_mfma_f32_16x16x32_bf16 v[92:95], v[148:151], v[200:203], v[92:95]
	v_mfma_f32_16x16x32_bf16 v[88:91], v[156:159], v[200:203], v[88:91]
	v_mfma_f32_16x16x32_bf16 v[76:79], v[148:151], v[208:211], v[76:79]
	v_mfma_f32_16x16x32_bf16 v[72:75], v[156:159], v[208:211], v[72:75]
	s_setprio 0
	s_setprio 1
	v_mfma_f32_16x16x32_bf16 v[116:119], v[160:163], v[176:179], v[116:119]
	v_mfma_f32_16x16x32_bf16 v[112:115], v[168:171], v[176:179], v[112:115]
	v_mfma_f32_16x16x32_bf16 v[100:103], v[160:163], v[184:187], v[100:103]
	v_mfma_f32_16x16x32_bf16 v[96:99], v[168:171], v[184:187], v[96:99]
	v_mfma_f32_16x16x32_bf16 v[84:87], v[160:163], v[196:199], v[84:87]
	v_mfma_f32_16x16x32_bf16 v[80:83], v[168:171], v[196:199], v[80:83]
	v_mfma_f32_16x16x32_bf16 v[68:71], v[160:163], v[204:207], v[68:71]
	v_mfma_f32_16x16x32_bf16 v[64:67], v[168:171], v[204:207], v[64:67]
	v_mfma_f32_16x16x32_bf16 v[116:119], v[164:167], v[180:183], v[116:119]
	v_mfma_f32_16x16x32_bf16 v[112:115], v[172:175], v[180:183], v[112:115]
	v_mfma_f32_16x16x32_bf16 v[100:103], v[164:167], v[192:195], v[100:103]
	v_mfma_f32_16x16x32_bf16 v[96:99], v[172:175], v[192:195], v[96:99]
	v_mfma_f32_16x16x32_bf16 v[84:87], v[164:167], v[200:203], v[84:87]
	v_mfma_f32_16x16x32_bf16 v[80:83], v[172:175], v[200:203], v[80:83]
	v_mfma_f32_16x16x32_bf16 v[68:71], v[164:167], v[208:211], v[68:71]
	v_mfma_f32_16x16x32_bf16 v[64:67], v[172:175], v[208:211], v[64:67]
	s_setprio 0
	s_barrier
; #define PG8_STAGE(bufoff, gbase, voff) do { _Pragma("unroll") for (int _i = 0; _i < 2; ++_i) \
;         __builtin_amdgcn_global_load_lds((const unsigned*)((const char*)(gbase) + (voff)[_i]), (LAS unsigned*)(lds + (bufoff) + ldsw + _i * 8192), 16, 0, 0); } while (0)
; #define PG8_LDA(dst, b, h) do { _Pragma("unroll") for (int m = 0; m < 4; ++m) _Pragma("unroll") for (int k = 0; k < 2; ++k) dst[m][k] = *(const LAS bf16x8*)(lds + PG8_SA(b, h) + aoff + m * 2048 + k * 1024); } while (0)
; #define PG8_MMA(ai, bj, At, Bt) do { __builtin_amdgcn_s_setprio(1); _Pragma("unroll") for (int m = 0; m < 4; ++m) _Pragma("unroll") for (int n = 0; n < 2; ++n) _Pragma("unroll") for (int k = 0; k < 2; ++k) \
;         acc[ai][bj][m][n] = __builtin_amdgcn_mfma_f32_16x16x32_bf16(Bt[n][k], At[m][k], acc[ai][bj][m][n], 0, 0, 0); __builtin_amdgcn_s_setprio(0); } while (0)
; #define PG8_WAIT_V(n) asm volatile("s_waitcnt vmcnt(" #n ")" ::: "memory")
; #define PG8_WAIT_L(n) asm volatile("s_waitcnt lgkmcnt(" #n ")" ::: "memory")
; #define PG8_BAR __builtin_amdgcn_s_barrier()
; #define PG8_SCHED __builtin_amdgcn_sched_barrier(0)
; template <class Epi, bool ALIGN_EPI = true>
; DI void gemm_phase(int tb_, LAS unsigned char* lds, const Gemm g, const Sched& S, const Epi& E) {
;     ...
;             PG8_LDA(At, 1, 1); PG8_STAGE(PG8_SB(1, 0), b3, voffB); PG8_STAGE(PG8_SB(1, 1), b3 + hstep, voffB); PG8_STAGE(PG8_SA(1, 0), a3, voffA);
;             PG8_WAIT_V(8); PG8_WAIT_L(0); PG8_BAR; PG8_MMA(1, 0, At, B0); PG8_MMA(1, 1, At, B1); PG8_BAR; PG8_SCHED;
;         }
	s_add_i32 s28, s50, s38
	v_lshl_add_u64 v[142:143], v[142:143], 0, s[72:73]
	s_mov_b32 m0, s28
	ds_read_b128 v[176:179], v147 offset:49152
	ds_read_b128 v[180:183], v147 offset:50176
	ds_read_b128 v[184:187], v147 offset:51200
	ds_read_b128 v[192:195], v147 offset:52224
	ds_read_b128 v[196:199], v147 offset:53248
	ds_read_b128 v[200:203], v147 offset:54272
	ds_read_b128 v[204:207], v147 offset:55296
	ds_read_b128 v[208:211], v147 offset:56320
	global_load_lds_dwordx4 v[142:143], off
	s_add_i32 m0, s28, 0x2000
	s_add_u32 s26, s26, 0x40080
	v_lshl_add_u64 v[142:143], v[212:213], 0, s[72:73]
	s_addc_u32 s27, s27, 0
	s_add_i32 s28, s51, s38
	global_load_lds_dwordx4 v[142:143], off
	v_lshl_add_u64 v[142:143], s[26:27], 0, v[188:189]
	s_mov_b32 m0, s28
	s_nop 0
	global_load_lds_dwordx4 v[142:143], off
	v_lshl_add_u64 v[142:143], s[26:27], 0, v[128:129]
	s_add_i32 m0, s28, 0x2000
	s_nop 0
	global_load_lds_dwordx4 v[142:143], off
	v_lshl_add_u64 v[142:143], v[214:215], 0, s[72:73]
	s_mov_b32 m0, s42
	s_nop 0
	global_load_lds_dwordx4 v[142:143], off
	v_lshl_add_u64 v[142:143], v[216:217], 0, s[72:73]
	s_mov_b32 m0, s43
	s_nop 0
	global_load_lds_dwordx4 v[142:143], off
	s_waitcnt vmcnt(8)
	s_waitcnt lgkmcnt(0)
	s_barrier
	s_setprio 1
	s_waitcnt lgkmcnt(0)
	v_mfma_f32_16x16x32_bf16 v[60:63], v[138:141], v[176:179], v[60:63]
	v_mfma_f32_16x16x32_bf16 v[56:59], v[152:155], v[176:179], v[56:59]
	v_mfma_f32_16x16x32_bf16 v[44:47], v[138:141], v[184:187], v[44:47]
	v_mfma_f32_16x16x32_bf16 v[40:43], v[152:155], v[184:187], v[40:43]
	v_mfma_f32_16x16x32_bf16 v[28:31], v[138:141], v[196:199], v[28:31]
	v_mfma_f32_16x16x32_bf16 v[24:27], v[152:155], v[196:199], v[24:27]
	v_mfma_f32_16x16x32_bf16 v[12:15], v[138:141], v[204:207], v[12:15]
	v_mfma_f32_16x16x32_bf16 v[8:11], v[152:155], v[204:207], v[8:11]
	v_mfma_f32_16x16x32_bf16 v[60:63], v[148:151], v[180:183], v[60:63]
	v_mfma_f32_16x16x32_bf16 v[56:59], v[156:159], v[180:183], v[56:59]
	v_mfma_f32_16x16x32_bf16 v[44:47], v[148:151], v[192:195], v[44:47]
	v_mfma_f32_16x16x32_bf16 v[40:43], v[156:159], v[192:195], v[40:43]
	v_mfma_f32_16x16x32_bf16 v[28:31], v[148:151], v[200:203], v[28:31]
	v_mfma_f32_16x16x32_bf16 v[24:27], v[156:159], v[200:203], v[24:27]
	v_mfma_f32_16x16x32_bf16 v[12:15], v[148:151], v[208:211], v[12:15]
	v_mfma_f32_16x16x32_bf16 v[8:11], v[156:159], v[208:211], v[8:11]
	s_setprio 0
	s_setprio 1
	v_mfma_f32_16x16x32_bf16 v[52:55], v[160:163], v[176:179], v[52:55]
	v_mfma_f32_16x16x32_bf16 v[48:51], v[168:171], v[176:179], v[48:51]
	v_mfma_f32_16x16x32_bf16 v[36:39], v[160:163], v[184:187], v[36:39]
	v_mfma_f32_16x16x32_bf16 v[32:35], v[168:171], v[184:187], v[32:35]
	v_mfma_f32_16x16x32_bf16 v[20:23], v[160:163], v[196:199], v[20:23]
	v_mfma_f32_16x16x32_bf16 v[16:19], v[168:171], v[196:199], v[16:19]
	v_mfma_f32_16x16x32_bf16 v[4:7], v[160:163], v[204:207], v[4:7]
	v_mfma_f32_16x16x32_bf16 v[0:3], v[168:171], v[204:207], v[0:3]
	v_mfma_f32_16x16x32_bf16 v[52:55], v[164:167], v[180:183], v[52:55]
	v_mfma_f32_16x16x32_bf16 v[48:51], v[172:175], v[180:183], v[48:51]
	v_mfma_f32_16x16x32_bf16 v[36:39], v[164:167], v[192:195], v[36:39]
	v_mfma_f32_16x16x32_bf16 v[32:35], v[172:175], v[192:195], v[32:35]
	v_mfma_f32_16x16x32_bf16 v[20:23], v[164:167], v[200:203], v[20:23]
	v_mfma_f32_16x16x32_bf16 v[16:19], v[172:175], v[200:203], v[16:19]
	v_mfma_f32_16x16x32_bf16 v[4:7], v[164:167], v[208:211], v[4:7]
	v_mfma_f32_16x16x32_bf16 v[0:3], v[172:175], v[208:211], v[0:3]
	s_setprio 0
	s_barrier
	s_add_i32 s49, s49, 2
	s_add_u32 s24, s24, 0x100
	s_addc_u32 s25, s25, 0
	s_add_u32 s47, s47, 0x100
	s_addc_u32 s48, s48, 0
	s_cmp_gt_u32 s49, 13
	s_cbranch_scc1 .Lpeel_exit_6

; #define PG8_BAR __builtin_amdgcn_s_barrier()
; template <class Epi, bool ALIGN_EPI = true>
; DI void gemm_phase(int tb_, LAS unsigned char* lds, const Gemm g, const Sched& S, const Epi& E) {
;     ...
;         if constexpr (ALIGN_EPI) { if (wr == 0) PG8_BAR; }
.Lpeel_exit_6:
	s_and_b64 vcc, exec, s[10:11]
	s_cbranch_vccz .LBB0_1493
	s_barrier

; #define PG8_STAGE(bufoff, gbase, voff) do { _Pragma("unroll") for (int _i = 0; _i < 2; ++_i) \
;         __builtin_amdgcn_global_load_lds((const unsigned*)((const char*)(gbase) + (voff)[_i]), (LAS unsigned*)(lds + (bufoff) + ldsw + _i * 8192), 16, 0, 0); } while (0)
; #define PG8_LDA(dst, b, h) do { _Pragma("unroll") for (int m = 0; m < 4; ++m) _Pragma("unroll") for (int k = 0; k < 2; ++k) dst[m][k] = *(const LAS bf16x8*)(lds + PG8_SA(b, h) + aoff + m * 2048 + k * 1024); } while (0)
; #define PG8_LDB(dst, b, h) do { _Pragma("unroll") for (int n = 0; n < 2; ++n) _Pragma("unroll") for (int k = 0; k < 2; ++k) dst[n][k] = *(const LAS bf16x8*)(lds + PG8_SB(b, h) + boff + n * 2048 + k * 1024); } while (0)
; #define PG8_WAIT_V(n) asm volatile("s_waitcnt vmcnt(" #n ")" ::: "memory")
; #define PG8_WAIT_L(n) asm volatile("s_waitcnt lgkmcnt(" #n ")" ::: "memory")
; #define PG8_BAR __builtin_amdgcn_s_barrier()
; #define PG8_SCHED __builtin_amdgcn_sched_barrier(0)
; template <class Epi, bool ALIGN_EPI = true>
; DI void gemm_phase(int tb_, LAS unsigned char* lds, const Gemm g, const Sched& S, const Epi& E) {
;     ...
;         const bool has_next = S.next(ui + 1, nxt);
;         const char* nA = has_next ? PG8_APTR(nxt) : cA; const char* nB = has_next ? PG8_BPTR(nxt) : cB;
;         const int nt = cur.nt;
;         for (int t = 0; t < nt; t += 2) {
;             const bool last = (t == nt - 2);
;             const char* a1 = cA + (size_t)(t + 1) * kstep;
;             const char* a2 = last ? nA : cA + (size_t)(t + 2) * kstep; const char* b2 = last ? nB : cB + (size_t)(t + 2) * kstep;
;             const char* a3 = a2 + kstep; const char* b3 = b2 + kstep;
;             PG8_LDB(B0, 0, 0); PG8_LDB(B1, 0, 1); PG8_SCHED; PG8_LDA(At, 0, 0); PG8_STAGE(PG8_SA(1, 1), a1 + hstep, voffA);
;             PG8_WAIT_V(8); PG8_WAIT_L(0); PG8_BAR; PG8_MMA(0, 0, At, B0); PG8_MMA(0, 1, At, B1); PG8_BAR; PG8_SCHED;
;             PG8_LDA(At, 0, 1); PG8_STAGE(PG8_SB(0, 0), b2, voffB); PG8_STAGE(PG8_SB(0, 1), b2 + hstep, voffB); PG8_STAGE(PG8_SA(0, 0), a2, voffA);
;     ...
;         for (int a = 0; a < 2; ++a)
; #pragma unroll
;             for (int b = 0; b < 2; ++b)
; #pragma unroll
;                 for (int m = 0; m < 4; ++m)
; #pragma unroll
;                     for (int n = 0; n < 2; ++n) acc[a][b][m][n] = (f32x4){0.f, 0.f, 0.f, 0.f};
.LBB0_1571:
	s_add_u32 s8, s30, 0x20080
	s_addc_u32 s9, s31, 0
	s_add_u32 s19, s34, 0x100
	s_addc_u32 s21, s35, 0
	s_mov_b32 s27, -2
	s_add_u32 s29, s8, 0xfffe0080
	s_addc_u32 s30, s9, -1
	s_add_i32 s33, 0, 0x10000
	s_cmp_eq_u32 s27, 4
	s_cselect_b32 s35, s23, s30
	s_cselect_b32 s34, s22, s29
	s_cselect_b32 s31, s25, s21
	s_cselect_b32 s30, s24, s19
	s_add_i32 s29, 0, 0x14000
	v_add_u32_e32 v140, s33, v181
	v_add_u32_e32 v156, s29, v181
	ds_read_b128 v[128:131], v140
	ds_read_b128 v[132:135], v140 offset:1024
	ds_read_b128 v[136:139], v140 offset:2048
	ds_read_b128 v[140:143], v140 offset:3072
	ds_read_b128 v[144:147], v156
	ds_read_b128 v[148:151], v156 offset:1024
	ds_read_b128 v[152:155], v156 offset:2048
	ds_read_b128 v[156:159], v156 offset:3072
	v_lshl_add_u64 v[160:161], s[8:9], 0, v[168:169]
	s_add_i32 m0, s43, 0xc000
	ds_read_b128 v[172:175], v183
	ds_read_b128 v[176:179], v183 offset:1024
	ds_read_b128 v[184:187], v183 offset:2048
	ds_read_b128 v[192:195], v183 offset:3072
	ds_read_b128 v[196:199], v183 offset:4096
	ds_read_b128 v[200:203], v183 offset:5120
	ds_read_b128 v[204:207], v183 offset:6144
	ds_read_b128 v[208:211], v183 offset:7168
	global_load_lds_dwordx4 v[160:161], off
	v_lshl_add_u64 v[160:161], s[8:9], 0, v[170:171]
	s_add_i32 m0, s43, 0xe000
	s_nop 0
	global_load_lds_dwordx4 v[160:161], off
	s_waitcnt vmcnt(8)
	s_waitcnt lgkmcnt(0)
	s_barrier
	s_setprio 1
	s_waitcnt lgkmcnt(0)
	v_mfma_f32_16x16x32_bf16 v[124:127], v[128:131], v[172:175], 0
	v_mfma_f32_16x16x32_bf16 v[120:123], v[136:139], v[172:175], 0
	v_mfma_f32_16x16x32_bf16 v[108:111], v[128:131], v[184:187], 0
	v_mfma_f32_16x16x32_bf16 v[104:107], v[136:139], v[184:187], 0
	v_mfma_f32_16x16x32_bf16 v[92:95], v[128:131], v[196:199], 0
	v_mfma_f32_16x16x32_bf16 v[88:91], v[136:139], v[196:199], 0
	v_mfma_f32_16x16x32_bf16 v[76:79], v[128:131], v[204:207], 0
	v_mfma_f32_16x16x32_bf16 v[72:75], v[136:139], v[204:207], 0
	v_mfma_f32_16x16x32_bf16 v[124:127], v[132:135], v[176:179], v[124:127]
	v_mfma_f32_16x16x32_bf16 v[120:123], v[140:143], v[176:179], v[120:123]
	v_mfma_f32_16x16x32_bf16 v[108:111], v[132:135], v[192:195], v[108:111]
	v_mfma_f32_16x16x32_bf16 v[104:107], v[140:143], v[192:195], v[104:107]
	v_mfma_f32_16x16x32_bf16 v[92:95], v[132:135], v[200:203], v[92:95]
	v_mfma_f32_16x16x32_bf16 v[88:91], v[140:143], v[200:203], v[88:91]
	v_mfma_f32_16x16x32_bf16 v[76:79], v[132:135], v[208:211], v[76:79]
	v_mfma_f32_16x16x32_bf16 v[72:75], v[140:143], v[208:211], v[72:75]
	s_setprio 0
	s_setprio 1
	v_mfma_f32_16x16x32_bf16 v[116:119], v[144:147], v[172:175], 0
	v_mfma_f32_16x16x32_bf16 v[112:115], v[152:155], v[172:175], 0
	v_mfma_f32_16x16x32_bf16 v[100:103], v[144:147], v[184:187], 0
	v_mfma_f32_16x16x32_bf16 v[96:99], v[152:155], v[184:187], 0
	v_mfma_f32_16x16x32_bf16 v[84:87], v[144:147], v[196:199], 0
	v_mfma_f32_16x16x32_bf16 v[80:83], v[152:155], v[196:199], 0
	v_mfma_f32_16x16x32_bf16 v[68:71], v[144:147], v[204:207], 0
	v_mfma_f32_16x16x32_bf16 v[64:67], v[152:155], v[204:207], 0
	v_mfma_f32_16x16x32_bf16 v[116:119], v[148:151], v[176:179], v[116:119]
	v_mfma_f32_16x16x32_bf16 v[112:115], v[156:159], v[176:179], v[112:115]
	v_mfma_f32_16x16x32_bf16 v[100:103], v[148:151], v[192:195], v[100:103]
	v_mfma_f32_16x16x32_bf16 v[96:99], v[156:159], v[192:195], v[96:99]
	v_mfma_f32_16x16x32_bf16 v[84:87], v[148:151], v[200:203], v[84:87]
	v_mfma_f32_16x16x32_bf16 v[80:83], v[156:159], v[200:203], v[80:83]
	v_mfma_f32_16x16x32_bf16 v[68:71], v[148:151], v[208:211], v[68:71]
	v_mfma_f32_16x16x32_bf16 v[64:67], v[156:159], v[208:211], v[64:67]
	s_setprio 0
	s_barrier
	s_add_i32 s33, s33, s42
	v_lshl_add_u64 v[160:161], s[30:31], 0, v[188:189]
	s_mov_b32 m0, s33
	ds_read_b128 v[172:175], v183 offset:16384
	ds_read_b128 v[176:179], v183 offset:17408
	ds_read_b128 v[184:187], v183 offset:18432
	ds_read_b128 v[192:195], v183 offset:19456
	ds_read_b128 v[196:199], v183 offset:20480
	ds_read_b128 v[200:203], v183 offset:21504
	ds_read_b128 v[204:207], v183 offset:22528
	ds_read_b128 v[208:211], v183 offset:23552
	global_load_lds_dwordx4 v[160:161], off
	s_add_i32 m0, s33, 0x2000
	s_add_u32 s60, s30, 0x20000
	v_lshl_add_u64 v[212:213], s[30:31], 0, v[166:167]
	s_addc_u32 s61, s31, 0
	s_add_i32 s29, s29, s42
	global_load_lds_dwordx4 v[212:213], off
	v_lshl_add_u64 v[214:215], s[60:61], 0, v[188:189]
	s_mov_b32 m0, s29
	v_lshl_add_u64 v[216:217], s[34:35], 0, v[164:165]
	global_load_lds_dwordx4 v[214:215], off
	v_lshl_add_u64 v[214:215], s[60:61], 0, v[166:167]
	s_add_i32 m0, s29, 0x2000
	s_nop 0
	global_load_lds_dwordx4 v[214:215], off
	v_lshl_add_u64 v[214:215], s[34:35], 0, v[162:163]
	s_mov_b32 m0, s43
	s_nop 0
	global_load_lds_dwordx4 v[214:215], off
	s_mov_b32 m0, s44
	s_nop 0
	global_load_lds_dwordx4 v[216:217], off
	s_waitcnt vmcnt(8)
	s_waitcnt lgkmcnt(0)
	s_barrier
; #define PG8_STAGE(bufoff, gbase, voff) do { _Pragma("unroll") for (int _i = 0; _i < 2; ++_i) \
;         __builtin_amdgcn_global_load_lds((const unsigned*)((const char*)(gbase) + (voff)[_i]), (LAS unsigned*)(lds + (bufoff) + ldsw + _i * 8192), 16, 0, 0); } while (0)
; #define PG8_LDA(dst, b, h) do { _Pragma("unroll") for (int m = 0; m < 4; ++m) _Pragma("unroll") for (int k = 0; k < 2; ++k) dst[m][k] = *(const LAS bf16x8*)(lds + PG8_SA(b, h) + aoff + m * 2048 + k * 1024); } while (0)
; #define PG8_LDB(dst, b, h) do { _Pragma("unroll") for (int n = 0; n < 2; ++n) _Pragma("unroll") for (int k = 0; k < 2; ++k) dst[n][k] = *(const LAS bf16x8*)(lds + PG8_SB(b, h) + boff + n * 2048 + k * 1024); } while (0)
; #define PG8_MMA(ai, bj, At, Bt) do { __builtin_amdgcn_s_setprio(1); _Pragma("unroll") for (int m = 0; m < 4; ++m) _Pragma("unroll") for (int n = 0; n < 2; ++n) _Pragma("unroll") for (int k = 0; k < 2; ++k) \
;         acc[ai][bj][m][n] = __builtin_amdgcn_mfma_f32_16x16x32_bf16(Bt[n][k], At[m][k], acc[ai][bj][m][n], 0, 0, 0); __builtin_amdgcn_s_setprio(0); } while (0)
; #define PG8_WAIT_V(n) asm volatile("s_waitcnt vmcnt(" #n ")" ::: "memory")
; #define PG8_WAIT_L(n) asm volatile("s_waitcnt lgkmcnt(" #n ")" ::: "memory")
; #define PG8_BAR __builtin_amdgcn_s_barrier()
; #define PG8_SCHED __builtin_amdgcn_sched_barrier(0)
; template <class Epi, bool ALIGN_EPI = true>
; DI void gemm_phase(int tb_, LAS unsigned char* lds, const Gemm g, const Sched& S, const Epi& E) {
;     ...
;             PG8_WAIT_V(8); PG8_WAIT_L(0); PG8_BAR; PG8_MMA(1, 0, At, B0); PG8_MMA(1, 1, At, B1); PG8_BAR; PG8_SCHED;
;             PG8_LDB(B0, 1, 0); PG8_LDB(B1, 1, 1); PG8_SCHED; PG8_LDA(At, 1, 0); PG8_STAGE(PG8_SA(0, 1), a2 + hstep, voffA);
;             PG8_WAIT_V(8); PG8_WAIT_L(0); PG8_BAR; PG8_MMA(0, 0, At, B0); PG8_MMA(0, 1, At, B1); PG8_BAR; PG8_SCHED;
	s_setprio 1
	s_waitcnt lgkmcnt(0)
	v_mfma_f32_16x16x32_bf16 v[60:63], v[128:131], v[172:175], 0
	v_mfma_f32_16x16x32_bf16 v[56:59], v[136:139], v[172:175], 0
	v_mfma_f32_16x16x32_bf16 v[44:47], v[128:131], v[184:187], 0
	v_mfma_f32_16x16x32_bf16 v[40:43], v[136:139], v[184:187], 0
	v_mfma_f32_16x16x32_bf16 v[28:31], v[128:131], v[196:199], 0
	v_mfma_f32_16x16x32_bf16 v[24:27], v[136:139], v[196:199], 0
	v_mfma_f32_16x16x32_bf16 v[12:15], v[128:131], v[204:207], 0
	v_mfma_f32_16x16x32_bf16 v[8:11], v[136:139], v[204:207], 0
	v_mfma_f32_16x16x32_bf16 v[60:63], v[132:135], v[176:179], v[60:63]
	v_mfma_f32_16x16x32_bf16 v[56:59], v[140:143], v[176:179], v[56:59]
	v_mfma_f32_16x16x32_bf16 v[44:47], v[132:135], v[192:195], v[44:47]
	v_mfma_f32_16x16x32_bf16 v[40:43], v[140:143], v[192:195], v[40:43]
	v_mfma_f32_16x16x32_bf16 v[28:31], v[132:135], v[200:203], v[28:31]
	v_mfma_f32_16x16x32_bf16 v[24:27], v[140:143], v[200:203], v[24:27]
	v_mfma_f32_16x16x32_bf16 v[12:15], v[132:135], v[208:211], v[12:15]
	v_mfma_f32_16x16x32_bf16 v[8:11], v[140:143], v[208:211], v[8:11]
	s_setprio 0
	s_setprio 1
	v_mfma_f32_16x16x32_bf16 v[52:55], v[144:147], v[172:175], 0
	v_mfma_f32_16x16x32_bf16 v[48:51], v[152:155], v[172:175], 0
	v_mfma_f32_16x16x32_bf16 v[36:39], v[144:147], v[184:187], 0
	v_mfma_f32_16x16x32_bf16 v[32:35], v[152:155], v[184:187], 0
	v_mfma_f32_16x16x32_bf16 v[20:23], v[144:147], v[196:199], 0
	v_mfma_f32_16x16x32_bf16 v[16:19], v[152:155], v[196:199], 0
	v_mfma_f32_16x16x32_bf16 v[4:7], v[144:147], v[204:207], 0
	v_mfma_f32_16x16x32_bf16 v[0:3], v[152:155], v[204:207], 0
	v_mfma_f32_16x16x32_bf16 v[52:55], v[148:151], v[176:179], v[52:55]
	v_mfma_f32_16x16x32_bf16 v[48:51], v[156:159], v[176:179], v[48:51]
	v_mfma_f32_16x16x32_bf16 v[36:39], v[148:151], v[192:195], v[36:39]
	v_mfma_f32_16x16x32_bf16 v[32:35], v[156:159], v[192:195], v[32:35]
	v_mfma_f32_16x16x32_bf16 v[20:23], v[148:151], v[200:203], v[20:23]
	v_mfma_f32_16x16x32_bf16 v[16:19], v[156:159], v[200:203], v[16:19]
	v_mfma_f32_16x16x32_bf16 v[4:7], v[148:151], v[208:211], v[4:7]
	v_mfma_f32_16x16x32_bf16 v[0:3], v[156:159], v[208:211], v[0:3]
	s_setprio 0
	s_barrier
	s_add_i32 s29, 0, 0x18000
	s_add_i32 s33, 0, 0x1c000
	v_add_u32_e32 v140, s29, v181
	v_add_u32_e32 v156, s33, v181
	ds_read_b128 v[128:131], v140
	ds_read_b128 v[132:135], v140 offset:1024
	ds_read_b128 v[136:139], v140 offset:2048
	ds_read_b128 v[140:143], v140 offset:3072
	ds_read_b128 v[144:147], v156
	ds_read_b128 v[148:151], v156 offset:1024
	ds_read_b128 v[152:155], v156 offset:2048
	ds_read_b128 v[156:159], v156 offset:3072
	s_add_u32 s34, s34, 0x20000
	s_addc_u32 s35, s35, 0
	s_mov_b32 m0, s45
	v_lshl_add_u64 v[218:219], s[34:35], 0, v[162:163]
	ds_read_b128 v[172:175], v183 offset:32768
	ds_read_b128 v[176:179], v183 offset:33792
	ds_read_b128 v[184:187], v183 offset:34816
	ds_read_b128 v[192:195], v183 offset:35840
	ds_read_b128 v[196:199], v183 offset:36864
	ds_read_b128 v[200:203], v183 offset:37888
	ds_read_b128 v[204:207], v183 offset:38912
	ds_read_b128 v[208:211], v183 offset:39936
	global_load_lds_dwordx4 v[218:219], off
	v_lshl_add_u64 v[218:219], s[34:35], 0, v[164:165]
	s_mov_b32 m0, s46
	s_nop 0
	global_load_lds_dwordx4 v[218:219], off
	s_waitcnt vmcnt(8)
	s_waitcnt lgkmcnt(0)
	s_barrier
	s_setprio 1
	s_waitcnt lgkmcnt(0)
	v_mfma_f32_16x16x32_bf16 v[124:127], v[128:131], v[172:175], v[124:127]
	v_mfma_f32_16x16x32_bf16 v[120:123], v[136:139], v[172:175], v[120:123]
	v_mfma_f32_16x16x32_bf16 v[108:111], v[128:131], v[184:187], v[108:111]
	v_mfma_f32_16x16x32_bf16 v[104:107], v[136:139], v[184:187], v[104:107]
	v_mfma_f32_16x16x32_bf16 v[92:95], v[128:131], v[196:199], v[92:95]
	v_mfma_f32_16x16x32_bf16 v[88:91], v[136:139], v[196:199], v[88:91]
	v_mfma_f32_16x16x32_bf16 v[76:79], v[128:131], v[204:207], v[76:79]
	v_mfma_f32_16x16x32_bf16 v[72:75], v[136:139], v[204:207], v[72:75]
	v_mfma_f32_16x16x32_bf16 v[124:127], v[132:135], v[176:179], v[124:127]
	v_mfma_f32_16x16x32_bf16 v[120:123], v[140:143], v[176:179], v[120:123]
	v_mfma_f32_16x16x32_bf16 v[108:111], v[132:135], v[192:195], v[108:111]
	v_mfma_f32_16x16x32_bf16 v[104:107], v[140:143], v[192:195], v[104:107]
	v_mfma_f32_16x16x32_bf16 v[92:95], v[132:135], v[200:203], v[92:95]
	v_mfma_f32_16x16x32_bf16 v[88:91], v[140:143], v[200:203], v[88:91]
	v_mfma_f32_16x16x32_bf16 v[76:79], v[132:135], v[208:211], v[76:79]
	v_mfma_f32_16x16x32_bf16 v[72:75], v[140:143], v[208:211], v[72:75]
	s_setprio 0
	s_setprio 1
	v_mfma_f32_16x16x32_bf16 v[116:119], v[144:147], v[172:175], v[116:119]
	v_mfma_f32_16x16x32_bf16 v[112:115], v[152:155], v[172:175], v[112:115]
	v_mfma_f32_16x16x32_bf16 v[100:103], v[144:147], v[184:187], v[100:103]
	v_mfma_f32_16x16x32_bf16 v[96:99], v[152:155], v[184:187], v[96:99]
	v_mfma_f32_16x16x32_bf16 v[84:87], v[144:147], v[196:199], v[84:87]
	v_mfma_f32_16x16x32_bf16 v[80:83], v[152:155], v[196:199], v[80:83]
	v_mfma_f32_16x16x32_bf16 v[68:71], v[144:147], v[204:207], v[68:71]
	v_mfma_f32_16x16x32_bf16 v[64:67], v[152:155], v[204:207], v[64:67]
	v_mfma_f32_16x16x32_bf16 v[116:119], v[148:151], v[176:179], v[116:119]
	v_mfma_f32_16x16x32_bf16 v[112:115], v[156:159], v[176:179], v[112:115]
	v_mfma_f32_16x16x32_bf16 v[100:103], v[148:151], v[192:195], v[100:103]
	v_mfma_f32_16x16x32_bf16 v[96:99], v[156:159], v[192:195], v[96:99]
	v_mfma_f32_16x16x32_bf16 v[84:87], v[148:151], v[200:203], v[84:87]
	v_mfma_f32_16x16x32_bf16 v[80:83], v[156:159], v[200:203], v[80:83]
	v_mfma_f32_16x16x32_bf16 v[68:71], v[148:151], v[208:211], v[68:71]
	v_mfma_f32_16x16x32_bf16 v[64:67], v[156:159], v[208:211], v[64:67]
	s_setprio 0
	s_barrier
; #define PG8_STAGE(bufoff, gbase, voff) do { _Pragma("unroll") for (int _i = 0; _i < 2; ++_i) \
;         __builtin_amdgcn_global_load_lds((const unsigned*)((const char*)(gbase) + (voff)[_i]), (LAS unsigned*)(lds + (bufoff) + ldsw + _i * 8192), 16, 0, 0); } while (0)
; #define PG8_LDA(dst, b, h) do { _Pragma("unroll") for (int m = 0; m < 4; ++m) _Pragma("unroll") for (int k = 0; k < 2; ++k) dst[m][k] = *(const LAS bf16x8*)(lds + PG8_SA(b, h) + aoff + m * 2048 + k * 1024); } while (0)
; #define PG8_MMA(ai, bj, At, Bt) do { __builtin_amdgcn_s_setprio(1); _Pragma("unroll") for (int m = 0; m < 4; ++m) _Pragma("unroll") for (int n = 0; n < 2; ++n) _Pragma("unroll") for (int k = 0; k < 2; ++k) \
;         acc[ai][bj][m][n] = __builtin_amdgcn_mfma_f32_16x16x32_bf16(Bt[n][k], At[m][k], acc[ai][bj][m][n], 0, 0, 0); __builtin_amdgcn_s_setprio(0); } while (0)
; #define PG8_WAIT_V(n) asm volatile("s_waitcnt vmcnt(" #n ")" ::: "memory")
; #define PG8_WAIT_L(n) asm volatile("s_waitcnt lgkmcnt(" #n ")" ::: "memory")
; #define PG8_BAR __builtin_amdgcn_s_barrier()
; #define PG8_SCHED __builtin_amdgcn_sched_barrier(0)
; template <class Epi, bool ALIGN_EPI = true>
; DI void gemm_phase(int tb_, LAS unsigned char* lds, const Gemm g, const Sched& S, const Epi& E) {
;     ...
;             PG8_LDA(At, 1, 1); PG8_STAGE(PG8_SB(1, 0), b3, voffB); PG8_STAGE(PG8_SB(1, 1), b3 + hstep, voffB); PG8_STAGE(PG8_SA(1, 0), a3, voffA);
;             PG8_WAIT_V(8); PG8_WAIT_L(0); PG8_BAR; PG8_MMA(1, 0, At, B0); PG8_MMA(1, 1, At, B1); PG8_BAR; PG8_SCHED;
;         }
	s_add_i32 s29, s29, s42
	v_lshl_add_u64 v[160:161], v[160:161], 0, s[72:73]
	s_mov_b32 m0, s29
	ds_read_b128 v[172:175], v183 offset:49152
	ds_read_b128 v[176:179], v183 offset:50176
	ds_read_b128 v[184:187], v183 offset:51200
	ds_read_b128 v[192:195], v183 offset:52224
	ds_read_b128 v[196:199], v183 offset:53248
	ds_read_b128 v[200:203], v183 offset:54272
	ds_read_b128 v[204:207], v183 offset:55296
	ds_read_b128 v[208:211], v183 offset:56320
	global_load_lds_dwordx4 v[160:161], off
	s_add_i32 m0, s29, 0x2000
	s_add_u32 s30, s30, 0x20080
	v_lshl_add_u64 v[160:161], v[212:213], 0, s[72:73]
	s_addc_u32 s31, s31, 0
	s_add_i32 s29, s33, s42
	global_load_lds_dwordx4 v[160:161], off
	v_lshl_add_u64 v[160:161], s[30:31], 0, v[188:189]
	s_mov_b32 m0, s29
	s_nop 0
	global_load_lds_dwordx4 v[160:161], off
	v_lshl_add_u64 v[160:161], s[30:31], 0, v[166:167]
	s_add_i32 m0, s29, 0x2000
	s_nop 0
	global_load_lds_dwordx4 v[160:161], off
	v_lshl_add_u64 v[160:161], v[214:215], 0, s[72:73]
	s_mov_b32 m0, s49
	s_nop 0
	global_load_lds_dwordx4 v[160:161], off
	v_lshl_add_u64 v[160:161], v[216:217], 0, s[72:73]
	s_mov_b32 m0, s50
	s_nop 0
	global_load_lds_dwordx4 v[160:161], off
	s_waitcnt vmcnt(8)
	s_waitcnt lgkmcnt(0)
	s_barrier
	s_setprio 1
	s_waitcnt lgkmcnt(0)
	v_mfma_f32_16x16x32_bf16 v[60:63], v[128:131], v[172:175], v[60:63]
	v_mfma_f32_16x16x32_bf16 v[56:59], v[136:139], v[172:175], v[56:59]
	v_mfma_f32_16x16x32_bf16 v[44:47], v[128:131], v[184:187], v[44:47]
	v_mfma_f32_16x16x32_bf16 v[40:43], v[136:139], v[184:187], v[40:43]
	v_mfma_f32_16x16x32_bf16 v[28:31], v[128:131], v[196:199], v[28:31]
	v_mfma_f32_16x16x32_bf16 v[24:27], v[136:139], v[196:199], v[24:27]
	v_mfma_f32_16x16x32_bf16 v[12:15], v[128:131], v[204:207], v[12:15]
	v_mfma_f32_16x16x32_bf16 v[8:11], v[136:139], v[204:207], v[8:11]
	v_mfma_f32_16x16x32_bf16 v[60:63], v[132:135], v[176:179], v[60:63]
	v_mfma_f32_16x16x32_bf16 v[56:59], v[140:143], v[176:179], v[56:59]
	v_mfma_f32_16x16x32_bf16 v[44:47], v[132:135], v[192:195], v[44:47]
	v_mfma_f32_16x16x32_bf16 v[40:43], v[140:143], v[192:195], v[40:43]
	v_mfma_f32_16x16x32_bf16 v[28:31], v[132:135], v[200:203], v[28:31]
	v_mfma_f32_16x16x32_bf16 v[24:27], v[140:143], v[200:203], v[24:27]
	v_mfma_f32_16x16x32_bf16 v[12:15], v[132:135], v[208:211], v[12:15]
	v_mfma_f32_16x16x32_bf16 v[8:11], v[140:143], v[208:211], v[8:11]
	s_setprio 0
	s_setprio 1
	v_mfma_f32_16x16x32_bf16 v[52:55], v[144:147], v[172:175], v[52:55]
	v_mfma_f32_16x16x32_bf16 v[48:51], v[152:155], v[172:175], v[48:51]
	v_mfma_f32_16x16x32_bf16 v[36:39], v[144:147], v[184:187], v[36:39]
	v_mfma_f32_16x16x32_bf16 v[32:35], v[152:155], v[184:187], v[32:35]
	v_mfma_f32_16x16x32_bf16 v[20:23], v[144:147], v[196:199], v[20:23]
	v_mfma_f32_16x16x32_bf16 v[16:19], v[152:155], v[196:199], v[16:19]
	v_mfma_f32_16x16x32_bf16 v[4:7], v[144:147], v[204:207], v[4:7]
	v_mfma_f32_16x16x32_bf16 v[0:3], v[152:155], v[204:207], v[0:3]
	v_mfma_f32_16x16x32_bf16 v[52:55], v[148:151], v[176:179], v[52:55]
	v_mfma_f32_16x16x32_bf16 v[48:51], v[156:159], v[176:179], v[48:51]
	v_mfma_f32_16x16x32_bf16 v[36:39], v[148:151], v[192:195], v[36:39]
	v_mfma_f32_16x16x32_bf16 v[32:35], v[156:159], v[192:195], v[32:35]
	v_mfma_f32_16x16x32_bf16 v[20:23], v[148:151], v[200:203], v[20:23]
	v_mfma_f32_16x16x32_bf16 v[16:19], v[156:159], v[200:203], v[16:19]
	v_mfma_f32_16x16x32_bf16 v[4:7], v[148:151], v[208:211], v[4:7]
	v_mfma_f32_16x16x32_bf16 v[0:3], v[156:159], v[208:211], v[0:3]
	s_setprio 0
	s_barrier
	s_add_i32 s27, s27, 2
	s_add_u32 s8, s8, 0x100
	s_addc_u32 s9, s9, 0
	s_add_u32 s19, s19, 0x100
	s_addc_u32 s21, s21, 0
	s_cmp_gt_u32 s27, 5
	s_cbranch_scc1 .Lpeel_exit_7

; #define PG8_STAGE(bufoff, gbase, voff) do { _Pragma("unroll") for (int _i = 0; _i < 2; ++_i) \
;         __builtin_amdgcn_global_load_lds((const unsigned*)((const char*)(gbase) + (voff)[_i]), (LAS unsigned*)(lds + (bufoff) + ldsw + _i * 8192), 16, 0, 0); } while (0)
; #define PG8_LDA(dst, b, h) do { _Pragma("unroll") for (int m = 0; m < 4; ++m) _Pragma("unroll") for (int k = 0; k < 2; ++k) dst[m][k] = *(const LAS bf16x8*)(lds + PG8_SA(b, h) + aoff + m * 2048 + k * 1024); } while (0)
; #define PG8_LDB(dst, b, h) do { _Pragma("unroll") for (int n = 0; n < 2; ++n) _Pragma("unroll") for (int k = 0; k < 2; ++k) dst[n][k] = *(const LAS bf16x8*)(lds + PG8_SB(b, h) + boff + n * 2048 + k * 1024); } while (0)
; #define PG8_MMA(ai, bj, At, Bt) do { __builtin_amdgcn_s_setprio(1); _Pragma("unroll") for (int m = 0; m < 4; ++m) _Pragma("unroll") for (int n = 0; n < 2; ++n) _Pragma("unroll") for (int k = 0; k < 2; ++k) \
;         acc[ai][bj][m][n] = __builtin_amdgcn_mfma_f32_16x16x32_bf16(Bt[n][k], At[m][k], acc[ai][bj][m][n], 0, 0, 0); __builtin_amdgcn_s_setprio(0); } while (0)
; #define PG8_WAIT_V(n) asm volatile("s_waitcnt vmcnt(" #n ")" ::: "memory")
; #define PG8_WAIT_L(n) asm volatile("s_waitcnt lgkmcnt(" #n ")" ::: "memory")
; #define PG8_BAR __builtin_amdgcn_s_barrier()
; #define PG8_SCHED __builtin_amdgcn_sched_barrier(0)
; template <class Epi, bool ALIGN_EPI = true>
; DI void gemm_phase(int tb_, LAS unsigned char* lds, const Gemm g, const Sched& S, const Epi& E) {
;     ...
;             const bool last = (t == nt - 2);
;             const char* a1 = cA + (size_t)(t + 1) * kstep;
;             const char* a2 = last ? nA : cA + (size_t)(t + 2) * kstep; const char* b2 = last ? nB : cB + (size_t)(t + 2) * kstep;
;             const char* a3 = a2 + kstep; const char* b3 = b2 + kstep;
;             PG8_LDB(B0, 0, 0); PG8_LDB(B1, 0, 1); PG8_SCHED; PG8_LDA(At, 0, 0); PG8_STAGE(PG8_SA(1, 1), a1 + hstep, voffA);
;             PG8_WAIT_V(8); PG8_WAIT_L(0); PG8_BAR; PG8_MMA(0, 0, At, B0); PG8_MMA(0, 1, At, B1); PG8_BAR; PG8_SCHED;
;             PG8_LDA(At, 0, 1); PG8_STAGE(PG8_SB(0, 0), b2, voffB); PG8_STAGE(PG8_SB(0, 1), b2 + hstep, voffB); PG8_STAGE(PG8_SA(0, 0), a2, voffA);
;             PG8_WAIT_V(8); PG8_WAIT_L(0); PG8_BAR; PG8_MMA(1, 0, At, B0); PG8_MMA(1, 1, At, B1); PG8_BAR; PG8_SCHED;
.LBB0_1702:
	s_add_i32 s9, s2, -2
	s_add_u32 s11, s36, 0x100
	s_addc_u32 s15, s37, 0
	s_mov_b32 s23, 0
	s_add_i32 s25, s23, 2
	s_add_u32 s36, s34, 0x100
	s_addc_u32 s37, s35, 0
	s_add_i32 s31, 0, 0x10000
	s_cmp_eq_u32 s9, s23
	s_cselect_b32 s41, s27, s37
	s_cselect_b32 s40, s26, s36
	s_cselect_b32 s39, s29, s15
	s_cselect_b32 s38, s28, s11
	s_add_i32 s23, 0, 0x14000
	s_waitcnt vmcnt(0)
	v_add_u32_e32 v104, s31, v192
	v_add_u32_e32 v186, s23, v192
	ds_read_b128 v[80:83], v104
	ds_read_b128 v[88:91], v104 offset:1024
	ds_read_b128 v[96:99], v104 offset:2048
	ds_read_b128 v[104:107], v104 offset:3072
	ds_read_b128 v[182:185], v186
	ds_read_b128 v[196:199], v186 offset:1024
	ds_read_b128 v[200:203], v186 offset:2048
	ds_read_b128 v[204:207], v186 offset:3072
	v_lshl_add_u64 v[186:187], s[34:35], 0, v[178:179]
	s_add_i32 m0, s51, 0xc000
	ds_read_b128 v[208:211], v194
	ds_read_b128 v[212:215], v194 offset:1024
	ds_read_b128 v[216:219], v194 offset:2048
	ds_read_b128 v[220:223], v194 offset:3072
	ds_read_b128 v[224:227], v194 offset:4096
	ds_read_b128 v[242:245], v194 offset:5120
	ds_read_b128 v[246:249], v194 offset:6144
	ds_read_b128 v[250:253], v194 offset:7168
	global_load_lds_dwordx4 v[186:187], off
	v_lshl_add_u64 v[186:187], s[34:35], 0, v[180:181]
	s_add_i32 m0, s51, 0xe000
	s_nop 0
	global_load_lds_dwordx4 v[186:187], off
	s_waitcnt vmcnt(8)
	s_waitcnt lgkmcnt(0)
	s_barrier
	s_setprio 1
	s_waitcnt lgkmcnt(0)
	v_mfma_f32_16x16x32_bf16 v[140:143], v[80:83], v[208:211], 0
	v_mfma_f32_16x16x32_bf16 v[136:139], v[96:99], v[208:211], 0
	v_mfma_f32_16x16x32_bf16 v[124:127], v[80:83], v[216:219], 0
	v_mfma_f32_16x16x32_bf16 v[120:123], v[96:99], v[216:219], 0
	v_mfma_f32_16x16x32_bf16 v[108:111], v[80:83], v[224:227], 0
	v_mfma_f32_16x16x32_bf16 v[100:103], v[96:99], v[224:227], 0
	v_mfma_f32_16x16x32_bf16 v[76:79], v[80:83], v[246:249], 0
	v_mfma_f32_16x16x32_bf16 v[72:75], v[96:99], v[246:249], 0
	v_mfma_f32_16x16x32_bf16 v[140:143], v[88:91], v[212:215], v[140:143]
	v_mfma_f32_16x16x32_bf16 v[136:139], v[104:107], v[212:215], v[136:139]
	v_mfma_f32_16x16x32_bf16 v[124:127], v[88:91], v[220:223], v[124:127]
	v_mfma_f32_16x16x32_bf16 v[120:123], v[104:107], v[220:223], v[120:123]
	v_mfma_f32_16x16x32_bf16 v[108:111], v[88:91], v[242:245], v[108:111]
	v_mfma_f32_16x16x32_bf16 v[100:103], v[104:107], v[242:245], v[100:103]
	v_mfma_f32_16x16x32_bf16 v[76:79], v[88:91], v[250:253], v[76:79]
	v_mfma_f32_16x16x32_bf16 v[72:75], v[104:107], v[250:253], v[72:75]
	s_setprio 0
	s_setprio 1
	v_mfma_f32_16x16x32_bf16 v[132:135], v[182:185], v[208:211], 0
	v_mfma_f32_16x16x32_bf16 v[128:131], v[200:203], v[208:211], 0
	v_mfma_f32_16x16x32_bf16 v[116:119], v[182:185], v[216:219], 0
	v_mfma_f32_16x16x32_bf16 v[112:115], v[200:203], v[216:219], 0
	v_mfma_f32_16x16x32_bf16 v[92:95], v[182:185], v[224:227], 0
	v_mfma_f32_16x16x32_bf16 v[84:87], v[200:203], v[224:227], 0
	v_mfma_f32_16x16x32_bf16 v[68:71], v[182:185], v[246:249], 0
	v_mfma_f32_16x16x32_bf16 v[64:67], v[200:203], v[246:249], 0
	v_mfma_f32_16x16x32_bf16 v[132:135], v[196:199], v[212:215], v[132:135]
	v_mfma_f32_16x16x32_bf16 v[128:131], v[204:207], v[212:215], v[128:131]
	v_mfma_f32_16x16x32_bf16 v[116:119], v[196:199], v[220:223], v[116:119]
	v_mfma_f32_16x16x32_bf16 v[112:115], v[204:207], v[220:223], v[112:115]
	v_mfma_f32_16x16x32_bf16 v[92:95], v[196:199], v[242:245], v[92:95]
	v_mfma_f32_16x16x32_bf16 v[84:87], v[204:207], v[242:245], v[84:87]
	v_mfma_f32_16x16x32_bf16 v[68:71], v[196:199], v[250:253], v[68:71]
	v_mfma_f32_16x16x32_bf16 v[64:67], v[204:207], v[250:253], v[64:67]
	s_setprio 0
	s_barrier
	s_add_i32 s31, s31, s50
	v_lshl_add_u64 v[186:187], s[38:39], 0, v[188:189]
	s_mov_b32 m0, s31
	ds_read_b128 v[208:211], v194 offset:16384
	ds_read_b128 v[212:215], v194 offset:17408
	ds_read_b128 v[216:219], v194 offset:18432
	ds_read_b128 v[220:223], v194 offset:19456
	ds_read_b128 v[224:227], v194 offset:20480
	ds_read_b128 v[242:245], v194 offset:21504
	ds_read_b128 v[246:249], v194 offset:22528
	ds_read_b128 v[250:253], v194 offset:23552
	global_load_lds_dwordx4 v[186:187], off
	s_add_i32 m0, s31, 0x2000
	s_add_u32 s34, s38, 0x40000
	v_lshl_add_u64 v[228:229], s[38:39], 0, v[144:145]
	s_addc_u32 s35, s39, 0
	s_add_i32 s23, s23, s50
	global_load_lds_dwordx4 v[228:229], off
	v_lshl_add_u64 v[232:233], s[34:35], 0, v[188:189]
	s_mov_b32 m0, s23
	v_lshl_add_u64 v[234:235], s[40:41], 0, v[144:145]
	global_load_lds_dwordx4 v[232:233], off
	v_lshl_add_u64 v[232:233], s[34:35], 0, v[144:145]
	s_add_i32 m0, s23, 0x2000
	s_nop 0
	global_load_lds_dwordx4 v[232:233], off
	v_lshl_add_u64 v[232:233], s[40:41], 0, v[188:189]
	s_mov_b32 m0, s51
	s_nop 0
	global_load_lds_dwordx4 v[232:233], off
	s_mov_b32 m0, s54
	s_nop 0
	global_load_lds_dwordx4 v[234:235], off
	s_waitcnt vmcnt(8)
	s_waitcnt lgkmcnt(0)
	s_barrier
; #define PG8_STAGE(bufoff, gbase, voff) do { _Pragma("unroll") for (int _i = 0; _i < 2; ++_i) \
;         __builtin_amdgcn_global_load_lds((const unsigned*)((const char*)(gbase) + (voff)[_i]), (LAS unsigned*)(lds + (bufoff) + ldsw + _i * 8192), 16, 0, 0); } while (0)
; #define PG8_LDA(dst, b, h) do { _Pragma("unroll") for (int m = 0; m < 4; ++m) _Pragma("unroll") for (int k = 0; k < 2; ++k) dst[m][k] = *(const LAS bf16x8*)(lds + PG8_SA(b, h) + aoff + m * 2048 + k * 1024); } while (0)
; #define PG8_LDB(dst, b, h) do { _Pragma("unroll") for (int n = 0; n < 2; ++n) _Pragma("unroll") for (int k = 0; k < 2; ++k) dst[n][k] = *(const LAS bf16x8*)(lds + PG8_SB(b, h) + boff + n * 2048 + k * 1024); } while (0)
; #define PG8_MMA(ai, bj, At, Bt) do { __builtin_amdgcn_s_setprio(1); _Pragma("unroll") for (int m = 0; m < 4; ++m) _Pragma("unroll") for (int n = 0; n < 2; ++n) _Pragma("unroll") for (int k = 0; k < 2; ++k) \
;         acc[ai][bj][m][n] = __builtin_amdgcn_mfma_f32_16x16x32_bf16(Bt[n][k], At[m][k], acc[ai][bj][m][n], 0, 0, 0); __builtin_amdgcn_s_setprio(0); } while (0)
; #define PG8_WAIT_V(n) asm volatile("s_waitcnt vmcnt(" #n ")" ::: "memory")
; #define PG8_WAIT_L(n) asm volatile("s_waitcnt lgkmcnt(" #n ")" ::: "memory")
; #define PG8_BAR __builtin_amdgcn_s_barrier()
; #define PG8_SCHED __builtin_amdgcn_sched_barrier(0)
; template <class Epi, bool ALIGN_EPI = true>
; DI void gemm_phase(int tb_, LAS unsigned char* lds, const Gemm g, const Sched& S, const Epi& E) {
;     ...
;             PG8_WAIT_V(8); PG8_WAIT_L(0); PG8_BAR; PG8_MMA(1, 0, At, B0); PG8_MMA(1, 1, At, B1); PG8_BAR; PG8_SCHED;
;             PG8_LDB(B0, 1, 0); PG8_LDB(B1, 1, 1); PG8_SCHED; PG8_LDA(At, 1, 0); PG8_STAGE(PG8_SA(0, 1), a2 + hstep, voffA);
;             PG8_WAIT_V(8); PG8_WAIT_L(0); PG8_BAR; PG8_MMA(0, 0, At, B0); PG8_MMA(0, 1, At, B1); PG8_BAR; PG8_SCHED;
	s_setprio 1
	s_waitcnt lgkmcnt(0)
	v_mfma_f32_16x16x32_bf16 v[60:63], v[80:83], v[208:211], 0
	v_mfma_f32_16x16x32_bf16 v[56:59], v[96:99], v[208:211], 0
	v_mfma_f32_16x16x32_bf16 v[44:47], v[80:83], v[216:219], 0
	v_mfma_f32_16x16x32_bf16 v[40:43], v[96:99], v[216:219], 0
	v_mfma_f32_16x16x32_bf16 v[28:31], v[80:83], v[224:227], 0
	v_mfma_f32_16x16x32_bf16 v[24:27], v[96:99], v[224:227], 0
	v_mfma_f32_16x16x32_bf16 v[12:15], v[80:83], v[246:249], 0
	v_mfma_f32_16x16x32_bf16 v[8:11], v[96:99], v[246:249], 0
	v_mfma_f32_16x16x32_bf16 v[60:63], v[88:91], v[212:215], v[60:63]
	v_mfma_f32_16x16x32_bf16 v[56:59], v[104:107], v[212:215], v[56:59]
	v_mfma_f32_16x16x32_bf16 v[44:47], v[88:91], v[220:223], v[44:47]
	v_mfma_f32_16x16x32_bf16 v[40:43], v[104:107], v[220:223], v[40:43]
	v_mfma_f32_16x16x32_bf16 v[28:31], v[88:91], v[242:245], v[28:31]
	v_mfma_f32_16x16x32_bf16 v[24:27], v[104:107], v[242:245], v[24:27]
	v_mfma_f32_16x16x32_bf16 v[12:15], v[88:91], v[250:253], v[12:15]
	v_mfma_f32_16x16x32_bf16 v[8:11], v[104:107], v[250:253], v[8:11]
	s_setprio 0
	s_setprio 1
	v_mfma_f32_16x16x32_bf16 v[52:55], v[182:185], v[208:211], 0
	v_mfma_f32_16x16x32_bf16 v[48:51], v[200:203], v[208:211], 0
	v_mfma_f32_16x16x32_bf16 v[36:39], v[182:185], v[216:219], 0
	v_mfma_f32_16x16x32_bf16 v[32:35], v[200:203], v[216:219], 0
	v_mfma_f32_16x16x32_bf16 v[20:23], v[182:185], v[224:227], 0
	v_mfma_f32_16x16x32_bf16 v[16:19], v[200:203], v[224:227], 0
	v_mfma_f32_16x16x32_bf16 v[4:7], v[182:185], v[246:249], 0
	v_mfma_f32_16x16x32_bf16 v[0:3], v[200:203], v[246:249], 0
	v_mfma_f32_16x16x32_bf16 v[52:55], v[196:199], v[212:215], v[52:55]
	v_mfma_f32_16x16x32_bf16 v[48:51], v[204:207], v[212:215], v[48:51]
	v_mfma_f32_16x16x32_bf16 v[36:39], v[196:199], v[220:223], v[36:39]
	v_mfma_f32_16x16x32_bf16 v[32:35], v[204:207], v[220:223], v[32:35]
	v_mfma_f32_16x16x32_bf16 v[20:23], v[196:199], v[242:245], v[20:23]
	v_mfma_f32_16x16x32_bf16 v[16:19], v[204:207], v[242:245], v[16:19]
	v_mfma_f32_16x16x32_bf16 v[4:7], v[196:199], v[250:253], v[4:7]
	v_mfma_f32_16x16x32_bf16 v[0:3], v[204:207], v[250:253], v[0:3]
	s_setprio 0
	s_barrier
	s_add_i32 s23, 0, 0x18000
	s_add_i32 s31, 0, 0x1c000
	v_add_u32_e32 v104, s23, v192
	v_add_u32_e32 v195, s31, v192
	ds_read_b128 v[80:83], v104
	ds_read_b128 v[88:91], v104 offset:1024
	ds_read_b128 v[96:99], v104 offset:2048
	ds_read_b128 v[104:107], v104 offset:3072
	ds_read_b128 v[182:185], v195
	ds_read_b128 v[196:199], v195 offset:1024
	ds_read_b128 v[200:203], v195 offset:2048
	ds_read_b128 v[204:207], v195 offset:3072
	s_add_u32 s34, s40, 0x40000
	s_addc_u32 s35, s41, 0
	s_mov_b32 m0, s55
	v_lshl_add_u64 v[236:237], s[34:35], 0, v[188:189]
	ds_read_b128 v[208:211], v194 offset:32768
	ds_read_b128 v[212:215], v194 offset:33792
	ds_read_b128 v[216:219], v194 offset:34816
	ds_read_b128 v[220:223], v194 offset:35840
	ds_read_b128 v[224:227], v194 offset:36864
	ds_read_b128 v[242:245], v194 offset:37888
	ds_read_b128 v[246:249], v194 offset:38912
	ds_read_b128 v[250:253], v194 offset:39936
	global_load_lds_dwordx4 v[236:237], off
	v_lshl_add_u64 v[236:237], s[34:35], 0, v[144:145]
	s_mov_b32 m0, s60
	s_nop 0
	global_load_lds_dwordx4 v[236:237], off
	s_waitcnt vmcnt(8)
	s_waitcnt lgkmcnt(0)
	s_barrier
	s_setprio 1
	s_waitcnt lgkmcnt(0)
	v_mfma_f32_16x16x32_bf16 v[140:143], v[80:83], v[208:211], v[140:143]
	v_mfma_f32_16x16x32_bf16 v[136:139], v[96:99], v[208:211], v[136:139]
	v_mfma_f32_16x16x32_bf16 v[124:127], v[80:83], v[216:219], v[124:127]
	v_mfma_f32_16x16x32_bf16 v[120:123], v[96:99], v[216:219], v[120:123]
	v_mfma_f32_16x16x32_bf16 v[108:111], v[80:83], v[224:227], v[108:111]
	v_mfma_f32_16x16x32_bf16 v[100:103], v[96:99], v[224:227], v[100:103]
	v_mfma_f32_16x16x32_bf16 v[76:79], v[80:83], v[246:249], v[76:79]
	v_mfma_f32_16x16x32_bf16 v[72:75], v[96:99], v[246:249], v[72:75]
	v_mfma_f32_16x16x32_bf16 v[140:143], v[88:91], v[212:215], v[140:143]
	v_mfma_f32_16x16x32_bf16 v[136:139], v[104:107], v[212:215], v[136:139]
	v_mfma_f32_16x16x32_bf16 v[124:127], v[88:91], v[220:223], v[124:127]
	v_mfma_f32_16x16x32_bf16 v[120:123], v[104:107], v[220:223], v[120:123]
	v_mfma_f32_16x16x32_bf16 v[108:111], v[88:91], v[242:245], v[108:111]
	v_mfma_f32_16x16x32_bf16 v[100:103], v[104:107], v[242:245], v[100:103]
	v_mfma_f32_16x16x32_bf16 v[76:79], v[88:91], v[250:253], v[76:79]
	v_mfma_f32_16x16x32_bf16 v[72:75], v[104:107], v[250:253], v[72:75]
	s_setprio 0
	s_setprio 1
	v_mfma_f32_16x16x32_bf16 v[132:135], v[182:185], v[208:211], v[132:135]
	v_mfma_f32_16x16x32_bf16 v[128:131], v[200:203], v[208:211], v[128:131]
	v_mfma_f32_16x16x32_bf16 v[116:119], v[182:185], v[216:219], v[116:119]
	v_mfma_f32_16x16x32_bf16 v[112:115], v[200:203], v[216:219], v[112:115]
	v_mfma_f32_16x16x32_bf16 v[92:95], v[182:185], v[224:227], v[92:95]
	v_mfma_f32_16x16x32_bf16 v[84:87], v[200:203], v[224:227], v[84:87]
	v_mfma_f32_16x16x32_bf16 v[68:71], v[182:185], v[246:249], v[68:71]
	v_mfma_f32_16x16x32_bf16 v[64:67], v[200:203], v[246:249], v[64:67]
	v_mfma_f32_16x16x32_bf16 v[132:135], v[196:199], v[212:215], v[132:135]
	v_mfma_f32_16x16x32_bf16 v[128:131], v[204:207], v[212:215], v[128:131]
	v_mfma_f32_16x16x32_bf16 v[116:119], v[196:199], v[220:223], v[116:119]
	v_mfma_f32_16x16x32_bf16 v[112:115], v[204:207], v[220:223], v[112:115]
	v_mfma_f32_16x16x32_bf16 v[92:95], v[196:199], v[242:245], v[92:95]
	v_mfma_f32_16x16x32_bf16 v[84:87], v[204:207], v[242:245], v[84:87]
	v_mfma_f32_16x16x32_bf16 v[68:71], v[196:199], v[250:253], v[68:71]
	v_mfma_f32_16x16x32_bf16 v[64:67], v[204:207], v[250:253], v[64:67]
	s_setprio 0
	s_barrier
; #define PG8_STAGE(bufoff, gbase, voff) do { _Pragma("unroll") for (int _i = 0; _i < 2; ++_i) \
;         __builtin_amdgcn_global_load_lds((const unsigned*)((const char*)(gbase) + (voff)[_i]), (LAS unsigned*)(lds + (bufoff) + ldsw + _i * 8192), 16, 0, 0); } while (0)
; #define PG8_LDA(dst, b, h) do { _Pragma("unroll") for (int m = 0; m < 4; ++m) _Pragma("unroll") for (int k = 0; k < 2; ++k) dst[m][k] = *(const LAS bf16x8*)(lds + PG8_SA(b, h) + aoff + m * 2048 + k * 1024); } while (0)
; #define PG8_MMA(ai, bj, At, Bt) do { __builtin_amdgcn_s_setprio(1); _Pragma("unroll") for (int m = 0; m < 4; ++m) _Pragma("unroll") for (int n = 0; n < 2; ++n) _Pragma("unroll") for (int k = 0; k < 2; ++k) \
;         acc[ai][bj][m][n] = __builtin_amdgcn_mfma_f32_16x16x32_bf16(Bt[n][k], At[m][k], acc[ai][bj][m][n], 0, 0, 0); __builtin_amdgcn_s_setprio(0); } while (0)
; #define PG8_WAIT_V(n) asm volatile("s_waitcnt vmcnt(" #n ")" ::: "memory")
; #define PG8_WAIT_L(n) asm volatile("s_waitcnt lgkmcnt(" #n ")" ::: "memory")
; #define PG8_BAR __builtin_amdgcn_s_barrier()
; #define PG8_SCHED __builtin_amdgcn_sched_barrier(0)
; template <class Epi, bool ALIGN_EPI = true>
; DI void gemm_phase(int tb_, LAS unsigned char* lds, const Gemm g, const Sched& S, const Epi& E) {
;     ...
;         for (int t = 0; t < nt; t += 2) {
;     ...
;             PG8_LDA(At, 1, 1); PG8_STAGE(PG8_SB(1, 0), b3, voffB); PG8_STAGE(PG8_SB(1, 1), b3 + hstep, voffB); PG8_STAGE(PG8_SA(1, 0), a3, voffA);
;             PG8_WAIT_V(8); PG8_WAIT_L(0); PG8_BAR; PG8_MMA(1, 0, At, B0); PG8_MMA(1, 1, At, B1); PG8_BAR; PG8_SCHED;
	s_add_i32 s23, s23, s50
	v_lshl_add_u64 v[186:187], v[186:187], 0, s[72:73]
	s_mov_b32 m0, s23
	ds_read_b128 v[208:211], v194 offset:49152
	ds_read_b128 v[212:215], v194 offset:50176
	ds_read_b128 v[216:219], v194 offset:51200
	ds_read_b128 v[220:223], v194 offset:52224
	ds_read_b128 v[224:227], v194 offset:53248
	ds_read_b128 v[242:245], v194 offset:54272
	ds_read_b128 v[246:249], v194 offset:55296
	ds_read_b128 v[250:253], v194 offset:56320
	global_load_lds_dwordx4 v[186:187], off
	s_add_i32 m0, s23, 0x2000
	s_add_u32 s34, s38, 0x40080
	v_lshl_add_u64 v[186:187], v[228:229], 0, s[72:73]
	s_addc_u32 s35, s39, 0
	s_add_i32 s23, s31, s50
	global_load_lds_dwordx4 v[186:187], off
	v_lshl_add_u64 v[186:187], s[34:35], 0, v[188:189]
	s_mov_b32 m0, s23
	s_nop 0
	global_load_lds_dwordx4 v[186:187], off
	v_lshl_add_u64 v[186:187], s[34:35], 0, v[144:145]
	s_add_i32 m0, s23, 0x2000
	s_nop 0
	global_load_lds_dwordx4 v[186:187], off
	v_lshl_add_u64 v[186:187], v[232:233], 0, s[72:73]
	s_mov_b32 m0, s61
	s_nop 0
	global_load_lds_dwordx4 v[186:187], off
	v_lshl_add_u64 v[186:187], v[234:235], 0, s[72:73]
	s_mov_b32 m0, s64
	s_nop 0
	global_load_lds_dwordx4 v[186:187], off
	s_waitcnt vmcnt(8)
	s_waitcnt lgkmcnt(0)
	s_barrier
	s_setprio 1
	s_waitcnt lgkmcnt(0)
	v_mfma_f32_16x16x32_bf16 v[60:63], v[80:83], v[208:211], v[60:63]
	v_mfma_f32_16x16x32_bf16 v[56:59], v[96:99], v[208:211], v[56:59]
	v_mfma_f32_16x16x32_bf16 v[44:47], v[80:83], v[216:219], v[44:47]
	v_mfma_f32_16x16x32_bf16 v[40:43], v[96:99], v[216:219], v[40:43]
	v_mfma_f32_16x16x32_bf16 v[28:31], v[80:83], v[224:227], v[28:31]
	v_mfma_f32_16x16x32_bf16 v[24:27], v[96:99], v[224:227], v[24:27]
	v_mfma_f32_16x16x32_bf16 v[12:15], v[80:83], v[246:249], v[12:15]
	v_mfma_f32_16x16x32_bf16 v[8:11], v[96:99], v[246:249], v[8:11]
	v_mfma_f32_16x16x32_bf16 v[60:63], v[88:91], v[212:215], v[60:63]
	v_mfma_f32_16x16x32_bf16 v[56:59], v[104:107], v[212:215], v[56:59]
	v_mfma_f32_16x16x32_bf16 v[44:47], v[88:91], v[220:223], v[44:47]
	v_mfma_f32_16x16x32_bf16 v[40:43], v[104:107], v[220:223], v[40:43]
	v_mfma_f32_16x16x32_bf16 v[28:31], v[88:91], v[242:245], v[28:31]
	v_mfma_f32_16x16x32_bf16 v[24:27], v[104:107], v[242:245], v[24:27]
	v_mfma_f32_16x16x32_bf16 v[12:15], v[88:91], v[250:253], v[12:15]
	v_mfma_f32_16x16x32_bf16 v[8:11], v[104:107], v[250:253], v[8:11]
	s_setprio 0
	s_setprio 1
	v_mfma_f32_16x16x32_bf16 v[52:55], v[182:185], v[208:211], v[52:55]
	v_mfma_f32_16x16x32_bf16 v[48:51], v[200:203], v[208:211], v[48:51]
	v_mfma_f32_16x16x32_bf16 v[36:39], v[182:185], v[216:219], v[36:39]
	v_mfma_f32_16x16x32_bf16 v[32:35], v[200:203], v[216:219], v[32:35]
	v_mfma_f32_16x16x32_bf16 v[20:23], v[182:185], v[224:227], v[20:23]
	v_mfma_f32_16x16x32_bf16 v[16:19], v[200:203], v[224:227], v[16:19]
	v_mfma_f32_16x16x32_bf16 v[4:7], v[182:185], v[246:249], v[4:7]
	v_mfma_f32_16x16x32_bf16 v[0:3], v[200:203], v[246:249], v[0:3]
	v_mfma_f32_16x16x32_bf16 v[52:55], v[196:199], v[212:215], v[52:55]
	v_mfma_f32_16x16x32_bf16 v[48:51], v[204:207], v[212:215], v[48:51]
	v_mfma_f32_16x16x32_bf16 v[36:39], v[196:199], v[220:223], v[36:39]
	v_mfma_f32_16x16x32_bf16 v[32:35], v[204:207], v[220:223], v[32:35]
	v_mfma_f32_16x16x32_bf16 v[20:23], v[196:199], v[242:245], v[20:23]
	v_mfma_f32_16x16x32_bf16 v[16:19], v[204:207], v[242:245], v[16:19]
	v_mfma_f32_16x16x32_bf16 v[4:7], v[196:199], v[250:253], v[4:7]
	v_mfma_f32_16x16x32_bf16 v[0:3], v[204:207], v[250:253], v[0:3]
	s_setprio 0
	s_barrier
	s_add_u32 s11, s11, 0x100
	s_addc_u32 s15, s15, 0
	s_cmp_ge_i32 s25, s2
	s_mov_b64 s[34:35], s[36:37]
	s_mov_b32 s23, s25
	s_cbranch_scc1 .Lpeel_exit_8

; #define PG8_STAGE(bufoff, gbase, voff) do { _Pragma("unroll") for (int _i = 0; _i < 2; ++_i) \
;         __builtin_amdgcn_global_load_lds((const unsigned*)((const char*)(gbase) + (voff)[_i]), (LAS unsigned*)(lds + (bufoff) + ldsw + _i * 8192), 16, 0, 0); } while (0)
; #define PG8_LDA(dst, b, h) do { _Pragma("unroll") for (int m = 0; m < 4; ++m) _Pragma("unroll") for (int k = 0; k < 2; ++k) dst[m][k] = *(const LAS bf16x8*)(lds + PG8_SA(b, h) + aoff + m * 2048 + k * 1024); } while (0)
; #define PG8_LDB(dst, b, h) do { _Pragma("unroll") for (int n = 0; n < 2; ++n) _Pragma("unroll") for (int k = 0; k < 2; ++k) dst[n][k] = *(const LAS bf16x8*)(lds + PG8_SB(b, h) + boff + n * 2048 + k * 1024); } while (0)
; #define PG8_MMA(ai, bj, At, Bt) do { __builtin_amdgcn_s_setprio(1); _Pragma("unroll") for (int m = 0; m < 4; ++m) _Pragma("unroll") for (int n = 0; n < 2; ++n) _Pragma("unroll") for (int k = 0; k < 2; ++k) \
;         acc[ai][bj][m][n] = __builtin_amdgcn_mfma_f32_16x16x32_bf16(Bt[n][k], At[m][k], acc[ai][bj][m][n], 0, 0, 0); __builtin_amdgcn_s_setprio(0); } while (0)
; #define PG8_WAIT_V(n) asm volatile("s_waitcnt vmcnt(" #n ")" ::: "memory")
; template <class Epi, bool ALIGN_EPI = true>
; DI void gemm_phase(int tb_, LAS unsigned char* lds, const Gemm g, const Sched& S, const Epi& E) {
;     ...
;         const bool has_next = S.next(ui + 1, nxt);
;         const char* nA = has_next ? PG8_APTR(nxt) : cA; const char* nB = has_next ? PG8_BPTR(nxt) : cB;
;         const int nt = cur.nt;
;         for (int t = 0; t < nt; t += 2) {
;             const bool last = (t == nt - 2);
;             const char* a1 = cA + (size_t)(t + 1) * kstep;
;             const char* a2 = last ? nA : cA + (size_t)(t + 2) * kstep; const char* b2 = last ? nB : cB + (size_t)(t + 2) * kstep;
;             const char* a3 = a2 + kstep; const char* b3 = b2 + kstep;
;             PG8_LDB(B0, 0, 0); PG8_LDB(B1, 0, 1); PG8_SCHED; PG8_LDA(At, 0, 0); PG8_STAGE(PG8_SA(1, 1), a1 + hstep, voffA);
;             PG8_WAIT_V(8); PG8_WAIT_L(0); PG8_BAR; PG8_MMA(0, 0, At, B0); PG8_MMA(0, 1, At, B1); PG8_BAR; PG8_SCHED;
;             PG8_LDA(At, 0, 1); PG8_STAGE(PG8_SB(0, 0), b2, voffB); PG8_STAGE(PG8_SB(0, 1), b2 + hstep, voffB); PG8_STAGE(PG8_SA(0, 0), a2, voffA);
;             PG8_WAIT_V(8); PG8_WAIT_L(0); PG8_BAR; PG8_MMA(1, 0, At, B0); PG8_MMA(1, 1, At, B1); PG8_BAR; PG8_SCHED;
.LBB0_1993:
	s_ashr_i32 s17, s16, 31
	s_lshl_b64 s[18:19], s[16:17], 19
	s_add_u32 s18, s34, s18
	s_addc_u32 s19, s35, s19
	s_and_b64 s[20:21], s[6:7], exec
	s_cselect_b32 s2, s19, s27
	s_cselect_b32 s17, s18, s26
	s_ashr_i32 s15, s14, 31
	s_lshl_b64 s[20:21], s[14:15], 19
	s_add_u32 s20, s36, s20
	s_addc_u32 s21, s37, s21
	s_and_b64 s[30:31], s[6:7], exec
	s_cselect_b32 s15, s21, s29
	s_cselect_b32 s23, s20, s28
	s_add_u32 s26, s26, 0x40080
	s_addc_u32 s27, s27, 0
	s_add_u32 s33, s28, 0x100
	s_addc_u32 s48, s29, 0
	s_mov_b32 s49, -2
	s_add_u32 s28, s26, 0xfffc0080
	s_addc_u32 s29, s27, -1
	s_add_i32 s50, 0, 0x10000
	s_cmp_eq_u32 s49, 12
	s_cselect_b32 s31, s2, s29
	s_cselect_b32 s30, s17, s28
	v_add_u32_e32 v138, s50, v141
	s_cselect_b32 s29, s15, s48
	s_cselect_b32 s28, s23, s33
	s_add_i32 s52, 0, 0x14000
	ds_read_b128 v[144:147], v138
	ds_read_b128 v[148:151], v138 offset:1024
	ds_read_b128 v[152:155], v138 offset:2048
	ds_read_b128 v[156:159], v138 offset:3072
	v_add_u32_e32 v138, s52, v141
	ds_read_b128 v[160:163], v138
	ds_read_b128 v[164:167], v138 offset:1024
	ds_read_b128 v[168:171], v138 offset:2048
	ds_read_b128 v[172:175], v138 offset:3072
	v_lshl_add_u64 v[138:139], s[26:27], 0, v[134:135]
	s_add_i32 m0, s25, 0xc000
	ds_read_b128 v[176:179], v143
	ds_read_b128 v[180:183], v143 offset:1024
	ds_read_b128 v[184:187], v143 offset:2048
	ds_read_b128 v[192:195], v143 offset:3072
	ds_read_b128 v[196:199], v143 offset:4096
	ds_read_b128 v[200:203], v143 offset:5120
	ds_read_b128 v[204:207], v143 offset:6144
	ds_read_b128 v[208:211], v143 offset:7168
	global_load_lds_dwordx4 v[138:139], off
	v_lshl_add_u64 v[138:139], s[26:27], 0, v[136:137]
	s_add_i32 m0, s25, 0xe000
	s_nop 0
	global_load_lds_dwordx4 v[138:139], off
	s_waitcnt vmcnt(8)
	s_waitcnt lgkmcnt(0)
	s_barrier
	s_setprio 1
	s_waitcnt lgkmcnt(0)
	v_mfma_f32_16x16x32_bf16 v[124:127], v[144:147], v[176:179], 0
	v_mfma_f32_16x16x32_bf16 v[116:119], v[152:155], v[176:179], 0
	v_mfma_f32_16x16x32_bf16 v[108:111], v[144:147], v[184:187], 0
	v_mfma_f32_16x16x32_bf16 v[100:103], v[152:155], v[184:187], 0
	v_mfma_f32_16x16x32_bf16 v[92:95], v[144:147], v[196:199], 0
	v_mfma_f32_16x16x32_bf16 v[84:87], v[152:155], v[196:199], 0
	v_mfma_f32_16x16x32_bf16 v[76:79], v[144:147], v[204:207], 0
	v_mfma_f32_16x16x32_bf16 v[68:71], v[152:155], v[204:207], 0
	v_mfma_f32_16x16x32_bf16 v[124:127], v[148:151], v[180:183], v[124:127]
	v_mfma_f32_16x16x32_bf16 v[116:119], v[156:159], v[180:183], v[116:119]
	v_mfma_f32_16x16x32_bf16 v[108:111], v[148:151], v[192:195], v[108:111]
	v_mfma_f32_16x16x32_bf16 v[100:103], v[156:159], v[192:195], v[100:103]
	v_mfma_f32_16x16x32_bf16 v[92:95], v[148:151], v[200:203], v[92:95]
	v_mfma_f32_16x16x32_bf16 v[84:87], v[156:159], v[200:203], v[84:87]
	v_mfma_f32_16x16x32_bf16 v[76:79], v[148:151], v[208:211], v[76:79]
	v_mfma_f32_16x16x32_bf16 v[68:71], v[156:159], v[208:211], v[68:71]
	s_setprio 0
	s_setprio 1
	v_mfma_f32_16x16x32_bf16 v[120:123], v[160:163], v[176:179], 0
	v_mfma_f32_16x16x32_bf16 v[112:115], v[168:171], v[176:179], 0
	v_mfma_f32_16x16x32_bf16 v[104:107], v[160:163], v[184:187], 0
	v_mfma_f32_16x16x32_bf16 v[96:99], v[168:171], v[184:187], 0
	v_mfma_f32_16x16x32_bf16 v[88:91], v[160:163], v[196:199], 0
	v_mfma_f32_16x16x32_bf16 v[80:83], v[168:171], v[196:199], 0
	v_mfma_f32_16x16x32_bf16 v[72:75], v[160:163], v[204:207], 0
	v_mfma_f32_16x16x32_bf16 v[64:67], v[168:171], v[204:207], 0
	v_mfma_f32_16x16x32_bf16 v[120:123], v[164:167], v[180:183], v[120:123]
	v_mfma_f32_16x16x32_bf16 v[112:115], v[172:175], v[180:183], v[112:115]
	v_mfma_f32_16x16x32_bf16 v[104:107], v[164:167], v[192:195], v[104:107]
	v_mfma_f32_16x16x32_bf16 v[96:99], v[172:175], v[192:195], v[96:99]
	v_mfma_f32_16x16x32_bf16 v[88:91], v[164:167], v[200:203], v[88:91]
	v_mfma_f32_16x16x32_bf16 v[80:83], v[172:175], v[200:203], v[80:83]
	v_mfma_f32_16x16x32_bf16 v[72:75], v[164:167], v[208:211], v[72:75]
	v_mfma_f32_16x16x32_bf16 v[64:67], v[172:175], v[208:211], v[64:67]
	s_setprio 0
	s_barrier
	s_add_i32 s50, s50, s40
	v_lshl_add_u64 v[138:139], s[28:29], 0, v[188:189]
	s_mov_b32 m0, s50
	ds_read_b128 v[176:179], v143 offset:16384
	ds_read_b128 v[180:183], v143 offset:17408
	ds_read_b128 v[184:187], v143 offset:18432
	ds_read_b128 v[192:195], v143 offset:19456
	ds_read_b128 v[196:199], v143 offset:20480
	ds_read_b128 v[200:203], v143 offset:21504
	ds_read_b128 v[204:207], v143 offset:22528
	ds_read_b128 v[208:211], v143 offset:23552
	global_load_lds_dwordx4 v[138:139], off
	s_add_i32 m0, s50, 0x2000
	s_add_u32 s50, s28, 0x40000
	v_lshl_add_u64 v[212:213], s[28:29], 0, v[128:129]
	s_addc_u32 s51, s29, 0
	s_add_i32 s52, s52, s40
	global_load_lds_dwordx4 v[212:213], off
	v_lshl_add_u64 v[214:215], s[50:51], 0, v[188:189]
	s_mov_b32 m0, s52
	v_lshl_add_u64 v[216:217], s[30:31], 0, v[130:131]
	global_load_lds_dwordx4 v[214:215], off
	v_lshl_add_u64 v[214:215], s[50:51], 0, v[128:129]
	s_add_i32 m0, s52, 0x2000
	s_nop 0
	global_load_lds_dwordx4 v[214:215], off
	v_lshl_add_u64 v[214:215], s[30:31], 0, v[132:133]
	s_mov_b32 m0, s25
	s_nop 0
	global_load_lds_dwordx4 v[214:215], off
	s_mov_b32 m0, s41
	s_nop 0
	global_load_lds_dwordx4 v[216:217], off
	s_waitcnt vmcnt(8)
	s_waitcnt lgkmcnt(0)
	s_barrier
; #define PG8_STAGE(bufoff, gbase, voff) do { _Pragma("unroll") for (int _i = 0; _i < 2; ++_i) \
;         __builtin_amdgcn_global_load_lds((const unsigned*)((const char*)(gbase) + (voff)[_i]), (LAS unsigned*)(lds + (bufoff) + ldsw + _i * 8192), 16, 0, 0); } while (0)
; #define PG8_LDA(dst, b, h) do { _Pragma("unroll") for (int m = 0; m < 4; ++m) _Pragma("unroll") for (int k = 0; k < 2; ++k) dst[m][k] = *(const LAS bf16x8*)(lds + PG8_SA(b, h) + aoff + m * 2048 + k * 1024); } while (0)
; #define PG8_LDB(dst, b, h) do { _Pragma("unroll") for (int n = 0; n < 2; ++n) _Pragma("unroll") for (int k = 0; k < 2; ++k) dst[n][k] = *(const LAS bf16x8*)(lds + PG8_SB(b, h) + boff + n * 2048 + k * 1024); } while (0)
; #define PG8_MMA(ai, bj, At, Bt) do { __builtin_amdgcn_s_setprio(1); _Pragma("unroll") for (int m = 0; m < 4; ++m) _Pragma("unroll") for (int n = 0; n < 2; ++n) _Pragma("unroll") for (int k = 0; k < 2; ++k) \
;         acc[ai][bj][m][n] = __builtin_amdgcn_mfma_f32_16x16x32_bf16(Bt[n][k], At[m][k], acc[ai][bj][m][n], 0, 0, 0); __builtin_amdgcn_s_setprio(0); } while (0)
; #define PG8_WAIT_V(n) asm volatile("s_waitcnt vmcnt(" #n ")" ::: "memory")
; #define PG8_WAIT_L(n) asm volatile("s_waitcnt lgkmcnt(" #n ")" ::: "memory")
; #define PG8_BAR __builtin_amdgcn_s_barrier()
; #define PG8_SCHED __builtin_amdgcn_sched_barrier(0)
; template <class Epi, bool ALIGN_EPI = true>
; DI void gemm_phase(int tb_, LAS unsigned char* lds, const Gemm g, const Sched& S, const Epi& E) {
;     ...
;             PG8_WAIT_V(8); PG8_WAIT_L(0); PG8_BAR; PG8_MMA(1, 0, At, B0); PG8_MMA(1, 1, At, B1); PG8_BAR; PG8_SCHED;
;             PG8_LDB(B0, 1, 0); PG8_LDB(B1, 1, 1); PG8_SCHED; PG8_LDA(At, 1, 0); PG8_STAGE(PG8_SA(0, 1), a2 + hstep, voffA);
;             PG8_WAIT_V(8); PG8_WAIT_L(0); PG8_BAR; PG8_MMA(0, 0, At, B0); PG8_MMA(0, 1, At, B1); PG8_BAR; PG8_SCHED;
	s_setprio 1
	s_waitcnt lgkmcnt(0)
	v_mfma_f32_16x16x32_bf16 v[60:63], v[144:147], v[176:179], 0
	v_mfma_f32_16x16x32_bf16 v[52:55], v[152:155], v[176:179], 0
	v_mfma_f32_16x16x32_bf16 v[44:47], v[144:147], v[184:187], 0
	v_mfma_f32_16x16x32_bf16 v[36:39], v[152:155], v[184:187], 0
	v_mfma_f32_16x16x32_bf16 v[28:31], v[144:147], v[196:199], 0
	v_mfma_f32_16x16x32_bf16 v[20:23], v[152:155], v[196:199], 0
	v_mfma_f32_16x16x32_bf16 v[12:15], v[144:147], v[204:207], 0
	v_mfma_f32_16x16x32_bf16 v[4:7], v[152:155], v[204:207], 0
	v_mfma_f32_16x16x32_bf16 v[60:63], v[148:151], v[180:183], v[60:63]
	v_mfma_f32_16x16x32_bf16 v[52:55], v[156:159], v[180:183], v[52:55]
	v_mfma_f32_16x16x32_bf16 v[44:47], v[148:151], v[192:195], v[44:47]
	v_mfma_f32_16x16x32_bf16 v[36:39], v[156:159], v[192:195], v[36:39]
	v_mfma_f32_16x16x32_bf16 v[28:31], v[148:151], v[200:203], v[28:31]
	v_mfma_f32_16x16x32_bf16 v[20:23], v[156:159], v[200:203], v[20:23]
	v_mfma_f32_16x16x32_bf16 v[12:15], v[148:151], v[208:211], v[12:15]
	v_mfma_f32_16x16x32_bf16 v[4:7], v[156:159], v[208:211], v[4:7]
	s_setprio 0
	s_setprio 1
	v_mfma_f32_16x16x32_bf16 v[56:59], v[160:163], v[176:179], 0
	v_mfma_f32_16x16x32_bf16 v[48:51], v[168:171], v[176:179], 0
	v_mfma_f32_16x16x32_bf16 v[40:43], v[160:163], v[184:187], 0
	v_mfma_f32_16x16x32_bf16 v[32:35], v[168:171], v[184:187], 0
	v_mfma_f32_16x16x32_bf16 v[24:27], v[160:163], v[196:199], 0
	v_mfma_f32_16x16x32_bf16 v[16:19], v[168:171], v[196:199], 0
	v_mfma_f32_16x16x32_bf16 v[8:11], v[160:163], v[204:207], 0
	v_mfma_f32_16x16x32_bf16 v[0:3], v[168:171], v[204:207], 0
	v_mfma_f32_16x16x32_bf16 v[56:59], v[164:167], v[180:183], v[56:59]
	v_mfma_f32_16x16x32_bf16 v[48:51], v[172:175], v[180:183], v[48:51]
	v_mfma_f32_16x16x32_bf16 v[40:43], v[164:167], v[192:195], v[40:43]
	v_mfma_f32_16x16x32_bf16 v[32:35], v[172:175], v[192:195], v[32:35]
	v_mfma_f32_16x16x32_bf16 v[24:27], v[164:167], v[200:203], v[24:27]
	v_mfma_f32_16x16x32_bf16 v[16:19], v[172:175], v[200:203], v[16:19]
	v_mfma_f32_16x16x32_bf16 v[8:11], v[164:167], v[208:211], v[8:11]
	v_mfma_f32_16x16x32_bf16 v[0:3], v[172:175], v[208:211], v[0:3]
	s_setprio 0
	s_barrier
	s_add_i32 s50, 0, 0x18000
	s_add_i32 s51, 0, 0x1c000
	v_add_u32_e32 v156, s50, v141
	v_add_u32_e32 v172, s51, v141
	ds_read_b128 v[144:147], v156
	ds_read_b128 v[148:151], v156 offset:1024
	ds_read_b128 v[152:155], v156 offset:2048
	ds_read_b128 v[156:159], v156 offset:3072
	ds_read_b128 v[160:163], v172
	ds_read_b128 v[164:167], v172 offset:1024
	ds_read_b128 v[168:171], v172 offset:2048
	ds_read_b128 v[172:175], v172 offset:3072
	s_add_u32 s30, s30, 0x40000
	s_addc_u32 s31, s31, 0
	s_mov_b32 m0, s42
	v_lshl_add_u64 v[218:219], s[30:31], 0, v[132:133]
	ds_read_b128 v[176:179], v143 offset:32768
	ds_read_b128 v[180:183], v143 offset:33792
	ds_read_b128 v[184:187], v143 offset:34816
	ds_read_b128 v[192:195], v143 offset:35840
	ds_read_b128 v[196:199], v143 offset:36864
	ds_read_b128 v[200:203], v143 offset:37888
	ds_read_b128 v[204:207], v143 offset:38912
	ds_read_b128 v[208:211], v143 offset:39936
	global_load_lds_dwordx4 v[218:219], off
	v_lshl_add_u64 v[218:219], s[30:31], 0, v[130:131]
	s_mov_b32 m0, s43
	s_nop 0
	global_load_lds_dwordx4 v[218:219], off
	s_waitcnt vmcnt(8)
	s_waitcnt lgkmcnt(0)
	s_barrier
	s_setprio 1
	s_waitcnt lgkmcnt(0)
	v_mfma_f32_16x16x32_bf16 v[124:127], v[144:147], v[176:179], v[124:127]
	v_mfma_f32_16x16x32_bf16 v[116:119], v[152:155], v[176:179], v[116:119]
	v_mfma_f32_16x16x32_bf16 v[108:111], v[144:147], v[184:187], v[108:111]
	v_mfma_f32_16x16x32_bf16 v[100:103], v[152:155], v[184:187], v[100:103]
	v_mfma_f32_16x16x32_bf16 v[92:95], v[144:147], v[196:199], v[92:95]
	v_mfma_f32_16x16x32_bf16 v[84:87], v[152:155], v[196:199], v[84:87]
	v_mfma_f32_16x16x32_bf16 v[76:79], v[144:147], v[204:207], v[76:79]
	v_mfma_f32_16x16x32_bf16 v[68:71], v[152:155], v[204:207], v[68:71]
	v_mfma_f32_16x16x32_bf16 v[124:127], v[148:151], v[180:183], v[124:127]
	v_mfma_f32_16x16x32_bf16 v[116:119], v[156:159], v[180:183], v[116:119]
	v_mfma_f32_16x16x32_bf16 v[108:111], v[148:151], v[192:195], v[108:111]
	v_mfma_f32_16x16x32_bf16 v[100:103], v[156:159], v[192:195], v[100:103]
	v_mfma_f32_16x16x32_bf16 v[92:95], v[148:151], v[200:203], v[92:95]
	v_mfma_f32_16x16x32_bf16 v[84:87], v[156:159], v[200:203], v[84:87]
	v_mfma_f32_16x16x32_bf16 v[76:79], v[148:151], v[208:211], v[76:79]
	v_mfma_f32_16x16x32_bf16 v[68:71], v[156:159], v[208:211], v[68:71]
	s_setprio 0
	s_setprio 1
	v_mfma_f32_16x16x32_bf16 v[120:123], v[160:163], v[176:179], v[120:123]
	v_mfma_f32_16x16x32_bf16 v[112:115], v[168:171], v[176:179], v[112:115]
	v_mfma_f32_16x16x32_bf16 v[104:107], v[160:163], v[184:187], v[104:107]
	v_mfma_f32_16x16x32_bf16 v[96:99], v[168:171], v[184:187], v[96:99]
	v_mfma_f32_16x16x32_bf16 v[88:91], v[160:163], v[196:199], v[88:91]
	v_mfma_f32_16x16x32_bf16 v[80:83], v[168:171], v[196:199], v[80:83]
	v_mfma_f32_16x16x32_bf16 v[72:75], v[160:163], v[204:207], v[72:75]
	v_mfma_f32_16x16x32_bf16 v[64:67], v[168:171], v[204:207], v[64:67]
	v_mfma_f32_16x16x32_bf16 v[120:123], v[164:167], v[180:183], v[120:123]
	v_mfma_f32_16x16x32_bf16 v[112:115], v[172:175], v[180:183], v[112:115]
	v_mfma_f32_16x16x32_bf16 v[104:107], v[164:167], v[192:195], v[104:107]
	v_mfma_f32_16x16x32_bf16 v[96:99], v[172:175], v[192:195], v[96:99]
	v_mfma_f32_16x16x32_bf16 v[88:91], v[164:167], v[200:203], v[88:91]
	v_mfma_f32_16x16x32_bf16 v[80:83], v[172:175], v[200:203], v[80:83]
	v_mfma_f32_16x16x32_bf16 v[72:75], v[164:167], v[208:211], v[72:75]
	v_mfma_f32_16x16x32_bf16 v[64:67], v[172:175], v[208:211], v[64:67]
	s_setprio 0
	s_barrier
; #define PG8_STAGE(bufoff, gbase, voff) do { _Pragma("unroll") for (int _i = 0; _i < 2; ++_i) \
;         __builtin_amdgcn_global_load_lds((const unsigned*)((const char*)(gbase) + (voff)[_i]), (LAS unsigned*)(lds + (bufoff) + ldsw + _i * 8192), 16, 0, 0); } while (0)
; #define PG8_LDA(dst, b, h) do { _Pragma("unroll") for (int m = 0; m < 4; ++m) _Pragma("unroll") for (int k = 0; k < 2; ++k) dst[m][k] = *(const LAS bf16x8*)(lds + PG8_SA(b, h) + aoff + m * 2048 + k * 1024); } while (0)
; #define PG8_MMA(ai, bj, At, Bt) do { __builtin_amdgcn_s_setprio(1); _Pragma("unroll") for (int m = 0; m < 4; ++m) _Pragma("unroll") for (int n = 0; n < 2; ++n) _Pragma("unroll") for (int k = 0; k < 2; ++k) \
;         acc[ai][bj][m][n] = __builtin_amdgcn_mfma_f32_16x16x32_bf16(Bt[n][k], At[m][k], acc[ai][bj][m][n], 0, 0, 0); __builtin_amdgcn_s_setprio(0); } while (0)
; #define PG8_WAIT_V(n) asm volatile("s_waitcnt vmcnt(" #n ")" ::: "memory")
; #define PG8_WAIT_L(n) asm volatile("s_waitcnt lgkmcnt(" #n ")" ::: "memory")
; #define PG8_BAR __builtin_amdgcn_s_barrier()
; #define PG8_SCHED __builtin_amdgcn_sched_barrier(0)
; template <class Epi, bool ALIGN_EPI = true>
; DI void gemm_phase(int tb_, LAS unsigned char* lds, const Gemm g, const Sched& S, const Epi& E) {
;     ...
;             PG8_LDA(At, 1, 1); PG8_STAGE(PG8_SB(1, 0), b3, voffB); PG8_STAGE(PG8_SB(1, 1), b3 + hstep, voffB); PG8_STAGE(PG8_SA(1, 0), a3, voffA);
;             PG8_WAIT_V(8); PG8_WAIT_L(0); PG8_BAR; PG8_MMA(1, 0, At, B0); PG8_MMA(1, 1, At, B1); PG8_BAR; PG8_SCHED;
	s_add_i32 s30, s50, s40
	v_lshl_add_u64 v[138:139], v[138:139], 0, s[72:73]
	s_mov_b32 m0, s30
	ds_read_b128 v[176:179], v143 offset:49152
	ds_read_b128 v[180:183], v143 offset:50176
	ds_read_b128 v[184:187], v143 offset:51200
	ds_read_b128 v[192:195], v143 offset:52224
	ds_read_b128 v[196:199], v143 offset:53248
	ds_read_b128 v[200:203], v143 offset:54272
	ds_read_b128 v[204:207], v143 offset:55296
	ds_read_b128 v[208:211], v143 offset:56320
	global_load_lds_dwordx4 v[138:139], off
	s_add_i32 m0, s30, 0x2000
	s_add_u32 s28, s28, 0x40080
	v_lshl_add_u64 v[138:139], v[212:213], 0, s[72:73]
	s_addc_u32 s29, s29, 0
	s_add_i32 s30, s51, s40
	global_load_lds_dwordx4 v[138:139], off
	v_lshl_add_u64 v[138:139], s[28:29], 0, v[188:189]
	s_mov_b32 m0, s30
	s_nop 0
	global_load_lds_dwordx4 v[138:139], off
	v_lshl_add_u64 v[138:139], s[28:29], 0, v[128:129]
	s_add_i32 m0, s30, 0x2000
	s_nop 0
	global_load_lds_dwordx4 v[138:139], off
	v_lshl_add_u64 v[138:139], v[214:215], 0, s[72:73]
	s_mov_b32 m0, s45
	s_nop 0
	global_load_lds_dwordx4 v[138:139], off
	v_lshl_add_u64 v[138:139], v[216:217], 0, s[72:73]
	s_mov_b32 m0, s46
	s_nop 0
	global_load_lds_dwordx4 v[138:139], off
	s_waitcnt vmcnt(8)
	s_waitcnt lgkmcnt(0)
	s_barrier
	s_setprio 1
	s_waitcnt lgkmcnt(0)
	v_mfma_f32_16x16x32_bf16 v[60:63], v[144:147], v[176:179], v[60:63]
	v_mfma_f32_16x16x32_bf16 v[52:55], v[152:155], v[176:179], v[52:55]
	v_mfma_f32_16x16x32_bf16 v[44:47], v[144:147], v[184:187], v[44:47]
	v_mfma_f32_16x16x32_bf16 v[36:39], v[152:155], v[184:187], v[36:39]
	v_mfma_f32_16x16x32_bf16 v[28:31], v[144:147], v[196:199], v[28:31]
	v_mfma_f32_16x16x32_bf16 v[20:23], v[152:155], v[196:199], v[20:23]
	v_mfma_f32_16x16x32_bf16 v[12:15], v[144:147], v[204:207], v[12:15]
	v_mfma_f32_16x16x32_bf16 v[4:7], v[152:155], v[204:207], v[4:7]
	v_mfma_f32_16x16x32_bf16 v[60:63], v[148:151], v[180:183], v[60:63]
	v_mfma_f32_16x16x32_bf16 v[52:55], v[156:159], v[180:183], v[52:55]
	v_mfma_f32_16x16x32_bf16 v[44:47], v[148:151], v[192:195], v[44:47]
	v_mfma_f32_16x16x32_bf16 v[36:39], v[156:159], v[192:195], v[36:39]
	v_mfma_f32_16x16x32_bf16 v[28:31], v[148:151], v[200:203], v[28:31]
	v_mfma_f32_16x16x32_bf16 v[20:23], v[156:159], v[200:203], v[20:23]
	v_mfma_f32_16x16x32_bf16 v[12:15], v[148:151], v[208:211], v[12:15]
	v_mfma_f32_16x16x32_bf16 v[4:7], v[156:159], v[208:211], v[4:7]
	s_setprio 0
	s_setprio 1
	v_mfma_f32_16x16x32_bf16 v[56:59], v[160:163], v[176:179], v[56:59]
	v_mfma_f32_16x16x32_bf16 v[48:51], v[168:171], v[176:179], v[48:51]
	v_mfma_f32_16x16x32_bf16 v[40:43], v[160:163], v[184:187], v[40:43]
	v_mfma_f32_16x16x32_bf16 v[32:35], v[168:171], v[184:187], v[32:35]
	v_mfma_f32_16x16x32_bf16 v[24:27], v[160:163], v[196:199], v[24:27]
	v_mfma_f32_16x16x32_bf16 v[16:19], v[168:171], v[196:199], v[16:19]
	v_mfma_f32_16x16x32_bf16 v[8:11], v[160:163], v[204:207], v[8:11]
	v_mfma_f32_16x16x32_bf16 v[0:3], v[168:171], v[204:207], v[0:3]
	v_mfma_f32_16x16x32_bf16 v[56:59], v[164:167], v[180:183], v[56:59]
	v_mfma_f32_16x16x32_bf16 v[48:51], v[172:175], v[180:183], v[48:51]
	v_mfma_f32_16x16x32_bf16 v[40:43], v[164:167], v[192:195], v[40:43]
	v_mfma_f32_16x16x32_bf16 v[32:35], v[172:175], v[192:195], v[32:35]
	v_mfma_f32_16x16x32_bf16 v[24:27], v[164:167], v[200:203], v[24:27]
	v_mfma_f32_16x16x32_bf16 v[16:19], v[172:175], v[200:203], v[16:19]
	v_mfma_f32_16x16x32_bf16 v[8:11], v[164:167], v[208:211], v[8:11]
	v_mfma_f32_16x16x32_bf16 v[0:3], v[172:175], v[208:211], v[0:3]
	s_setprio 0
	s_barrier
	s_add_i32 s49, s49, 2
	s_add_u32 s26, s26, 0x100
	s_addc_u32 s27, s27, 0
	s_add_u32 s33, s33, 0x100
	s_addc_u32 s48, s48, 0
	s_cmp_gt_u32 s49, 13
	s_cbranch_scc1 .Lpeel_exit_9

; #define PG8_STAGE(bufoff, gbase, voff) do { _Pragma("unroll") for (int _i = 0; _i < 2; ++_i) \
;         __builtin_amdgcn_global_load_lds((const unsigned*)((const char*)(gbase) + (voff)[_i]), (LAS unsigned*)(lds + (bufoff) + ldsw + _i * 8192), 16, 0, 0); } while (0)
; #define PG8_LDA(dst, b, h) do { _Pragma("unroll") for (int m = 0; m < 4; ++m) _Pragma("unroll") for (int k = 0; k < 2; ++k) dst[m][k] = *(const LAS bf16x8*)(lds + PG8_SA(b, h) + aoff + m * 2048 + k * 1024); } while (0)
; #define PG8_LDB(dst, b, h) do { _Pragma("unroll") for (int n = 0; n < 2; ++n) _Pragma("unroll") for (int k = 0; k < 2; ++k) dst[n][k] = *(const LAS bf16x8*)(lds + PG8_SB(b, h) + boff + n * 2048 + k * 1024); } while (0)
; #define PG8_MMA(ai, bj, At, Bt) do { __builtin_amdgcn_s_setprio(1); _Pragma("unroll") for (int m = 0; m < 4; ++m) _Pragma("unroll") for (int n = 0; n < 2; ++n) _Pragma("unroll") for (int k = 0; k < 2; ++k) \
;         acc[ai][bj][m][n] = __builtin_amdgcn_mfma_f32_16x16x32_bf16(Bt[n][k], At[m][k], acc[ai][bj][m][n], 0, 0, 0); __builtin_amdgcn_s_setprio(0); } while (0)
; #define PG8_WAIT_V(n) asm volatile("s_waitcnt vmcnt(" #n ")" ::: "memory")
; #define PG8_WAIT_L(n) asm volatile("s_waitcnt lgkmcnt(" #n ")" ::: "memory")
; #define PG8_BAR __builtin_amdgcn_s_barrier()
; #define PG8_SCHED __builtin_amdgcn_sched_barrier(0)
; template <class Epi, bool ALIGN_EPI = true>
; DI void gemm_phase(int tb_, LAS unsigned char* lds, const Gemm g, const Sched& S, const Epi& E) {
;     ...
;             const bool last = (t == nt - 2);
;             const char* a1 = cA + (size_t)(t + 1) * kstep;
;             const char* a2 = last ? nA : cA + (size_t)(t + 2) * kstep; const char* b2 = last ? nB : cB + (size_t)(t + 2) * kstep;
;             const char* a3 = a2 + kstep; const char* b3 = b2 + kstep;
;             PG8_LDB(B0, 0, 0); PG8_LDB(B1, 0, 1); PG8_SCHED; PG8_LDA(At, 0, 0); PG8_STAGE(PG8_SA(1, 1), a1 + hstep, voffA);
;             PG8_WAIT_V(8); PG8_WAIT_L(0); PG8_BAR; PG8_MMA(0, 0, At, B0); PG8_MMA(0, 1, At, B1); PG8_BAR; PG8_SCHED;
;             PG8_LDA(At, 0, 1); PG8_STAGE(PG8_SB(0, 0), b2, voffB); PG8_STAGE(PG8_SB(0, 1), b2 + hstep, voffB); PG8_STAGE(PG8_SA(0, 0), a2, voffA);
;             PG8_WAIT_V(8); PG8_WAIT_L(0); PG8_BAR; PG8_MMA(1, 0, At, B0); PG8_MMA(1, 1, At, B1); PG8_BAR; PG8_SCHED;
.LBB0_2090:
	s_add_i32 s5, s4, -2
	s_add_u32 s11, s30, 0x100
	s_addc_u32 s15, s31, 0
	s_mov_b32 s29, 0
	s_add_i32 s33, s29, 2
	s_add_u32 s30, s8, 0x100
	s_addc_u32 s31, s9, 0
	s_add_i32 s52, 0, 0x10000
	s_cmp_eq_u32 s5, s29
	s_cselect_b32 s37, s25, s31
	s_cselect_b32 s36, s24, s30
	s_cselect_b32 s35, s27, s15
	s_cselect_b32 s34, s26, s11
	s_add_i32 s29, 0, 0x14000
	v_add_u32_e32 v178, s52, v214
	v_add_u32_e32 v186, s29, v214
	ds_read_b128 v[128:131], v178
	ds_read_b128 v[170:173], v178 offset:1024
	ds_read_b128 v[174:177], v178 offset:2048
	ds_read_b128 v[178:181], v178 offset:3072
	ds_read_b128 v[182:185], v186
	ds_read_b128 v[192:195], v186 offset:1024
	ds_read_b128 v[196:199], v186 offset:2048
	ds_read_b128 v[200:203], v186 offset:3072
	v_lshl_add_u64 v[186:187], s[8:9], 0, v[166:167]
	s_add_i32 m0, s47, 0xc000
	ds_read_b128 v[204:207], v216
	ds_read_b128 v[208:211], v216 offset:1024
	ds_read_b128 v[218:221], v216 offset:2048
	ds_read_b128 v[222:225], v216 offset:3072
	ds_read_b128 v[226:229], v216 offset:4096
	ds_read_b128 v[242:245], v216 offset:5120
	ds_read_b128 v[246:249], v216 offset:6144
	ds_read_b128 v[250:253], v216 offset:7168
	global_load_lds_dwordx4 v[186:187], off
	v_lshl_add_u64 v[186:187], s[8:9], 0, v[168:169]
	s_add_i32 m0, s47, 0xe000
	s_nop 0
	global_load_lds_dwordx4 v[186:187], off
	s_waitcnt vmcnt(8)
	s_waitcnt lgkmcnt(0)
	s_barrier
	s_setprio 1
	s_waitcnt lgkmcnt(0)
	v_mfma_f32_16x16x32_bf16 v[124:127], v[128:131], v[204:207], 0
	v_mfma_f32_16x16x32_bf16 v[120:123], v[174:177], v[204:207], 0
	v_mfma_f32_16x16x32_bf16 v[108:111], v[128:131], v[218:221], 0
	v_mfma_f32_16x16x32_bf16 v[104:107], v[174:177], v[218:221], 0
	v_mfma_f32_16x16x32_bf16 v[92:95], v[128:131], v[226:229], 0
	v_mfma_f32_16x16x32_bf16 v[88:91], v[174:177], v[226:229], 0
	v_mfma_f32_16x16x32_bf16 v[76:79], v[128:131], v[246:249], 0
	v_mfma_f32_16x16x32_bf16 v[72:75], v[174:177], v[246:249], 0
	v_mfma_f32_16x16x32_bf16 v[124:127], v[170:173], v[208:211], v[124:127]
	v_mfma_f32_16x16x32_bf16 v[120:123], v[178:181], v[208:211], v[120:123]
	v_mfma_f32_16x16x32_bf16 v[108:111], v[170:173], v[222:225], v[108:111]
	v_mfma_f32_16x16x32_bf16 v[104:107], v[178:181], v[222:225], v[104:107]
	v_mfma_f32_16x16x32_bf16 v[92:95], v[170:173], v[242:245], v[92:95]
	v_mfma_f32_16x16x32_bf16 v[88:91], v[178:181], v[242:245], v[88:91]
	v_mfma_f32_16x16x32_bf16 v[76:79], v[170:173], v[250:253], v[76:79]
	v_mfma_f32_16x16x32_bf16 v[72:75], v[178:181], v[250:253], v[72:75]
	s_setprio 0
	s_setprio 1
	v_mfma_f32_16x16x32_bf16 v[116:119], v[182:185], v[204:207], 0
	v_mfma_f32_16x16x32_bf16 v[112:115], v[196:199], v[204:207], 0
	v_mfma_f32_16x16x32_bf16 v[100:103], v[182:185], v[218:221], 0
	v_mfma_f32_16x16x32_bf16 v[96:99], v[196:199], v[218:221], 0
	v_mfma_f32_16x16x32_bf16 v[84:87], v[182:185], v[226:229], 0
	v_mfma_f32_16x16x32_bf16 v[80:83], v[196:199], v[226:229], 0
	v_mfma_f32_16x16x32_bf16 v[68:71], v[182:185], v[246:249], 0
	v_mfma_f32_16x16x32_bf16 v[64:67], v[196:199], v[246:249], 0
	v_mfma_f32_16x16x32_bf16 v[116:119], v[192:195], v[208:211], v[116:119]
	v_mfma_f32_16x16x32_bf16 v[112:115], v[200:203], v[208:211], v[112:115]
	v_mfma_f32_16x16x32_bf16 v[100:103], v[192:195], v[222:225], v[100:103]
	v_mfma_f32_16x16x32_bf16 v[96:99], v[200:203], v[222:225], v[96:99]
	v_mfma_f32_16x16x32_bf16 v[84:87], v[192:195], v[242:245], v[84:87]
	v_mfma_f32_16x16x32_bf16 v[80:83], v[200:203], v[242:245], v[80:83]
	v_mfma_f32_16x16x32_bf16 v[68:71], v[192:195], v[250:253], v[68:71]
	v_mfma_f32_16x16x32_bf16 v[64:67], v[200:203], v[250:253], v[64:67]
	s_setprio 0
	s_barrier
	s_add_i32 s8, s52, s46
	v_lshl_add_u64 v[186:187], s[34:35], 0, v[188:189]
	s_mov_b32 m0, s8
	ds_read_b128 v[204:207], v216 offset:16384
	ds_read_b128 v[208:211], v216 offset:17408
	ds_read_b128 v[218:221], v216 offset:18432
	ds_read_b128 v[222:225], v216 offset:19456
	ds_read_b128 v[226:229], v216 offset:20480
	ds_read_b128 v[242:245], v216 offset:21504
	ds_read_b128 v[246:249], v216 offset:22528
	ds_read_b128 v[250:253], v216 offset:23552
	global_load_lds_dwordx4 v[186:187], off
	s_add_i32 m0, s8, 0x2000
	s_add_u32 s8, s34, 0xb0000
	v_lshl_add_u64 v[212:213], s[34:35], 0, v[132:133]
	s_addc_u32 s9, s35, 0
	s_add_i32 s29, s29, s46
	global_load_lds_dwordx4 v[212:213], off
	v_lshl_add_u64 v[232:233], s[8:9], 0, v[188:189]
	s_mov_b32 m0, s29
	v_lshl_add_u64 v[234:235], s[36:37], 0, v[132:133]
	global_load_lds_dwordx4 v[232:233], off
	v_lshl_add_u64 v[232:233], s[8:9], 0, v[132:133]
	s_add_i32 m0, s29, 0x2000
	s_nop 0
	global_load_lds_dwordx4 v[232:233], off
	v_lshl_add_u64 v[232:233], s[36:37], 0, v[188:189]
	s_mov_b32 m0, s47
	s_nop 0
	global_load_lds_dwordx4 v[232:233], off
	s_mov_b32 m0, s48
	s_nop 0
	global_load_lds_dwordx4 v[234:235], off
	s_waitcnt vmcnt(8)
	s_waitcnt lgkmcnt(0)
	s_barrier
; #define PG8_STAGE(bufoff, gbase, voff) do { _Pragma("unroll") for (int _i = 0; _i < 2; ++_i) \
;         __builtin_amdgcn_global_load_lds((const unsigned*)((const char*)(gbase) + (voff)[_i]), (LAS unsigned*)(lds + (bufoff) + ldsw + _i * 8192), 16, 0, 0); } while (0)
; #define PG8_LDA(dst, b, h) do { _Pragma("unroll") for (int m = 0; m < 4; ++m) _Pragma("unroll") for (int k = 0; k < 2; ++k) dst[m][k] = *(const LAS bf16x8*)(lds + PG8_SA(b, h) + aoff + m * 2048 + k * 1024); } while (0)
; #define PG8_LDB(dst, b, h) do { _Pragma("unroll") for (int n = 0; n < 2; ++n) _Pragma("unroll") for (int k = 0; k < 2; ++k) dst[n][k] = *(const LAS bf16x8*)(lds + PG8_SB(b, h) + boff + n * 2048 + k * 1024); } while (0)
; #define PG8_MMA(ai, bj, At, Bt) do { __builtin_amdgcn_s_setprio(1); _Pragma("unroll") for (int m = 0; m < 4; ++m) _Pragma("unroll") for (int n = 0; n < 2; ++n) _Pragma("unroll") for (int k = 0; k < 2; ++k) \
;         acc[ai][bj][m][n] = __builtin_amdgcn_mfma_f32_16x16x32_bf16(Bt[n][k], At[m][k], acc[ai][bj][m][n], 0, 0, 0); __builtin_amdgcn_s_setprio(0); } while (0)
; #define PG8_WAIT_V(n) asm volatile("s_waitcnt vmcnt(" #n ")" ::: "memory")
; #define PG8_WAIT_L(n) asm volatile("s_waitcnt lgkmcnt(" #n ")" ::: "memory")
; #define PG8_BAR __builtin_amdgcn_s_barrier()
; #define PG8_SCHED __builtin_amdgcn_sched_barrier(0)
; template <class Epi, bool ALIGN_EPI = true>
; DI void gemm_phase(int tb_, LAS unsigned char* lds, const Gemm g, const Sched& S, const Epi& E) {
;     ...
;             PG8_WAIT_V(8); PG8_WAIT_L(0); PG8_BAR; PG8_MMA(1, 0, At, B0); PG8_MMA(1, 1, At, B1); PG8_BAR; PG8_SCHED;
;             PG8_LDB(B0, 1, 0); PG8_LDB(B1, 1, 1); PG8_SCHED; PG8_LDA(At, 1, 0); PG8_STAGE(PG8_SA(0, 1), a2 + hstep, voffA);
;             PG8_WAIT_V(8); PG8_WAIT_L(0); PG8_BAR; PG8_MMA(0, 0, At, B0); PG8_MMA(0, 1, At, B1); PG8_BAR; PG8_SCHED;
	s_setprio 1
	s_waitcnt lgkmcnt(0)
	v_mfma_f32_16x16x32_bf16 v[60:63], v[128:131], v[204:207], 0
	v_mfma_f32_16x16x32_bf16 v[56:59], v[174:177], v[204:207], 0
	v_mfma_f32_16x16x32_bf16 v[44:47], v[128:131], v[218:221], 0
	v_mfma_f32_16x16x32_bf16 v[40:43], v[174:177], v[218:221], 0
	v_mfma_f32_16x16x32_bf16 v[28:31], v[128:131], v[226:229], 0
	v_mfma_f32_16x16x32_bf16 v[24:27], v[174:177], v[226:229], 0
	v_mfma_f32_16x16x32_bf16 v[12:15], v[128:131], v[246:249], 0
	v_mfma_f32_16x16x32_bf16 v[8:11], v[174:177], v[246:249], 0
	v_mfma_f32_16x16x32_bf16 v[60:63], v[170:173], v[208:211], v[60:63]
	v_mfma_f32_16x16x32_bf16 v[56:59], v[178:181], v[208:211], v[56:59]
	v_mfma_f32_16x16x32_bf16 v[44:47], v[170:173], v[222:225], v[44:47]
	v_mfma_f32_16x16x32_bf16 v[40:43], v[178:181], v[222:225], v[40:43]
	v_mfma_f32_16x16x32_bf16 v[28:31], v[170:173], v[242:245], v[28:31]
	v_mfma_f32_16x16x32_bf16 v[24:27], v[178:181], v[242:245], v[24:27]
	v_mfma_f32_16x16x32_bf16 v[12:15], v[170:173], v[250:253], v[12:15]
	v_mfma_f32_16x16x32_bf16 v[8:11], v[178:181], v[250:253], v[8:11]
	s_setprio 0
	s_setprio 1
	v_mfma_f32_16x16x32_bf16 v[52:55], v[182:185], v[204:207], 0
	v_mfma_f32_16x16x32_bf16 v[48:51], v[196:199], v[204:207], 0
	v_mfma_f32_16x16x32_bf16 v[36:39], v[182:185], v[218:221], 0
	v_mfma_f32_16x16x32_bf16 v[32:35], v[196:199], v[218:221], 0
	v_mfma_f32_16x16x32_bf16 v[20:23], v[182:185], v[226:229], 0
	v_mfma_f32_16x16x32_bf16 v[16:19], v[196:199], v[226:229], 0
	v_mfma_f32_16x16x32_bf16 v[4:7], v[182:185], v[246:249], 0
	v_mfma_f32_16x16x32_bf16 v[0:3], v[196:199], v[246:249], 0
	v_mfma_f32_16x16x32_bf16 v[52:55], v[192:195], v[208:211], v[52:55]
	v_mfma_f32_16x16x32_bf16 v[48:51], v[200:203], v[208:211], v[48:51]
	v_mfma_f32_16x16x32_bf16 v[36:39], v[192:195], v[222:225], v[36:39]
	v_mfma_f32_16x16x32_bf16 v[32:35], v[200:203], v[222:225], v[32:35]
	v_mfma_f32_16x16x32_bf16 v[20:23], v[192:195], v[242:245], v[20:23]
	v_mfma_f32_16x16x32_bf16 v[16:19], v[200:203], v[242:245], v[16:19]
	v_mfma_f32_16x16x32_bf16 v[4:7], v[192:195], v[250:253], v[4:7]
	v_mfma_f32_16x16x32_bf16 v[0:3], v[200:203], v[250:253], v[0:3]
	s_setprio 0
	s_barrier
	s_add_i32 s29, 0, 0x18000
	s_add_i32 s52, 0, 0x1c000
	v_add_u32_e32 v178, s29, v214
	v_add_u32_e32 v200, s52, v214
	ds_read_b128 v[128:131], v178
	ds_read_b128 v[170:173], v178 offset:1024
	ds_read_b128 v[174:177], v178 offset:2048
	ds_read_b128 v[178:181], v178 offset:3072
	ds_read_b128 v[182:185], v200
	ds_read_b128 v[192:195], v200 offset:1024
	ds_read_b128 v[196:199], v200 offset:2048
	ds_read_b128 v[200:203], v200 offset:3072
	s_add_u32 s8, s36, 0xb0000
	s_addc_u32 s9, s37, 0
	s_mov_b32 m0, s49
	v_lshl_add_u64 v[236:237], s[8:9], 0, v[188:189]
	ds_read_b128 v[204:207], v216 offset:32768
	ds_read_b128 v[208:211], v216 offset:33792
	ds_read_b128 v[218:221], v216 offset:34816
	ds_read_b128 v[222:225], v216 offset:35840
	ds_read_b128 v[226:229], v216 offset:36864
	ds_read_b128 v[242:245], v216 offset:37888
	ds_read_b128 v[246:249], v216 offset:38912
	ds_read_b128 v[250:253], v216 offset:39936
	global_load_lds_dwordx4 v[236:237], off
	v_lshl_add_u64 v[236:237], s[8:9], 0, v[132:133]
	s_mov_b32 m0, s50
	s_nop 0
	global_load_lds_dwordx4 v[236:237], off
	s_waitcnt vmcnt(8)
	s_waitcnt lgkmcnt(0)
	s_barrier
	s_setprio 1
	s_waitcnt lgkmcnt(0)
	v_mfma_f32_16x16x32_bf16 v[124:127], v[128:131], v[204:207], v[124:127]
	v_mfma_f32_16x16x32_bf16 v[120:123], v[174:177], v[204:207], v[120:123]
	v_mfma_f32_16x16x32_bf16 v[108:111], v[128:131], v[218:221], v[108:111]
	v_mfma_f32_16x16x32_bf16 v[104:107], v[174:177], v[218:221], v[104:107]
	v_mfma_f32_16x16x32_bf16 v[92:95], v[128:131], v[226:229], v[92:95]
	v_mfma_f32_16x16x32_bf16 v[88:91], v[174:177], v[226:229], v[88:91]
	v_mfma_f32_16x16x32_bf16 v[76:79], v[128:131], v[246:249], v[76:79]
	v_mfma_f32_16x16x32_bf16 v[72:75], v[174:177], v[246:249], v[72:75]
	v_mfma_f32_16x16x32_bf16 v[124:127], v[170:173], v[208:211], v[124:127]
	v_mfma_f32_16x16x32_bf16 v[120:123], v[178:181], v[208:211], v[120:123]
	v_mfma_f32_16x16x32_bf16 v[108:111], v[170:173], v[222:225], v[108:111]
	v_mfma_f32_16x16x32_bf16 v[104:107], v[178:181], v[222:225], v[104:107]
	v_mfma_f32_16x16x32_bf16 v[92:95], v[170:173], v[242:245], v[92:95]
	v_mfma_f32_16x16x32_bf16 v[88:91], v[178:181], v[242:245], v[88:91]
	v_mfma_f32_16x16x32_bf16 v[76:79], v[170:173], v[250:253], v[76:79]
	v_mfma_f32_16x16x32_bf16 v[72:75], v[178:181], v[250:253], v[72:75]
	s_setprio 0
	s_setprio 1
	v_mfma_f32_16x16x32_bf16 v[116:119], v[182:185], v[204:207], v[116:119]
	v_mfma_f32_16x16x32_bf16 v[112:115], v[196:199], v[204:207], v[112:115]
	v_mfma_f32_16x16x32_bf16 v[100:103], v[182:185], v[218:221], v[100:103]
	v_mfma_f32_16x16x32_bf16 v[96:99], v[196:199], v[218:221], v[96:99]
	v_mfma_f32_16x16x32_bf16 v[84:87], v[182:185], v[226:229], v[84:87]
	v_mfma_f32_16x16x32_bf16 v[80:83], v[196:199], v[226:229], v[80:83]
	v_mfma_f32_16x16x32_bf16 v[68:71], v[182:185], v[246:249], v[68:71]
	v_mfma_f32_16x16x32_bf16 v[64:67], v[196:199], v[246:249], v[64:67]
	v_mfma_f32_16x16x32_bf16 v[116:119], v[192:195], v[208:211], v[116:119]
	v_mfma_f32_16x16x32_bf16 v[112:115], v[200:203], v[208:211], v[112:115]
	v_mfma_f32_16x16x32_bf16 v[100:103], v[192:195], v[222:225], v[100:103]
	v_mfma_f32_16x16x32_bf16 v[96:99], v[200:203], v[222:225], v[96:99]
	v_mfma_f32_16x16x32_bf16 v[84:87], v[192:195], v[242:245], v[84:87]
	v_mfma_f32_16x16x32_bf16 v[80:83], v[200:203], v[242:245], v[80:83]
	v_mfma_f32_16x16x32_bf16 v[68:71], v[192:195], v[250:253], v[68:71]
	v_mfma_f32_16x16x32_bf16 v[64:67], v[200:203], v[250:253], v[64:67]
	s_setprio 0
	s_barrier
; #define PG8_STAGE(bufoff, gbase, voff) do { _Pragma("unroll") for (int _i = 0; _i < 2; ++_i) \
;         __builtin_amdgcn_global_load_lds((const unsigned*)((const char*)(gbase) + (voff)[_i]), (LAS unsigned*)(lds + (bufoff) + ldsw + _i * 8192), 16, 0, 0); } while (0)
; #define PG8_LDA(dst, b, h) do { _Pragma("unroll") for (int m = 0; m < 4; ++m) _Pragma("unroll") for (int k = 0; k < 2; ++k) dst[m][k] = *(const LAS bf16x8*)(lds + PG8_SA(b, h) + aoff + m * 2048 + k * 1024); } while (0)
; #define PG8_MMA(ai, bj, At, Bt) do { __builtin_amdgcn_s_setprio(1); _Pragma("unroll") for (int m = 0; m < 4; ++m) _Pragma("unroll") for (int n = 0; n < 2; ++n) _Pragma("unroll") for (int k = 0; k < 2; ++k) \
;         acc[ai][bj][m][n] = __builtin_amdgcn_mfma_f32_16x16x32_bf16(Bt[n][k], At[m][k], acc[ai][bj][m][n], 0, 0, 0); __builtin_amdgcn_s_setprio(0); } while (0)
; #define PG8_WAIT_V(n) asm volatile("s_waitcnt vmcnt(" #n ")" ::: "memory")
; #define PG8_WAIT_L(n) asm volatile("s_waitcnt lgkmcnt(" #n ")" ::: "memory")
; #define PG8_BAR __builtin_amdgcn_s_barrier()
; #define PG8_SCHED __builtin_amdgcn_sched_barrier(0)
; template <class Epi, bool ALIGN_EPI = true>
; DI void gemm_phase(int tb_, LAS unsigned char* lds, const Gemm g, const Sched& S, const Epi& E) {
;     ...
;         for (int t = 0; t < nt; t += 2) {
;     ...
;             PG8_LDA(At, 1, 1); PG8_STAGE(PG8_SB(1, 0), b3, voffB); PG8_STAGE(PG8_SB(1, 1), b3 + hstep, voffB); PG8_STAGE(PG8_SA(1, 0), a3, voffA);
;             PG8_WAIT_V(8); PG8_WAIT_L(0); PG8_BAR; PG8_MMA(1, 0, At, B0); PG8_MMA(1, 1, At, B1); PG8_BAR; PG8_SCHED;
	s_add_i32 s8, s29, s46
	v_lshl_add_u64 v[186:187], v[186:187], 0, s[72:73]
	s_mov_b32 m0, s8
	ds_read_b128 v[204:207], v216 offset:49152
	ds_read_b128 v[208:211], v216 offset:50176
	ds_read_b128 v[218:221], v216 offset:51200
	ds_read_b128 v[222:225], v216 offset:52224
	ds_read_b128 v[226:229], v216 offset:53248
	ds_read_b128 v[242:245], v216 offset:54272
	ds_read_b128 v[246:249], v216 offset:55296
	ds_read_b128 v[250:253], v216 offset:56320
	global_load_lds_dwordx4 v[186:187], off
	s_add_i32 m0, s8, 0x2000
	s_add_u32 s8, s34, 0xb0080
	v_lshl_add_u64 v[186:187], v[212:213], 0, s[72:73]
	s_addc_u32 s9, s35, 0
	s_add_i32 s29, s52, s46
	global_load_lds_dwordx4 v[186:187], off
	v_lshl_add_u64 v[186:187], s[8:9], 0, v[188:189]
	s_mov_b32 m0, s29
	s_nop 0
	global_load_lds_dwordx4 v[186:187], off
	v_lshl_add_u64 v[186:187], s[8:9], 0, v[132:133]
	s_add_i32 m0, s29, 0x2000
	s_nop 0
	global_load_lds_dwordx4 v[186:187], off
	v_lshl_add_u64 v[186:187], v[232:233], 0, s[72:73]
	s_mov_b32 m0, s51
	s_nop 0
	global_load_lds_dwordx4 v[186:187], off
	v_lshl_add_u64 v[186:187], v[234:235], 0, s[72:73]
	s_mov_b32 m0, s54
	s_nop 0
	global_load_lds_dwordx4 v[186:187], off
	s_waitcnt vmcnt(8)
	s_waitcnt lgkmcnt(0)
	s_barrier
	s_setprio 1
	s_waitcnt lgkmcnt(0)
	v_mfma_f32_16x16x32_bf16 v[60:63], v[128:131], v[204:207], v[60:63]
	v_mfma_f32_16x16x32_bf16 v[56:59], v[174:177], v[204:207], v[56:59]
	v_mfma_f32_16x16x32_bf16 v[44:47], v[128:131], v[218:221], v[44:47]
	v_mfma_f32_16x16x32_bf16 v[40:43], v[174:177], v[218:221], v[40:43]
	v_mfma_f32_16x16x32_bf16 v[28:31], v[128:131], v[226:229], v[28:31]
	v_mfma_f32_16x16x32_bf16 v[24:27], v[174:177], v[226:229], v[24:27]
	v_mfma_f32_16x16x32_bf16 v[12:15], v[128:131], v[246:249], v[12:15]
	v_mfma_f32_16x16x32_bf16 v[8:11], v[174:177], v[246:249], v[8:11]
	v_mfma_f32_16x16x32_bf16 v[60:63], v[170:173], v[208:211], v[60:63]
	v_mfma_f32_16x16x32_bf16 v[56:59], v[178:181], v[208:211], v[56:59]
	v_mfma_f32_16x16x32_bf16 v[44:47], v[170:173], v[222:225], v[44:47]
	v_mfma_f32_16x16x32_bf16 v[40:43], v[178:181], v[222:225], v[40:43]
	v_mfma_f32_16x16x32_bf16 v[28:31], v[170:173], v[242:245], v[28:31]
	v_mfma_f32_16x16x32_bf16 v[24:27], v[178:181], v[242:245], v[24:27]
	v_mfma_f32_16x16x32_bf16 v[12:15], v[170:173], v[250:253], v[12:15]
	v_mfma_f32_16x16x32_bf16 v[8:11], v[178:181], v[250:253], v[8:11]
	s_setprio 0
	s_setprio 1
	v_mfma_f32_16x16x32_bf16 v[52:55], v[182:185], v[204:207], v[52:55]
	v_mfma_f32_16x16x32_bf16 v[48:51], v[196:199], v[204:207], v[48:51]
	v_mfma_f32_16x16x32_bf16 v[36:39], v[182:185], v[218:221], v[36:39]
	v_mfma_f32_16x16x32_bf16 v[32:35], v[196:199], v[218:221], v[32:35]
	v_mfma_f32_16x16x32_bf16 v[20:23], v[182:185], v[226:229], v[20:23]
	v_mfma_f32_16x16x32_bf16 v[16:19], v[196:199], v[226:229], v[16:19]
	v_mfma_f32_16x16x32_bf16 v[4:7], v[182:185], v[246:249], v[4:7]
	v_mfma_f32_16x16x32_bf16 v[0:3], v[196:199], v[246:249], v[0:3]
	v_mfma_f32_16x16x32_bf16 v[52:55], v[192:195], v[208:211], v[52:55]
	v_mfma_f32_16x16x32_bf16 v[48:51], v[200:203], v[208:211], v[48:51]
	v_mfma_f32_16x16x32_bf16 v[36:39], v[192:195], v[222:225], v[36:39]
	v_mfma_f32_16x16x32_bf16 v[32:35], v[200:203], v[222:225], v[32:35]
	v_mfma_f32_16x16x32_bf16 v[20:23], v[192:195], v[242:245], v[20:23]
	v_mfma_f32_16x16x32_bf16 v[16:19], v[200:203], v[242:245], v[16:19]
	v_mfma_f32_16x16x32_bf16 v[4:7], v[192:195], v[250:253], v[4:7]
	v_mfma_f32_16x16x32_bf16 v[0:3], v[200:203], v[250:253], v[0:3]
	s_setprio 0
	s_barrier
	s_add_u32 s11, s11, 0x100
	s_addc_u32 s15, s15, 0
	s_cmp_ge_i32 s33, s4
	s_mov_b64 s[8:9], s[30:31]
	s_mov_b32 s29, s33
	s_cbranch_scc1 .Lpeel_exit_10

; #define PG8_BAR __builtin_amdgcn_s_barrier()
; template <class Epi, bool ALIGN_EPI = true>
; DI void gemm_phase(int tb_, LAS unsigned char* lds, const Gemm g, const Sched& S, const Epi& E) {
;     ...
;         if constexpr (ALIGN_EPI) { if (wr == 0) PG8_BAR; }
.Lpeel_exit_10:
	s_and_b64 vcc, exec, s[20:21]
	s_cbranch_vccz .LBB0_2094
